# baseline (speedup 1.0000x reference)
.LBB0_102:
	v_mov_b32_e32 v64, v232
	v_lshrrev_b32_e32 v66, 2, v64
	s_waitcnt lgkmcnt(0)
	v_lshrrev_b32_e32 v65, 1, v64
	v_and_b32_e32 v66, 12, v66
	v_and_or_b32 v65, v65, s48, v66
	v_and_b32_e32 v66, 0x4f, v64
	v_mul_lo_u32 v65, v65, s50
	v_cvt_pk_bf16_f32 v44, 0, v44
	v_lshl_add_u32 v65, v66, 1, v65
	ds_write_b16_d16_hi v65, v44
	v_cvt_pk_bf16_f32 v44, v45, v46
	ds_write_b16 v65, v44 offset:272
	ds_write_b16_d16_hi v65, v44 offset:544
	v_cvt_pk_bf16_f32 v44, 0, v47
	ds_write_b16_d16_hi v65, v44 offset:816
	v_cvt_pk_bf16_f32 v40, 0, v40
	ds_write_b16_d16_hi v65, v40 offset:32
	v_cvt_pk_bf16_f32 v40, v41, v42
	ds_write_b16 v65, v40 offset:304
	ds_write_b16_d16_hi v65, v40 offset:576
	v_cvt_pk_bf16_f32 v40, 0, v43
	ds_write_b16_d16_hi v65, v40 offset:848
	v_cvt_pk_bf16_f32 v36, 0, v36
	ds_write_b16_d16_hi v65, v36 offset:64
	v_cvt_pk_bf16_f32 v36, v37, v38
	ds_write_b16 v65, v36 offset:336
	ds_write_b16_d16_hi v65, v36 offset:608
	v_cvt_pk_bf16_f32 v36, 0, v39
	ds_write_b16_d16_hi v65, v36 offset:880
	v_cvt_pk_bf16_f32 v32, 0, v32
	ds_write_b16_d16_hi v65, v32 offset:96
	v_cvt_pk_bf16_f32 v32, v33, v34
	ds_write_b16 v65, v32 offset:368
	ds_write_b16_d16_hi v65, v32 offset:640
	v_cvt_pk_bf16_f32 v32, 0, v35
	ds_write_b16_d16_hi v65, v32 offset:912
	v_cvt_pk_bf16_f32 v28, 0, v28
	ds_write_b16_d16_hi v65, v28 offset:4352
	v_cvt_pk_bf16_f32 v28, v29, v30
	ds_write_b16 v65, v28 offset:4624
	ds_write_b16_d16_hi v65, v28 offset:4896
	v_cvt_pk_bf16_f32 v28, 0, v31
	ds_write_b16_d16_hi v65, v28 offset:5168
	v_cvt_pk_bf16_f32 v24, 0, v24
	ds_write_b16_d16_hi v65, v24 offset:4384
	v_cvt_pk_bf16_f32 v24, v25, v26
	ds_write_b16 v65, v24 offset:4656
	ds_write_b16_d16_hi v65, v24 offset:4928
	v_cvt_pk_bf16_f32 v24, 0, v27
	ds_write_b16_d16_hi v65, v24 offset:5200
	v_cvt_pk_bf16_f32 v20, 0, v20
	ds_write_b16_d16_hi v65, v20 offset:4416
	v_cvt_pk_bf16_f32 v20, v21, v22
	ds_write_b16 v65, v20 offset:4688
	ds_write_b16_d16_hi v65, v20 offset:4960
	v_cvt_pk_bf16_f32 v20, 0, v23
	ds_write_b16_d16_hi v65, v20 offset:5232
	v_cvt_pk_bf16_f32 v16, 0, v16
	ds_write_b16_d16_hi v65, v16 offset:4448
	v_cvt_pk_bf16_f32 v16, v17, v18
	ds_write_b16 v65, v16 offset:4720
	ds_write_b16_d16_hi v65, v16 offset:4992
	v_cvt_pk_bf16_f32 v16, 0, v19
	ds_write_b16_d16_hi v65, v16 offset:5264
	v_cvt_pk_bf16_f32 v12, 0, v12
	ds_write_b16_d16_hi v65, v12 offset:8704
	v_cvt_pk_bf16_f32 v12, v13, v14
	ds_write_b16 v65, v12 offset:8976
	ds_write_b16_d16_hi v65, v12 offset:9248
	v_cvt_pk_bf16_f32 v12, 0, v15
	ds_write_b16_d16_hi v65, v12 offset:9520
	v_cvt_pk_bf16_f32 v8, 0, v8
	ds_write_b16_d16_hi v65, v8 offset:8736
	v_cvt_pk_bf16_f32 v8, v9, v10
	ds_write_b16 v65, v8 offset:9008
	ds_write_b16_d16_hi v65, v8 offset:9280
	v_cvt_pk_bf16_f32 v8, 0, v11
	ds_write_b16_d16_hi v65, v8 offset:9552
	v_cvt_pk_bf16_f32 v4, 0, v4
	ds_write_b16_d16_hi v65, v4 offset:8768
	v_cvt_pk_bf16_f32 v4, v5, v6
	ds_write_b16 v65, v4 offset:9040
	ds_write_b16_d16_hi v65, v4 offset:9312
	v_cvt_pk_bf16_f32 v4, 0, v7
	ds_write_b16_d16_hi v65, v4 offset:9584
	v_cvt_pk_bf16_f32 v0, 0, v0
	ds_write_b16_d16_hi v65, v0 offset:8800
	v_cvt_pk_bf16_f32 v0, v1, v2
	ds_write_b16 v65, v0 offset:9072
	ds_write_b16_d16_hi v65, v0 offset:9344
	v_cvt_pk_bf16_f32 v0, v3, v60
	ds_write_b16 v65, v0 offset:9616
	ds_write_b16_d16_hi v65, v0 offset:13056
	v_cvt_pk_bf16_f32 v0, v61, v62
	ds_write_b16 v65, v0 offset:13328
	ds_write_b16_d16_hi v65, v0 offset:13600
	v_cvt_pk_bf16_f32 v0, v63, v56
	ds_write_b16 v65, v0 offset:13872
	ds_write_b16_d16_hi v65, v0 offset:13088
	v_cvt_pk_bf16_f32 v0, v57, v58
	ds_write_b16 v65, v0 offset:13360
	ds_write_b16_d16_hi v65, v0 offset:13632
	v_cvt_pk_bf16_f32 v0, v59, v52
	ds_write_b16 v65, v0 offset:13904
	ds_write_b16_d16_hi v65, v0 offset:13120
	v_cvt_pk_bf16_f32 v0, v53, v54
	ds_write_b16 v65, v0 offset:13392
	ds_write_b16_d16_hi v65, v0 offset:13664
	v_cvt_pk_bf16_f32 v0, v55, v48
	ds_write_b16 v65, v0 offset:13936
	ds_write_b16_d16_hi v65, v0 offset:13152
	v_cvt_pk_bf16_f32 v0, v49, v50
	ds_write_b16 v65, v0 offset:13424
	ds_write_b16_d16_hi v65, v0 offset:13696
	s_lshl_b32 s12, s12, 7
	s_mul_hi_i32 s6, s10, 0x130000
	s_mul_i32 s10, s10, 0x130000
	v_cvt_pk_bf16_f32 v0, 0, v51
	s_add_u32 s14, s37, s10
	ds_write_b16_d16_hi v65, v0 offset:13968
	v_ashrrev_i32_e32 v0, 31, v64
	s_addc_u32 s6, s38, s6
	s_ashr_i32 s13, s12, 31
	v_lshrrev_b32_e32 v0, 28, v0
	s_lshl_b64 s[10:11], s[12:13], 1
	v_add_u32_e32 v0, v64, v0
	s_add_u32 s10, s14, s10
	v_ashrrev_i32_e32 v6, 4, v0
	v_and_b32_e32 v0, -16, v0
	s_addc_u32 s11, s6, s11
	v_sub_u32_e32 v0, v64, v0
	v_lshlrev_b32_e32 v4, 3, v0
	v_mov_b64_e32 v[8:9], s[10:11]
	v_mul_lo_u32 v1, v6, s50
	v_ashrrev_i32_e32 v5, 31, v4
	v_mad_i64_i32 v[6:7], s[10:11], v6, s24, v[8:9]
	v_lshl_add_u64 v[10:11], v[4:5], 1, v[6:7]
	v_add_u32_e32 v4, 0x100, v64
	v_ashrrev_i32_e32 v5, 31, v4
	v_lshrrev_b32_e32 v5, 28, v5
	v_lshl_add_u32 v0, v0, 4, v1
	v_add_u32_e32 v5, v4, v5
	s_waitcnt lgkmcnt(0)
	s_barrier
	ds_read_b128 v[0:3], v0
	v_ashrrev_i32_e32 v12, 4, v5
	v_and_b32_e32 v5, -16, v5
	v_sub_u32_e32 v13, v4, v5
	v_mul_lo_u32 v4, v12, s50
	v_lshl_add_u32 v4, v13, 4, v4
	ds_read_b128 v[4:7], v4
	s_waitcnt lgkmcnt(1)
	global_store_dwordx4 v[10:11], v[0:3], off
	s_add_i32 s51, s51, s61
	s_cmp_lt_i32 s51, s47
	v_lshlrev_b32_e32 v0, 3, v13
	v_ashrrev_i32_e32 v1, 31, v0
	v_mad_i64_i32 v[2:3], s[10:11], v12, s24, v[8:9]
	v_lshl_add_u64 v[0:1], v[0:1], 1, v[2:3]
	s_waitcnt lgkmcnt(0)
	global_store_dwordx4 v[0:1], v[4:7], off
	v_add_u32_e32 v0, 0x200, v64
	v_ashrrev_i32_e32 v1, 31, v0
	v_lshrrev_b32_e32 v1, 28, v1
	v_add_u32_e32 v1, v0, v1
	v_ashrrev_i32_e32 v6, 4, v1
	v_and_b32_e32 v1, -16, v1
	v_sub_u32_e32 v0, v0, v1
	v_lshlrev_b32_e32 v4, 3, v0
	v_mul_lo_u32 v1, v6, s50
	v_ashrrev_i32_e32 v5, 31, v4
	v_mad_i64_i32 v[6:7], s[10:11], v6, s24, v[8:9]
	v_lshl_add_u64 v[10:11], v[4:5], 1, v[6:7]
	v_add_u32_e32 v4, 0x300, v64
	v_ashrrev_i32_e32 v5, 31, v4
	v_lshrrev_b32_e32 v5, 28, v5
	v_lshl_add_u32 v0, v0, 4, v1
	v_add_u32_e32 v5, v4, v5
	ds_read_b128 v[0:3], v0
	v_ashrrev_i32_e32 v12, 4, v5
	v_and_b32_e32 v5, -16, v5
	v_sub_u32_e32 v13, v4, v5
	v_mul_lo_u32 v4, v12, s50
	v_lshl_add_u32 v4, v13, 4, v4
	ds_read_b128 v[4:7], v4
	s_waitcnt lgkmcnt(1)
	global_store_dwordx4 v[10:11], v[0:3], off
	s_nop 1
	v_lshlrev_b32_e32 v0, 3, v13
	v_ashrrev_i32_e32 v1, 31, v0
	v_mad_i64_i32 v[2:3], s[10:11], v12, s24, v[8:9]
	v_lshl_add_u64 v[0:1], v[0:1], 1, v[2:3]
	s_waitcnt lgkmcnt(0)
	global_store_dwordx4 v[0:1], v[4:7], off
	v_add_u32_e32 v0, 0x400, v64
	v_ashrrev_i32_e32 v1, 31, v0
	v_lshrrev_b32_e32 v1, 28, v1
	v_add_u32_e32 v1, v0, v1
	v_ashrrev_i32_e32 v6, 4, v1
	v_and_b32_e32 v1, -16, v1
	v_sub_u32_e32 v0, v0, v1
	v_lshlrev_b32_e32 v4, 3, v0
	v_mul_lo_u32 v1, v6, s50
	v_ashrrev_i32_e32 v5, 31, v4
	v_mad_i64_i32 v[6:7], s[10:11], v6, s24, v[8:9]
	v_lshl_add_u64 v[10:11], v[4:5], 1, v[6:7]
	v_add_u32_e32 v4, 0x500, v64
	v_ashrrev_i32_e32 v5, 31, v4
	v_lshrrev_b32_e32 v5, 28, v5
	v_lshl_add_u32 v0, v0, 4, v1
	v_add_u32_e32 v5, v4, v5
	ds_read_b128 v[0:3], v0
	v_ashrrev_i32_e32 v12, 4, v5
	v_and_b32_e32 v5, -16, v5
	v_sub_u32_e32 v13, v4, v5
	v_mul_lo_u32 v4, v12, s50
	v_lshl_add_u32 v4, v13, 4, v4
	ds_read_b128 v[4:7], v4
	s_waitcnt lgkmcnt(1)
	global_store_dwordx4 v[10:11], v[0:3], off
	s_nop 1
	v_lshlrev_b32_e32 v0, 3, v13
	v_ashrrev_i32_e32 v1, 31, v0
	v_mad_i64_i32 v[2:3], s[10:11], v12, s24, v[8:9]
	v_lshl_add_u64 v[0:1], v[0:1], 1, v[2:3]
	s_waitcnt lgkmcnt(0)
	global_store_dwordx4 v[0:1], v[4:7], off
	v_add_u32_e32 v0, 0x600, v64
	v_ashrrev_i32_e32 v1, 31, v0
	v_lshrrev_b32_e32 v1, 28, v1
	v_add_u32_e32 v1, v0, v1
	v_ashrrev_i32_e32 v6, 4, v1
	v_and_b32_e32 v1, -16, v1
	v_sub_u32_e32 v0, v0, v1
	v_lshlrev_b32_e32 v4, 3, v0
	v_mul_lo_u32 v1, v6, s50
	v_ashrrev_i32_e32 v5, 31, v4
	v_mad_i64_i32 v[6:7], s[10:11], v6, s24, v[8:9]
	v_lshl_add_u64 v[10:11], v[4:5], 1, v[6:7]
	v_add_u32_e32 v4, 0x700, v64
	v_ashrrev_i32_e32 v5, 31, v4
	v_lshrrev_b32_e32 v5, 28, v5
	v_lshl_add_u32 v0, v0, 4, v1
	v_add_u32_e32 v5, v4, v5
	ds_read_b128 v[0:3], v0
	v_ashrrev_i32_e32 v12, 4, v5
	v_and_b32_e32 v5, -16, v5
	v_sub_u32_e32 v13, v4, v5
	v_mul_lo_u32 v4, v12, s50
	v_lshl_add_u32 v4, v13, 4, v4
	ds_read_b128 v[4:7], v4
	s_waitcnt lgkmcnt(1)
	global_store_dwordx4 v[10:11], v[0:3], off
	s_nop 1
	v_lshlrev_b32_e32 v0, 3, v13
	v_ashrrev_i32_e32 v1, 31, v0
	v_mad_i64_i32 v[2:3], s[10:11], v12, s24, v[8:9]
	v_lshl_add_u64 v[0:1], v[0:1], 1, v[2:3]
	s_waitcnt lgkmcnt(0)
	global_store_dwordx4 v[0:1], v[4:7], off
	s_cbranch_scc0 .LBB0_110

.LBB0_257:
	v_mov_b32_e32 v1, v232
	s_waitcnt vmcnt(7)
	v_lshrrev_b32_e32 v3, 2, v1
	v_lshrrev_b32_e32 v2, 1, v1
	v_and_b32_e32 v3, 12, v3
	v_and_or_b32 v2, v2, s64, v3
	v_and_b32_e32 v3, 0x4f, v1
	v_mul_lo_u32 v2, v2, s65
	v_lshl_add_u32 v2, v3, 1, v2
	v_cvt_pk_bf16_f32 v3, v65, v66
	ds_write_b16 v2, v3 offset:272
	ds_write_b16_d16_hi v2, v3 offset:544
	v_cvt_pk_bf16_f32 v3, v67, v60
	ds_write_b16 v2, v3 offset:816
	ds_write_b16_d16_hi v2, v3 offset:32
	v_cvt_pk_bf16_f32 v3, v61, v62
	ds_write_b16 v2, v3 offset:304
	ds_write_b16_d16_hi v2, v3 offset:576
	v_cvt_pk_bf16_f32 v3, v63, v56
	ds_write_b16 v2, v3 offset:848
	ds_write_b16_d16_hi v2, v3 offset:64
	v_cvt_pk_bf16_f32 v3, v57, v58
	ds_write_b16 v2, v3 offset:336
	ds_write_b16_d16_hi v2, v3 offset:608
	v_cvt_pk_bf16_f32 v3, v59, v52
	ds_write_b16 v2, v3 offset:880
	ds_write_b16_d16_hi v2, v3 offset:96
	v_cvt_pk_bf16_f32 v3, v53, v54
	ds_write_b16 v2, v3 offset:368
	ds_write_b16_d16_hi v2, v3 offset:640
	v_cvt_pk_bf16_f32 v3, v55, v48
	ds_write_b16 v2, v3 offset:912
	ds_write_b16_d16_hi v2, v3 offset:4352
	v_cvt_pk_bf16_f32 v3, v49, v50
	ds_write_b16 v2, v3 offset:4624
	ds_write_b16_d16_hi v2, v3 offset:4896
	v_cvt_pk_bf16_f32 v3, v51, v44
	ds_write_b16 v2, v3 offset:5168
	ds_write_b16_d16_hi v2, v3 offset:4384
	v_cvt_pk_bf16_f32 v3, v45, v46
	ds_write_b16 v2, v3 offset:4656
	ds_write_b16_d16_hi v2, v3 offset:4928
	v_cvt_pk_bf16_f32 v3, v47, v40
	ds_write_b16 v2, v3 offset:5200
	ds_write_b16_d16_hi v2, v3 offset:4416
	v_cvt_pk_bf16_f32 v3, v41, v42
	ds_write_b16 v2, v3 offset:4688
	ds_write_b16_d16_hi v2, v3 offset:4960
	v_cvt_pk_bf16_f32 v3, v43, v36
	ds_write_b16 v2, v3 offset:5232
	ds_write_b16_d16_hi v2, v3 offset:4448
	v_cvt_pk_bf16_f32 v3, v37, v38
	ds_write_b16 v2, v3 offset:4720
	ds_write_b16_d16_hi v2, v3 offset:4992
	v_cvt_pk_bf16_f32 v3, v39, v32
	ds_write_b16 v2, v3 offset:5264
	ds_write_b16_d16_hi v2, v3 offset:8704
	v_cvt_pk_bf16_f32 v3, v33, v34
	ds_write_b16 v2, v3 offset:8976
	ds_write_b16_d16_hi v2, v3 offset:9248
	v_cvt_pk_bf16_f32 v3, v35, v28
	ds_write_b16 v2, v3 offset:9520
	ds_write_b16_d16_hi v2, v3 offset:8736
	v_cvt_pk_bf16_f32 v3, v29, v30
	ds_write_b16 v2, v3 offset:9008
	ds_write_b16_d16_hi v2, v3 offset:9280
	v_cvt_pk_bf16_f32 v3, v31, v24
	ds_write_b16 v2, v3 offset:9552
	ds_write_b16_d16_hi v2, v3 offset:8768
	v_cvt_pk_bf16_f32 v3, v25, v26
	ds_write_b16 v2, v3 offset:9040
	ds_write_b16_d16_hi v2, v3 offset:9312
	v_cvt_pk_bf16_f32 v3, v27, v20
	ds_write_b16 v2, v3 offset:9584
	ds_write_b16_d16_hi v2, v3 offset:8800
	v_cvt_pk_bf16_f32 v3, v21, v22
	ds_write_b16 v2, v3 offset:9072
	ds_write_b16_d16_hi v2, v3 offset:9344
	v_cvt_pk_bf16_f32 v3, v23, v16
	ds_write_b16 v2, v3 offset:9616
	ds_write_b16_d16_hi v2, v3 offset:13056
	v_cvt_pk_bf16_f32 v3, v17, v18
	ds_write_b16 v2, v3 offset:13328
	ds_write_b16_d16_hi v2, v3 offset:13600
	v_cvt_pk_bf16_f32 v3, v19, v12
	ds_write_b16 v2, v3 offset:13872
	ds_write_b16_d16_hi v2, v3 offset:13088
	v_cvt_pk_bf16_f32 v3, v13, v14
	ds_write_b16 v2, v3 offset:13360
	ds_write_b16_d16_hi v2, v3 offset:13632
	v_cvt_pk_bf16_f32 v3, v15, v8
	ds_write_b16 v2, v3 offset:13904
	ds_write_b16_d16_hi v2, v3 offset:13120
	v_cvt_pk_bf16_f32 v3, v9, v10
	ds_write_b16 v2, v3 offset:13392
	ds_write_b16_d16_hi v2, v3 offset:13664
	v_cvt_pk_bf16_f32 v3, v11, v4
	ds_write_b16 v2, v3 offset:13936
	ds_write_b16_d16_hi v2, v3 offset:13152
	v_cvt_pk_bf16_f32 v3, v5, v6
	ds_write_b16 v2, v3 offset:13424
	ds_write_b16_d16_hi v2, v3 offset:13696
	v_cvt_pk_bf16_f32 v64, 0, v64
	v_cvt_pk_bf16_f32 v3, 0, v7
	ds_write_b16_d16_hi v2, v64
	ds_write_b16_d16_hi v2, v3 offset:13968
	v_ashrrev_i32_e32 v2, 31, v1
	s_lshl_b64 s[4:5], s[24:25], 1
	v_lshrrev_b32_e32 v2, 28, v2
	s_add_u32 s6, s51, s4
	v_add_u32_e32 v2, v1, v2
	s_addc_u32 s7, s52, s5
	s_lshl_b64 s[4:5], s[36:37], 1
	v_ashrrev_i32_e32 v6, 4, v2
	v_and_b32_e32 v2, -16, v2
	s_add_u32 s4, s6, s4
	v_sub_u32_e32 v2, v1, v2
	v_ashrrev_i32_e32 v7, 31, v6
	s_addc_u32 s5, s7, s5
	v_mul_lo_u32 v3, v6, s65
	v_lshlrev_b32_e32 v8, 3, v2
	v_lshlrev_b64 v[6:7], 11, v[6:7]
	v_ashrrev_i32_e32 v9, 31, v8
	v_lshl_add_u64 v[6:7], s[4:5], 0, v[6:7]
	v_lshl_add_u64 v[10:11], v[8:9], 1, v[6:7]
	v_add_u32_e32 v6, 0x100, v1
	v_ashrrev_i32_e32 v7, 31, v6
	v_lshl_add_u32 v2, v2, 4, v3
	v_lshrrev_b32_e32 v7, 28, v7
	s_waitcnt lgkmcnt(0)
	s_barrier
	ds_read_b128 v[2:5], v2
	v_add_u32_e32 v7, v6, v7
	v_ashrrev_i32_e32 v12, 4, v7
	v_and_b32_e32 v7, -16, v7
	v_sub_u32_e32 v13, v6, v7
	v_mul_lo_u32 v6, v12, s65
	v_lshl_add_u32 v6, v13, 4, v6
	ds_read_b128 v[6:9], v6
	s_waitcnt lgkmcnt(1)
	global_store_dwordx4 v[10:11], v[2:5], off
	s_add_i32 s66, s66, s61
	s_cmp_lt_i32 s66, s62
	v_lshlrev_b32_e32 v2, 3, v13
	v_ashrrev_i32_e32 v13, 31, v12
	v_lshlrev_b64 v[4:5], 11, v[12:13]
	v_ashrrev_i32_e32 v3, 31, v2
	v_lshl_add_u64 v[4:5], s[4:5], 0, v[4:5]
	v_lshl_add_u64 v[2:3], v[2:3], 1, v[4:5]
	s_waitcnt lgkmcnt(0)
	global_store_dwordx4 v[2:3], v[6:9], off
	v_add_u32_e32 v2, 0x200, v1
	v_ashrrev_i32_e32 v3, 31, v2
	v_lshrrev_b32_e32 v3, 28, v3
	v_add_u32_e32 v3, v2, v3
	v_ashrrev_i32_e32 v6, 4, v3
	v_and_b32_e32 v3, -16, v3
	v_sub_u32_e32 v2, v2, v3
	v_ashrrev_i32_e32 v7, 31, v6
	v_mul_lo_u32 v3, v6, s65
	v_lshlrev_b32_e32 v8, 3, v2
	v_lshlrev_b64 v[6:7], 11, v[6:7]
	v_ashrrev_i32_e32 v9, 31, v8
	v_lshl_add_u64 v[6:7], s[4:5], 0, v[6:7]
	v_lshl_add_u64 v[10:11], v[8:9], 1, v[6:7]
	v_add_u32_e32 v6, 0x300, v1
	v_ashrrev_i32_e32 v7, 31, v6
	v_lshl_add_u32 v2, v2, 4, v3
	v_lshrrev_b32_e32 v7, 28, v7
	ds_read_b128 v[2:5], v2
	v_add_u32_e32 v7, v6, v7
	v_ashrrev_i32_e32 v12, 4, v7
	v_and_b32_e32 v7, -16, v7
	v_sub_u32_e32 v13, v6, v7
	v_mul_lo_u32 v6, v12, s65
	v_lshl_add_u32 v6, v13, 4, v6
	ds_read_b128 v[6:9], v6
	s_waitcnt lgkmcnt(1)
	global_store_dwordx4 v[10:11], v[2:5], off
	s_nop 1
	v_lshlrev_b32_e32 v2, 3, v13
	v_ashrrev_i32_e32 v13, 31, v12
	v_lshlrev_b64 v[4:5], 11, v[12:13]
	v_ashrrev_i32_e32 v3, 31, v2
	v_lshl_add_u64 v[4:5], s[4:5], 0, v[4:5]
	v_lshl_add_u64 v[2:3], v[2:3], 1, v[4:5]
	s_waitcnt lgkmcnt(0)
	global_store_dwordx4 v[2:3], v[6:9], off
	v_add_u32_e32 v2, 0x400, v1
	v_ashrrev_i32_e32 v3, 31, v2
	v_lshrrev_b32_e32 v3, 28, v3
	v_add_u32_e32 v3, v2, v3
	v_ashrrev_i32_e32 v6, 4, v3
	v_and_b32_e32 v3, -16, v3
	v_sub_u32_e32 v2, v2, v3
	v_ashrrev_i32_e32 v7, 31, v6
	v_mul_lo_u32 v3, v6, s65
	v_lshlrev_b32_e32 v8, 3, v2
	v_lshlrev_b64 v[6:7], 11, v[6:7]
	v_ashrrev_i32_e32 v9, 31, v8
	v_lshl_add_u64 v[6:7], s[4:5], 0, v[6:7]
	v_lshl_add_u64 v[10:11], v[8:9], 1, v[6:7]
	v_add_u32_e32 v6, 0x500, v1
	v_ashrrev_i32_e32 v7, 31, v6
	v_lshl_add_u32 v2, v2, 4, v3
	v_lshrrev_b32_e32 v7, 28, v7
	ds_read_b128 v[2:5], v2
	v_add_u32_e32 v7, v6, v7
	v_ashrrev_i32_e32 v12, 4, v7
	v_and_b32_e32 v7, -16, v7
	v_sub_u32_e32 v13, v6, v7
	v_mul_lo_u32 v6, v12, s65
	v_lshl_add_u32 v6, v13, 4, v6
	ds_read_b128 v[6:9], v6
	s_waitcnt lgkmcnt(1)
	global_store_dwordx4 v[10:11], v[2:5], off
	s_nop 1
	v_lshlrev_b32_e32 v2, 3, v13
	v_ashrrev_i32_e32 v13, 31, v12
	v_lshlrev_b64 v[4:5], 11, v[12:13]
	v_ashrrev_i32_e32 v3, 31, v2
	v_lshl_add_u64 v[4:5], s[4:5], 0, v[4:5]
	v_lshl_add_u64 v[2:3], v[2:3], 1, v[4:5]
	s_waitcnt lgkmcnt(0)
	global_store_dwordx4 v[2:3], v[6:9], off
	v_add_u32_e32 v2, 0x600, v1
	v_ashrrev_i32_e32 v3, 31, v2
	v_lshrrev_b32_e32 v3, 28, v3
	v_add_u32_e32 v3, v2, v3
	v_ashrrev_i32_e32 v6, 4, v3
	v_and_b32_e32 v3, -16, v3
	v_sub_u32_e32 v2, v2, v3
	v_ashrrev_i32_e32 v7, 31, v6
	v_mul_lo_u32 v3, v6, s65
	v_lshlrev_b32_e32 v8, 3, v2
	v_lshlrev_b64 v[6:7], 11, v[6:7]
	v_ashrrev_i32_e32 v9, 31, v8
	v_lshl_add_u64 v[6:7], s[4:5], 0, v[6:7]
	v_add_u32_e32 v1, 0x700, v1
	v_lshl_add_u64 v[10:11], v[8:9], 1, v[6:7]
	v_ashrrev_i32_e32 v6, 31, v1
	v_lshrrev_b32_e32 v6, 28, v6
	v_lshl_add_u32 v2, v2, 4, v3
	v_add_u32_e32 v6, v1, v6
	ds_read_b128 v[2:5], v2
	v_ashrrev_i32_e32 v12, 4, v6
	v_and_b32_e32 v6, -16, v6
	v_sub_u32_e32 v1, v1, v6
	v_mul_lo_u32 v6, v12, s65
	v_lshl_add_u32 v6, v1, 4, v6
	ds_read_b128 v[6:9], v6
	v_ashrrev_i32_e32 v13, 31, v12
	s_waitcnt lgkmcnt(1)
	global_store_dwordx4 v[10:11], v[2:5], off
	s_nop 1
	v_lshlrev_b32_e32 v2, 3, v1
	v_lshlrev_b64 v[4:5], 11, v[12:13]
	v_ashrrev_i32_e32 v3, 31, v2
	v_lshl_add_u64 v[4:5], s[4:5], 0, v[4:5]
	v_lshl_add_u64 v[2:3], v[2:3], 1, v[4:5]
	s_waitcnt lgkmcnt(0)
	global_store_dwordx4 v[2:3], v[6:9], off
	s_cbranch_scc0 .LBB0_278

.LBB0_318:
	s_add_i32 s44, s7, 2
	s_add_i32 s7, s7, 4
	s_min_u32 s7, s7, 15
	s_lshl_b32 s7, s7, 7
	s_add_u32 s92, s10, s7
	s_addc_u32 s93, s11, 0
	s_add_u32 s94, s12, s7
	s_addc_u32 s95, s13, 0
	ds_read_b128 v[144:147], v124
	ds_read_b128 v[128:131], v125 offset:16512
	ds_read_b128 v[132:135], v125 offset:17536
	ds_read_b128 v[136:139], v125 offset:18560
	ds_read_b128 v[140:143], v125 offset:19584
	v_mfma_f32_16x16x32_bf16 v[64:67], v[48:51], v[64:67], v[92:95]
	v_mfma_f32_16x16x32_bf16 v[88:91], v[48:51], v[104:107], v[88:91]
	s_waitcnt vmcnt(7)
	ds_write_b128 v126, v[32:35] offset:33024
	global_load_dwordx4 v[32:35], v116, s[92:93]
	s_add_u32 s48, s10, s7
	s_addc_u32 s49, s11, 0
	v_mfma_f32_16x16x32_bf16 v[80:83], v[48:51], v[112:115], v[80:83]
	v_mfma_f32_16x16x32_bf16 v[48:51], v[48:51], v[108:111], v[56:59]
	s_waitcnt lgkmcnt(4)
	v_mfma_f32_16x16x32_bf16 v[56:59], v[144:147], v[128:131], v[100:103]
	ds_read_b128 v[92:95], v124 offset:1024
	s_waitcnt lgkmcnt(4)
	v_mfma_f32_16x16x32_bf16 v[96:99], v[144:147], v[132:135], v[96:99]
	s_waitcnt vmcnt(7)
	ds_write_b128 v126, v[20:23] offset:35072
	global_load_dwordx4 v[20:23], v118, s[92:93]
	ds_read_b128 v[100:103], v124 offset:2048
	s_waitcnt lgkmcnt(5)
	v_mfma_f32_16x16x32_bf16 v[84:87], v[144:147], v[136:139], v[84:87]
	ds_read_b128 v[104:107], v124 offset:3072
	s_waitcnt lgkmcnt(5)
	v_mfma_f32_16x16x32_bf16 v[76:79], v[144:147], v[140:143], v[76:79]
	ds_read_b128 v[108:111], v124 offset:8256
	s_waitcnt lgkmcnt(4)
	v_mfma_f32_16x16x32_bf16 v[72:75], v[92:95], v[128:131], v[72:75]
	ds_read_b128 v[112:115], v124 offset:9280
	v_mfma_f32_16x16x32_bf16 v[68:71], v[92:95], v[132:135], v[68:71]
	ds_read_b128 v[144:147], v124 offset:10304
	v_mfma_f32_16x16x32_bf16 v[60:63], v[92:95], v[136:139], v[60:63]
	s_waitcnt vmcnt(7)
	ds_write_b128 v126, v[16:19] offset:37120
	global_load_dwordx4 v[16:19], v120, s[92:93]
	ds_read_b128 v[148:151], v124 offset:11328
	v_mfma_f32_16x16x32_bf16 v[52:55], v[92:95], v[140:143], v[52:55]
	ds_read_b128 v[92:95], v125 offset:24768
	s_waitcnt lgkmcnt(7)
	v_mfma_f32_16x16x32_bf16 v[44:47], v[100:103], v[128:131], v[44:47]
	ds_read_b128 v[152:155], v125 offset:25792
	v_mfma_f32_16x16x32_bf16 v[40:43], v[100:103], v[132:135], v[40:43]
	ds_read_b128 v[156:159], v125 offset:26816
	v_mfma_f32_16x16x32_bf16 v[36:39], v[100:103], v[136:139], v[36:39]
	s_waitcnt vmcnt(7)
	ds_write_b128 v126, v[24:27] offset:39168
	global_load_dwordx4 v[24:27], v122, s[92:93]
	ds_read_b128 v[160:163], v125 offset:27840
	v_mfma_f32_16x16x32_bf16 v[28:31], v[100:103], v[140:143], v[28:31]
	s_waitcnt lgkmcnt(10)
	v_mfma_f32_16x16x32_bf16 v[64:67], v[104:107], v[128:131], v[64:67]
	v_mfma_f32_16x16x32_bf16 v[88:91], v[104:107], v[132:135], v[88:91]
	v_mfma_f32_16x16x32_bf16 v[80:83], v[104:107], v[136:139], v[80:83]
	v_mfma_f32_16x16x32_bf16 v[48:51], v[104:107], v[140:143], v[48:51]
	s_waitcnt vmcnt(7)
	ds_write_b128 v126, v[12:15] offset:49536
	global_load_dwordx4 v[12:15], v116, s[94:95]
	s_waitcnt lgkmcnt(5)
	v_mfma_f32_16x16x32_bf16 v[56:59], v[108:111], v[92:95], v[56:59]
	s_add_u32 s48, s12, s7
	s_addc_u32 s49, s13, 0
	s_waitcnt lgkmcnt(4)
	v_mfma_f32_16x16x32_bf16 v[96:99], v[108:111], v[152:155], v[96:99]
	s_min_u32 s7, s44, 12
	s_lshl_b32 s7, s7, 7
	s_waitcnt lgkmcnt(3)
	v_mfma_f32_16x16x32_bf16 v[84:87], v[108:111], v[156:159], v[84:87]
	s_waitcnt lgkmcnt(1)
	v_mfma_f32_16x16x32_bf16 v[76:79], v[108:111], v[160:163], v[76:79]
	s_waitcnt vmcnt(7)
	ds_write_b128 v126, v[8:11] offset:51584
	global_load_dwordx4 v[8:11], v118, s[94:95]
	v_mfma_f32_16x16x32_bf16 v[72:75], v[112:115], v[92:95], v[72:75]
	v_mfma_f32_16x16x32_bf16 v[68:71], v[112:115], v[152:155], v[68:71]
	v_mfma_f32_16x16x32_bf16 v[60:63], v[112:115], v[156:159], v[60:63]
	v_mfma_f32_16x16x32_bf16 v[52:55], v[112:115], v[160:163], v[52:55]
	v_mfma_f32_16x16x32_bf16 v[44:47], v[144:147], v[92:95], v[44:47]
	s_waitcnt vmcnt(7)
	ds_write_b128 v126, v[4:7] offset:53632
	global_load_dwordx4 v[4:7], v120, s[94:95]
	v_mfma_f32_16x16x32_bf16 v[40:43], v[144:147], v[152:155], v[40:43]
	s_add_u32 s48, s10, s7
	s_addc_u32 s49, s11, 0
	s_add_u32 s50, s12, s7
	v_mfma_f32_16x16x32_bf16 v[36:39], v[144:147], v[156:159], v[36:39]
	s_addc_u32 s51, s13, 0
	v_mfma_f32_16x16x32_bf16 v[28:31], v[144:147], v[160:163], v[28:31]
	v_mfma_f32_16x16x32_bf16 v[92:95], v[148:151], v[92:95], v[64:67]
	s_waitcnt vmcnt(7)
	ds_write_b128 v126, v[0:3] offset:55680
	global_load_dwordx4 v[0:3], v122, s[94:95]
	v_mfma_f32_16x16x32_bf16 v[88:91], v[148:151], v[152:155], v[88:91]
	v_mfma_f32_16x16x32_bf16 v[80:83], v[148:151], v[156:159], v[80:83]
	v_mfma_f32_16x16x32_bf16 v[100:103], v[148:151], v[160:163], v[48:51]
	s_waitcnt lgkmcnt(0)
	s_barrier
	s_nop 0
	ds_read_b128 v[48:51], v124 offset:33024
	ds_read_b128 v[108:111], v125 offset:49536
	ds_read_b128 v[128:131], v125 offset:50560
	ds_read_b128 v[132:135], v125 offset:51584
	ds_read_b128 v[136:139], v125 offset:52608
	s_waitcnt lgkmcnt(3)
	v_mfma_f32_16x16x32_bf16 v[140:143], v[48:51], v[108:111], v[56:59]
	s_waitcnt lgkmcnt(2)
	v_mfma_f32_16x16x32_bf16 v[96:99], v[48:51], v[128:131], v[96:99]
	s_waitcnt vmcnt(7)
	ds_write_b128 v126, v[32:35]
	global_load_dwordx4 v[32:35], v116, s[48:49] offset:384
	s_waitcnt lgkmcnt(2)
	v_mfma_f32_16x16x32_bf16 v[84:87], v[48:51], v[132:135], v[84:87]
	s_waitcnt lgkmcnt(0)
	v_mfma_f32_16x16x32_bf16 v[76:79], v[48:51], v[136:139], v[76:79]
	ds_read_b128 v[48:51], v124 offset:34048
	s_waitcnt lgkmcnt(0)
	v_mfma_f32_16x16x32_bf16 v[72:75], v[48:51], v[108:111], v[72:75]
	s_waitcnt vmcnt(7)
	ds_write_b128 v126, v[20:23] offset:2048
	global_load_dwordx4 v[20:23], v118, s[48:49] offset:384
	ds_read_b128 v[56:59], v124 offset:35072
	v_mfma_f32_16x16x32_bf16 v[68:71], v[48:51], v[128:131], v[68:71]
	ds_read_b128 v[144:147], v124 offset:36096
	v_mfma_f32_16x16x32_bf16 v[60:63], v[48:51], v[132:135], v[60:63]
	ds_read_b128 v[148:151], v124 offset:41280
	v_mfma_f32_16x16x32_bf16 v[52:55], v[48:51], v[136:139], v[52:55]
	ds_read_b128 v[152:155], v124 offset:42304
	s_waitcnt lgkmcnt(3)
	v_mfma_f32_16x16x32_bf16 v[44:47], v[56:59], v[108:111], v[44:47]
	s_waitcnt vmcnt(7)
	ds_write_b128 v126, v[16:19] offset:4096
	global_load_dwordx4 v[16:19], v120, s[48:49] offset:384
	ds_read_b128 v[156:159], v124 offset:43328
	v_mfma_f32_16x16x32_bf16 v[40:43], v[56:59], v[128:131], v[40:43]
	ds_read_b128 v[48:51], v124 offset:44352
	v_mfma_f32_16x16x32_bf16 v[36:39], v[56:59], v[132:135], v[36:39]
	ds_read_b128 v[64:67], v125 offset:57792
	v_mfma_f32_16x16x32_bf16 v[28:31], v[56:59], v[136:139], v[28:31]
	s_waitcnt vmcnt(7)
	ds_write_b128 v126, v[24:27] offset:6144
	global_load_dwordx4 v[24:27], v122, s[48:49] offset:384
	ds_read_b128 v[104:107], v125 offset:58816
	s_waitcnt lgkmcnt(8)
	v_mfma_f32_16x16x32_bf16 v[92:95], v[144:147], v[108:111], v[92:95]
	ds_read_b128 v[112:115], v125 offset:59840
	v_mfma_f32_16x16x32_bf16 v[88:91], v[144:147], v[128:131], v[88:91]
	ds_read_b128 v[108:111], v125 offset:60864
	v_mfma_f32_16x16x32_bf16 v[80:83], v[144:147], v[132:135], v[80:83]
	v_mfma_f32_16x16x32_bf16 v[56:59], v[144:147], v[136:139], v[100:103]
	s_waitcnt vmcnt(7)
	ds_write_b128 v126, v[12:15] offset:16512
	global_load_dwordx4 v[12:15], v116, s[50:51] offset:384
	s_waitcnt lgkmcnt(5)
	v_mfma_f32_16x16x32_bf16 v[100:103], v[148:151], v[64:67], v[140:143]
	s_waitcnt lgkmcnt(3)
	v_mfma_f32_16x16x32_bf16 v[96:99], v[148:151], v[104:107], v[96:99]
	s_waitcnt lgkmcnt(2)
	v_mfma_f32_16x16x32_bf16 v[84:87], v[148:151], v[112:115], v[84:87]
	s_waitcnt vmcnt(7)
	ds_write_b128 v126, v[8:11] offset:18560
	global_load_dwordx4 v[8:11], v118, s[50:51] offset:384
	s_waitcnt lgkmcnt(2)
	v_mfma_f32_16x16x32_bf16 v[76:79], v[148:151], v[108:111], v[76:79]
	v_mfma_f32_16x16x32_bf16 v[72:75], v[152:155], v[64:67], v[72:75]
	v_mfma_f32_16x16x32_bf16 v[68:71], v[152:155], v[104:107], v[68:71]
	v_mfma_f32_16x16x32_bf16 v[60:63], v[152:155], v[112:115], v[60:63]
	s_waitcnt vmcnt(7)
	ds_write_b128 v126, v[4:7] offset:20608
	global_load_dwordx4 v[4:7], v120, s[50:51] offset:384
	v_mfma_f32_16x16x32_bf16 v[52:55], v[152:155], v[108:111], v[52:55]
	v_mfma_f32_16x16x32_bf16 v[44:47], v[156:159], v[64:67], v[44:47]
	v_mfma_f32_16x16x32_bf16 v[40:43], v[156:159], v[104:107], v[40:43]
	s_waitcnt vmcnt(7)
	ds_write_b128 v126, v[0:3] offset:22656
	global_load_dwordx4 v[0:3], v122, s[50:51] offset:384
	v_mfma_f32_16x16x32_bf16 v[36:39], v[156:159], v[112:115], v[36:39]
	v_mfma_f32_16x16x32_bf16 v[28:31], v[156:159], v[108:111], v[28:31]
	s_cmp_lt_u32 s44, 12
	s_mov_b32 s7, s44
	s_waitcnt lgkmcnt(0)
	s_barrier
	s_cbranch_scc1 .LBB0_318
	ds_read_b128 v[144:147], v124
	ds_read_b128 v[128:131], v125 offset:16512
	ds_read_b128 v[132:135], v125 offset:17536
	ds_read_b128 v[136:139], v125 offset:18560
	ds_read_b128 v[140:143], v125 offset:19584
	v_mfma_f32_16x16x32_bf16 v[64:67], v[48:51], v[64:67], v[92:95]
	s_add_i32 s44, s7, 2
	s_add_i32 s7, s7, 4
	s_min_u32 s7, s7, 15
	v_mfma_f32_16x16x32_bf16 v[88:91], v[48:51], v[104:107], v[88:91]
	s_lshl_b32 s7, s7, 7
	s_add_u32 s48, s10, s7
	s_addc_u32 s49, s11, 0
	v_mfma_f32_16x16x32_bf16 v[80:83], v[48:51], v[112:115], v[80:83]
	v_mfma_f32_16x16x32_bf16 v[48:51], v[48:51], v[108:111], v[56:59]
	s_waitcnt lgkmcnt(3)
	v_mfma_f32_16x16x32_bf16 v[56:59], v[144:147], v[128:131], v[100:103]
	ds_read_b128 v[92:95], v124 offset:1024
	s_waitcnt lgkmcnt(3)
	v_mfma_f32_16x16x32_bf16 v[96:99], v[144:147], v[132:135], v[96:99]
	ds_read_b128 v[100:103], v124 offset:2048
	s_waitcnt lgkmcnt(3)
	v_mfma_f32_16x16x32_bf16 v[84:87], v[144:147], v[136:139], v[84:87]
	ds_read_b128 v[104:107], v124 offset:3072
	s_waitcnt lgkmcnt(3)
	v_mfma_f32_16x16x32_bf16 v[76:79], v[144:147], v[140:143], v[76:79]
	ds_read_b128 v[108:111], v124 offset:8256
	s_waitcnt lgkmcnt(3)
	v_mfma_f32_16x16x32_bf16 v[72:75], v[92:95], v[128:131], v[72:75]
	ds_read_b128 v[112:115], v124 offset:9280
	v_mfma_f32_16x16x32_bf16 v[68:71], v[92:95], v[132:135], v[68:71]
	ds_read_b128 v[144:147], v124 offset:10304
	v_mfma_f32_16x16x32_bf16 v[60:63], v[92:95], v[136:139], v[60:63]
	ds_read_b128 v[148:151], v124 offset:11328
	v_mfma_f32_16x16x32_bf16 v[52:55], v[92:95], v[140:143], v[52:55]
	ds_read_b128 v[92:95], v125 offset:24768
	s_waitcnt lgkmcnt(6)
	v_mfma_f32_16x16x32_bf16 v[44:47], v[100:103], v[128:131], v[44:47]
	ds_read_b128 v[152:155], v125 offset:25792
	v_mfma_f32_16x16x32_bf16 v[40:43], v[100:103], v[132:135], v[40:43]
	ds_read_b128 v[156:159], v125 offset:26816
	v_mfma_f32_16x16x32_bf16 v[36:39], v[100:103], v[136:139], v[36:39]
	ds_read_b128 v[160:163], v125 offset:27840
	v_mfma_f32_16x16x32_bf16 v[28:31], v[100:103], v[140:143], v[28:31]
	s_waitcnt lgkmcnt(8)
	v_mfma_f32_16x16x32_bf16 v[64:67], v[104:107], v[128:131], v[64:67]
	s_waitcnt vmcnt(7)
	ds_write_b128 v126, v[32:35] offset:33024
	v_mfma_f32_16x16x32_bf16 v[88:91], v[104:107], v[132:135], v[88:91]
	v_mfma_f32_16x16x32_bf16 v[80:83], v[104:107], v[136:139], v[80:83]
	s_waitcnt vmcnt(6)
	ds_write_b128 v126, v[20:23] offset:35072
	v_mfma_f32_16x16x32_bf16 v[48:51], v[104:107], v[140:143], v[48:51]
	s_waitcnt lgkmcnt(5)
	v_mfma_f32_16x16x32_bf16 v[56:59], v[108:111], v[92:95], v[56:59]
	s_waitcnt vmcnt(5)
	ds_write_b128 v126, v[16:19] offset:37120
	s_add_u32 s48, s12, s7
	s_addc_u32 s49, s13, 0
	s_waitcnt lgkmcnt(5)
	v_mfma_f32_16x16x32_bf16 v[96:99], v[108:111], v[152:155], v[96:99]
	s_min_u32 s7, s44, 12
	s_lshl_b32 s7, s7, 7
	s_waitcnt lgkmcnt(4)
	v_mfma_f32_16x16x32_bf16 v[84:87], v[108:111], v[156:159], v[84:87]
	s_waitcnt vmcnt(4)
	ds_write_b128 v126, v[24:27] offset:39168
	s_waitcnt lgkmcnt(4)
	v_mfma_f32_16x16x32_bf16 v[76:79], v[108:111], v[160:163], v[76:79]
	v_mfma_f32_16x16x32_bf16 v[72:75], v[112:115], v[92:95], v[72:75]
	s_waitcnt vmcnt(3)
	ds_write_b128 v126, v[12:15] offset:49536
	v_mfma_f32_16x16x32_bf16 v[68:71], v[112:115], v[152:155], v[68:71]
	v_mfma_f32_16x16x32_bf16 v[60:63], v[112:115], v[156:159], v[60:63]
	s_waitcnt vmcnt(2)
	ds_write_b128 v126, v[8:11] offset:51584
	v_mfma_f32_16x16x32_bf16 v[52:55], v[112:115], v[160:163], v[52:55]
	v_mfma_f32_16x16x32_bf16 v[44:47], v[144:147], v[92:95], v[44:47]
	s_waitcnt vmcnt(1)
	ds_write_b128 v126, v[4:7] offset:53632
	v_mfma_f32_16x16x32_bf16 v[40:43], v[144:147], v[152:155], v[40:43]
	s_add_u32 s48, s10, s7
	s_addc_u32 s49, s11, 0
	s_add_u32 s50, s12, s7
	v_mfma_f32_16x16x32_bf16 v[36:39], v[144:147], v[156:159], v[36:39]
	s_waitcnt vmcnt(0)
	ds_write_b128 v126, v[0:3] offset:55680
	s_addc_u32 s51, s13, 0
	v_mfma_f32_16x16x32_bf16 v[28:31], v[144:147], v[160:163], v[28:31]
	v_mfma_f32_16x16x32_bf16 v[92:95], v[148:151], v[92:95], v[64:67]
	v_mfma_f32_16x16x32_bf16 v[88:91], v[148:151], v[152:155], v[88:91]
	v_mfma_f32_16x16x32_bf16 v[80:83], v[148:151], v[156:159], v[80:83]
	v_mfma_f32_16x16x32_bf16 v[100:103], v[148:151], v[160:163], v[48:51]
	s_waitcnt lgkmcnt(0)
	s_barrier
	s_nop 0
	ds_read_b128 v[48:51], v124 offset:33024
	ds_read_b128 v[108:111], v125 offset:49536
	ds_read_b128 v[128:131], v125 offset:50560
	ds_read_b128 v[132:135], v125 offset:51584
	ds_read_b128 v[136:139], v125 offset:52608
	s_waitcnt lgkmcnt(3)
	v_mfma_f32_16x16x32_bf16 v[140:143], v[48:51], v[108:111], v[56:59]
	s_waitcnt lgkmcnt(2)
	v_mfma_f32_16x16x32_bf16 v[96:99], v[48:51], v[128:131], v[96:99]
	s_waitcnt lgkmcnt(1)
	v_mfma_f32_16x16x32_bf16 v[84:87], v[48:51], v[132:135], v[84:87]
	s_waitcnt lgkmcnt(0)
	v_mfma_f32_16x16x32_bf16 v[76:79], v[48:51], v[136:139], v[76:79]
	ds_read_b128 v[48:51], v124 offset:34048
	s_waitcnt lgkmcnt(0)
	v_mfma_f32_16x16x32_bf16 v[72:75], v[48:51], v[108:111], v[72:75]
	ds_read_b128 v[56:59], v124 offset:35072
	v_mfma_f32_16x16x32_bf16 v[68:71], v[48:51], v[128:131], v[68:71]
	ds_read_b128 v[144:147], v124 offset:36096
	v_mfma_f32_16x16x32_bf16 v[60:63], v[48:51], v[132:135], v[60:63]
	ds_read_b128 v[148:151], v124 offset:41280
	v_mfma_f32_16x16x32_bf16 v[52:55], v[48:51], v[136:139], v[52:55]
	ds_read_b128 v[152:155], v124 offset:42304
	s_waitcnt lgkmcnt(3)
	v_mfma_f32_16x16x32_bf16 v[44:47], v[56:59], v[108:111], v[44:47]
	ds_read_b128 v[156:159], v124 offset:43328
	v_mfma_f32_16x16x32_bf16 v[40:43], v[56:59], v[128:131], v[40:43]
	ds_read_b128 v[48:51], v124 offset:44352
	v_mfma_f32_16x16x32_bf16 v[36:39], v[56:59], v[132:135], v[36:39]
	ds_read_b128 v[64:67], v125 offset:57792
	v_mfma_f32_16x16x32_bf16 v[28:31], v[56:59], v[136:139], v[28:31]
	ds_read_b128 v[104:107], v125 offset:58816
	s_waitcnt lgkmcnt(6)
	v_mfma_f32_16x16x32_bf16 v[92:95], v[144:147], v[108:111], v[92:95]
	ds_read_b128 v[112:115], v125 offset:59840
	v_mfma_f32_16x16x32_bf16 v[88:91], v[144:147], v[128:131], v[88:91]
	ds_read_b128 v[108:111], v125 offset:60864
	v_mfma_f32_16x16x32_bf16 v[80:83], v[144:147], v[132:135], v[80:83]
	v_mfma_f32_16x16x32_bf16 v[56:59], v[144:147], v[136:139], v[100:103]
	ds_write_b128 v126, v[32:35]
	s_waitcnt lgkmcnt(4)
	v_mfma_f32_16x16x32_bf16 v[100:103], v[148:151], v[64:67], v[140:143]
	s_waitcnt lgkmcnt(3)
	v_mfma_f32_16x16x32_bf16 v[96:99], v[148:151], v[104:107], v[96:99]
	ds_write_b128 v126, v[20:23] offset:2048
	s_waitcnt lgkmcnt(3)
	v_mfma_f32_16x16x32_bf16 v[84:87], v[148:151], v[112:115], v[84:87]
	s_waitcnt lgkmcnt(2)
	v_mfma_f32_16x16x32_bf16 v[76:79], v[148:151], v[108:111], v[76:79]
	ds_write_b128 v126, v[16:19] offset:4096
	v_mfma_f32_16x16x32_bf16 v[72:75], v[152:155], v[64:67], v[72:75]
	v_mfma_f32_16x16x32_bf16 v[68:71], v[152:155], v[104:107], v[68:71]
	ds_write_b128 v126, v[24:27] offset:6144
	v_mfma_f32_16x16x32_bf16 v[60:63], v[152:155], v[112:115], v[60:63]
	v_mfma_f32_16x16x32_bf16 v[52:55], v[152:155], v[108:111], v[52:55]
	ds_write_b128 v126, v[12:15] offset:16512
	v_mfma_f32_16x16x32_bf16 v[44:47], v[156:159], v[64:67], v[44:47]
	v_mfma_f32_16x16x32_bf16 v[40:43], v[156:159], v[104:107], v[40:43]
	ds_write_b128 v126, v[8:11] offset:18560
	v_mfma_f32_16x16x32_bf16 v[36:39], v[156:159], v[112:115], v[36:39]
	v_mfma_f32_16x16x32_bf16 v[28:31], v[156:159], v[108:111], v[28:31]
	ds_write_b128 v126, v[4:7] offset:20608
	ds_write_b128 v126, v[0:3] offset:22656
	s_cmp_lt_u32 s44, 14
	s_mov_b32 s7, s44
	s_waitcnt lgkmcnt(0)
	s_barrier
	s_waitcnt vmcnt(5)
	v_mov_b32_e32 v16, v232
	s_waitcnt vmcnt(0)
	v_mfma_f32_16x16x32_bf16 v[0:3], v[48:51], v[64:67], v[92:95]
	v_lshrrev_b32_e32 v18, 2, v16
	v_lshrrev_b32_e32 v17, 1, v16
	v_and_b32_e32 v18, 12, v18
	v_and_or_b32 v17, v17, s40, v18
	v_and_b32_e32 v18, 0x4f, v16
	v_mul_lo_u32 v17, v17, s42
	v_lshl_add_u32 v17, v18, 1, v17
	v_cvt_pk_bf16_f32 v18, v101, v102
	ds_write_b16 v17, v18 offset:272
	ds_write_b16_d16_hi v17, v18 offset:544
	v_cvt_pk_bf16_f32 v18, v103, v96
	ds_write_b16 v17, v18 offset:816
	ds_write_b16_d16_hi v17, v18 offset:32
	v_cvt_pk_bf16_f32 v18, v97, v98
	ds_write_b16 v17, v18 offset:304
	ds_write_b16_d16_hi v17, v18 offset:576
	v_cvt_pk_bf16_f32 v18, v99, v84
	ds_write_b16 v17, v18 offset:848
	ds_write_b16_d16_hi v17, v18 offset:64
	v_cvt_pk_bf16_f32 v18, v85, v86
	ds_write_b16 v17, v18 offset:336
	ds_write_b16_d16_hi v17, v18 offset:608
	v_cvt_pk_bf16_f32 v18, v87, v76
	ds_write_b16 v17, v18 offset:880
	ds_write_b16_d16_hi v17, v18 offset:96
	v_cvt_pk_bf16_f32 v18, v77, v78
	ds_write_b16 v17, v18 offset:368
	ds_write_b16_d16_hi v17, v18 offset:640
	v_cvt_pk_bf16_f32 v18, v79, v72
	ds_write_b16 v17, v18 offset:912
	ds_write_b16_d16_hi v17, v18 offset:4352
	v_cvt_pk_bf16_f32 v18, v73, v74
	ds_write_b16 v17, v18 offset:4624
	ds_write_b16_d16_hi v17, v18 offset:4896
	v_cvt_pk_bf16_f32 v18, v75, v68
	ds_write_b16 v17, v18 offset:5168
	ds_write_b16_d16_hi v17, v18 offset:4384
	v_cvt_pk_bf16_f32 v18, v69, v70
	ds_write_b16 v17, v18 offset:4656
	ds_write_b16_d16_hi v17, v18 offset:4928
	v_cvt_pk_bf16_f32 v18, v71, v60
	ds_write_b16 v17, v18 offset:5200
	ds_write_b16_d16_hi v17, v18 offset:4416
	v_cvt_pk_bf16_f32 v18, v61, v62
	ds_write_b16 v17, v18 offset:4688
	ds_write_b16_d16_hi v17, v18 offset:4960
	v_cvt_pk_bf16_f32 v18, v63, v52
	ds_write_b16 v17, v18 offset:5232
	ds_write_b16_d16_hi v17, v18 offset:4448
	v_cvt_pk_bf16_f32 v18, v53, v54
	ds_write_b16 v17, v18 offset:4720
	ds_write_b16_d16_hi v17, v18 offset:4992
	v_cvt_pk_bf16_f32 v18, v55, v44
	ds_write_b16 v17, v18 offset:5264
	ds_write_b16_d16_hi v17, v18 offset:8704
	v_cvt_pk_bf16_f32 v18, v45, v46
	ds_write_b16 v17, v18 offset:8976
	ds_write_b16_d16_hi v17, v18 offset:9248
	v_cvt_pk_bf16_f32 v18, v47, v40
	ds_write_b16 v17, v18 offset:9520
	ds_write_b16_d16_hi v17, v18 offset:8736
	v_cvt_pk_bf16_f32 v18, v41, v42
	ds_write_b16 v17, v18 offset:9008
	ds_write_b16_d16_hi v17, v18 offset:9280
	v_cvt_pk_bf16_f32 v18, v43, v36
	ds_write_b16 v17, v18 offset:9552
	ds_write_b16_d16_hi v17, v18 offset:8768
	v_cvt_pk_bf16_f32 v18, v37, v38
	ds_write_b16 v17, v18 offset:9040
	ds_write_b16_d16_hi v17, v18 offset:9312
	v_cvt_pk_bf16_f32 v18, v39, v28
	ds_write_b16 v17, v18 offset:9584
	ds_write_b16_d16_hi v17, v18 offset:8800
	v_cvt_pk_bf16_f32 v18, v29, v30
	ds_write_b16 v17, v18 offset:9072
	ds_write_b16_d16_hi v17, v18 offset:9344
	v_cvt_pk_bf16_f32 v18, 0, v31
	ds_write_b16_d16_hi v17, v18 offset:9616
	v_cvt_pk_bf16_f32 v0, 0, v0
	ds_write_b16_d16_hi v17, v0 offset:13056
	v_cvt_pk_bf16_f32 v0, 0, v1
	v_mfma_f32_16x16x32_bf16 v[4:7], v[48:51], v[104:107], v[88:91]
	ds_write_b16_d16_hi v17, v0 offset:13328
	v_cvt_pk_bf16_f32 v0, v2, v3
	ds_write_b16 v17, v0 offset:13600
	ds_write_b16_d16_hi v17, v0 offset:13872
	s_nop 0
	s_nop 1
	s_nop 0
	v_cvt_pk_bf16_f32 v0, 0, v4
	ds_write_b16_d16_hi v17, v0 offset:13088
	v_cvt_pk_bf16_f32 v0, 0, v5
	v_mfma_f32_16x16x32_bf16 v[8:11], v[48:51], v[112:115], v[80:83]
	ds_write_b16_d16_hi v17, v0 offset:13360
	v_cvt_pk_bf16_f32 v0, v6, v7
	ds_write_b16 v17, v0 offset:13632
	ds_write_b16_d16_hi v17, v0 offset:13904
	s_nop 0
	s_nop 1
	s_nop 0
	v_cvt_pk_bf16_f32 v0, 0, v8
	ds_write_b16_d16_hi v17, v0 offset:13120
	v_cvt_pk_bf16_f32 v0, 0, v9
	v_mfma_f32_16x16x32_bf16 v[12:15], v[48:51], v[108:111], v[56:59]
	ds_write_b16_d16_hi v17, v0 offset:13392
	v_cvt_pk_bf16_f32 v0, v10, v11
	ds_write_b16 v17, v0 offset:13664
	ds_write_b16_d16_hi v17, v0 offset:13936
	s_nop 0
	s_nop 1
	s_nop 0
	v_cvt_pk_bf16_f32 v0, v12, v13
	ds_write_b16 v17, v0 offset:13152
	ds_write_b16_d16_hi v17, v0 offset:13424
	v_cvt_pk_bf16_f32 v0, 0, v14
	ds_write_b16_d16_hi v17, v0 offset:13696
	s_lshl_b64 s[8:9], s[8:9], 1
	v_cvt_pk_bf16_f32 v0, 0, v15
	s_add_u32 s8, s26, s8
	ds_write_b16_d16_hi v17, v0 offset:13968
	v_ashrrev_i32_e32 v0, 31, v16
	s_addc_u32 s9, s27, s9
	s_lshl_b32 s6, s6, 7
	v_lshrrev_b32_e32 v0, 28, v0
	s_ashr_i32 s7, s6, 31
	v_add_u32_e32 v0, v16, v0
	s_lshl_b64 s[6:7], s[6:7], 1
	v_ashrrev_i32_e32 v4, 4, v0
	v_and_b32_e32 v0, -16, v0
	s_add_u32 s6, s8, s6
	v_sub_u32_e32 v0, v16, v0
	v_ashrrev_i32_e32 v5, 31, v4
	s_addc_u32 s7, s9, s7
	v_mul_lo_u32 v1, v4, s42
	v_lshlrev_b32_e32 v6, 3, v0
	v_lshlrev_b64 v[4:5], 11, v[4:5]
	v_ashrrev_i32_e32 v7, 31, v6
	v_lshl_add_u64 v[4:5], s[6:7], 0, v[4:5]
	v_lshl_add_u64 v[8:9], v[6:7], 1, v[4:5]
	v_add_u32_e32 v4, 0x100, v16
	v_ashrrev_i32_e32 v5, 31, v4
	v_cvt_pk_bf16_f32 v19, 0, v100
	v_lshl_add_u32 v0, v0, 4, v1
	v_lshrrev_b32_e32 v5, 28, v5
	ds_write_b16_d16_hi v17, v19
	s_waitcnt lgkmcnt(0)
	s_barrier
	ds_read_b128 v[0:3], v0
	v_add_u32_e32 v5, v4, v5
	v_ashrrev_i32_e32 v10, 4, v5
	v_and_b32_e32 v5, -16, v5
	v_sub_u32_e32 v11, v4, v5
	v_mul_lo_u32 v4, v10, s42
	v_lshl_add_u32 v4, v11, 4, v4
	ds_read_b128 v[4:7], v4
	s_waitcnt lgkmcnt(1)
	global_store_dwordx4 v[8:9], v[0:3], off
	s_add_i32 s43, s43, s61
	s_cmp_lt_i32 s43, s62
	v_lshlrev_b32_e32 v0, 3, v11
	v_ashrrev_i32_e32 v11, 31, v10
	v_lshlrev_b64 v[2:3], 11, v[10:11]
	v_ashrrev_i32_e32 v1, 31, v0
	v_lshl_add_u64 v[2:3], s[6:7], 0, v[2:3]
	v_lshl_add_u64 v[0:1], v[0:1], 1, v[2:3]
	s_waitcnt lgkmcnt(0)
	global_store_dwordx4 v[0:1], v[4:7], off
	v_add_u32_e32 v0, 0x200, v16
	v_ashrrev_i32_e32 v1, 31, v0
	v_lshrrev_b32_e32 v1, 28, v1
	v_add_u32_e32 v1, v0, v1
	v_ashrrev_i32_e32 v4, 4, v1
	v_and_b32_e32 v1, -16, v1
	v_sub_u32_e32 v0, v0, v1
	v_ashrrev_i32_e32 v5, 31, v4
	v_mul_lo_u32 v1, v4, s42
	v_lshlrev_b32_e32 v6, 3, v0
	v_lshlrev_b64 v[4:5], 11, v[4:5]
	v_ashrrev_i32_e32 v7, 31, v6
	v_lshl_add_u64 v[4:5], s[6:7], 0, v[4:5]
	v_lshl_add_u64 v[8:9], v[6:7], 1, v[4:5]
	v_add_u32_e32 v4, 0x300, v16
	v_ashrrev_i32_e32 v5, 31, v4
	v_lshl_add_u32 v0, v0, 4, v1
	v_lshrrev_b32_e32 v5, 28, v5
	ds_read_b128 v[0:3], v0
	v_add_u32_e32 v5, v4, v5
	v_ashrrev_i32_e32 v10, 4, v5
	v_and_b32_e32 v5, -16, v5
	v_sub_u32_e32 v11, v4, v5
	v_mul_lo_u32 v4, v10, s42
	v_lshl_add_u32 v4, v11, 4, v4
	ds_read_b128 v[4:7], v4
	s_waitcnt lgkmcnt(1)
	global_store_dwordx4 v[8:9], v[0:3], off
	s_nop 1
	v_lshlrev_b32_e32 v0, 3, v11
	v_ashrrev_i32_e32 v11, 31, v10
	v_lshlrev_b64 v[2:3], 11, v[10:11]
	v_ashrrev_i32_e32 v1, 31, v0
	v_lshl_add_u64 v[2:3], s[6:7], 0, v[2:3]
	v_lshl_add_u64 v[0:1], v[0:1], 1, v[2:3]
	s_waitcnt lgkmcnt(0)
	global_store_dwordx4 v[0:1], v[4:7], off
	v_add_u32_e32 v0, 0x400, v16
	v_ashrrev_i32_e32 v1, 31, v0
	v_lshrrev_b32_e32 v1, 28, v1
	v_add_u32_e32 v1, v0, v1
	v_ashrrev_i32_e32 v4, 4, v1
	v_and_b32_e32 v1, -16, v1
	v_sub_u32_e32 v0, v0, v1
	v_ashrrev_i32_e32 v5, 31, v4
	v_mul_lo_u32 v1, v4, s42
	v_lshlrev_b32_e32 v6, 3, v0
	v_lshlrev_b64 v[4:5], 11, v[4:5]
	v_ashrrev_i32_e32 v7, 31, v6
	v_lshl_add_u64 v[4:5], s[6:7], 0, v[4:5]
	v_lshl_add_u64 v[8:9], v[6:7], 1, v[4:5]
	v_add_u32_e32 v4, 0x500, v16
	v_ashrrev_i32_e32 v5, 31, v4
	v_lshl_add_u32 v0, v0, 4, v1
	v_lshrrev_b32_e32 v5, 28, v5
	ds_read_b128 v[0:3], v0
	v_add_u32_e32 v5, v4, v5
	v_ashrrev_i32_e32 v10, 4, v5
	v_and_b32_e32 v5, -16, v5
	v_sub_u32_e32 v11, v4, v5
	v_mul_lo_u32 v4, v10, s42
	v_lshl_add_u32 v4, v11, 4, v4
	ds_read_b128 v[4:7], v4
	s_waitcnt lgkmcnt(1)
	global_store_dwordx4 v[8:9], v[0:3], off
	s_nop 1
	v_lshlrev_b32_e32 v0, 3, v11
	v_ashrrev_i32_e32 v11, 31, v10
	v_lshlrev_b64 v[2:3], 11, v[10:11]
	v_ashrrev_i32_e32 v1, 31, v0
	v_lshl_add_u64 v[2:3], s[6:7], 0, v[2:3]
	v_lshl_add_u64 v[0:1], v[0:1], 1, v[2:3]
	s_waitcnt lgkmcnt(0)
	global_store_dwordx4 v[0:1], v[4:7], off
	v_add_u32_e32 v0, 0x600, v16
	v_ashrrev_i32_e32 v1, 31, v0
	v_lshrrev_b32_e32 v1, 28, v1
	v_add_u32_e32 v1, v0, v1
	v_ashrrev_i32_e32 v4, 4, v1
	v_and_b32_e32 v1, -16, v1
	v_sub_u32_e32 v0, v0, v1
	v_ashrrev_i32_e32 v5, 31, v4
	v_mul_lo_u32 v1, v4, s42
	v_lshlrev_b32_e32 v6, 3, v0
	v_lshlrev_b64 v[4:5], 11, v[4:5]
	v_ashrrev_i32_e32 v7, 31, v6
	v_lshl_add_u64 v[4:5], s[6:7], 0, v[4:5]
	v_lshl_add_u64 v[8:9], v[6:7], 1, v[4:5]
	v_add_u32_e32 v4, 0x700, v16
	v_ashrrev_i32_e32 v5, 31, v4
	v_lshl_add_u32 v0, v0, 4, v1
	v_lshrrev_b32_e32 v5, 28, v5
	ds_read_b128 v[0:3], v0
	v_add_u32_e32 v5, v4, v5
	v_ashrrev_i32_e32 v10, 4, v5
	v_and_b32_e32 v5, -16, v5
	v_sub_u32_e32 v11, v4, v5
	v_mul_lo_u32 v4, v10, s42
	v_lshl_add_u32 v4, v11, 4, v4
	ds_read_b128 v[4:7], v4
	s_waitcnt lgkmcnt(1)
	global_store_dwordx4 v[8:9], v[0:3], off
	s_nop 1
	v_lshlrev_b32_e32 v0, 3, v11
	v_ashrrev_i32_e32 v11, 31, v10
	v_lshlrev_b64 v[2:3], 11, v[10:11]
	v_ashrrev_i32_e32 v1, 31, v0
	v_lshl_add_u64 v[2:3], s[6:7], 0, v[2:3]
	v_lshl_add_u64 v[0:1], v[0:1], 1, v[2:3]
	s_waitcnt lgkmcnt(0)
	global_store_dwordx4 v[0:1], v[4:7], off
	s_cbranch_scc1 .LBB0_317

.LBB0_423:
	v_mov_b32_e32 v64, v232
	v_lshrrev_b32_e32 v66, 2, v64
	s_waitcnt lgkmcnt(0)
	v_lshrrev_b32_e32 v65, 1, v64
	v_and_b32_e32 v66, 12, v66
	v_and_or_b32 v65, v65, s51, v66
	v_and_b32_e32 v66, 0x4f, v64
	v_mul_lo_u32 v65, v65, s53
	v_cvt_pk_bf16_f32 v44, 0, v44
	v_lshl_add_u32 v65, v66, 1, v65
	ds_write_b16_d16_hi v65, v44
	v_cvt_pk_bf16_f32 v44, v45, v46
	ds_write_b16 v65, v44 offset:272
	ds_write_b16_d16_hi v65, v44 offset:544
	v_cvt_pk_bf16_f32 v44, 0, v47
	ds_write_b16_d16_hi v65, v44 offset:816
	v_cvt_pk_bf16_f32 v40, 0, v40
	ds_write_b16_d16_hi v65, v40 offset:32
	v_cvt_pk_bf16_f32 v40, v41, v42
	ds_write_b16 v65, v40 offset:304
	ds_write_b16_d16_hi v65, v40 offset:576
	v_cvt_pk_bf16_f32 v40, 0, v43
	ds_write_b16_d16_hi v65, v40 offset:848
	v_cvt_pk_bf16_f32 v36, 0, v36
	ds_write_b16_d16_hi v65, v36 offset:64
	v_cvt_pk_bf16_f32 v36, v37, v38
	ds_write_b16 v65, v36 offset:336
	ds_write_b16_d16_hi v65, v36 offset:608
	v_cvt_pk_bf16_f32 v36, 0, v39
	ds_write_b16_d16_hi v65, v36 offset:880
	v_cvt_pk_bf16_f32 v32, 0, v32
	ds_write_b16_d16_hi v65, v32 offset:96
	v_cvt_pk_bf16_f32 v32, v33, v34
	ds_write_b16 v65, v32 offset:368
	ds_write_b16_d16_hi v65, v32 offset:640
	v_cvt_pk_bf16_f32 v32, 0, v35
	ds_write_b16_d16_hi v65, v32 offset:912
	v_cvt_pk_bf16_f32 v28, 0, v28
	ds_write_b16_d16_hi v65, v28 offset:4352
	v_cvt_pk_bf16_f32 v28, v29, v30
	ds_write_b16 v65, v28 offset:4624
	ds_write_b16_d16_hi v65, v28 offset:4896
	v_cvt_pk_bf16_f32 v28, 0, v31
	ds_write_b16_d16_hi v65, v28 offset:5168
	v_cvt_pk_bf16_f32 v24, 0, v24
	ds_write_b16_d16_hi v65, v24 offset:4384
	v_cvt_pk_bf16_f32 v24, v25, v26
	ds_write_b16 v65, v24 offset:4656
	ds_write_b16_d16_hi v65, v24 offset:4928
	v_cvt_pk_bf16_f32 v24, 0, v27
	ds_write_b16_d16_hi v65, v24 offset:5200
	v_cvt_pk_bf16_f32 v20, 0, v20
	ds_write_b16_d16_hi v65, v20 offset:4416
	v_cvt_pk_bf16_f32 v20, v21, v22
	ds_write_b16 v65, v20 offset:4688
	ds_write_b16_d16_hi v65, v20 offset:4960
	v_cvt_pk_bf16_f32 v20, 0, v23
	ds_write_b16_d16_hi v65, v20 offset:5232
	v_cvt_pk_bf16_f32 v16, 0, v16
	ds_write_b16_d16_hi v65, v16 offset:4448
	v_cvt_pk_bf16_f32 v16, v17, v18
	ds_write_b16 v65, v16 offset:4720
	ds_write_b16_d16_hi v65, v16 offset:4992
	v_cvt_pk_bf16_f32 v16, 0, v19
	ds_write_b16_d16_hi v65, v16 offset:5264
	v_cvt_pk_bf16_f32 v12, 0, v12
	ds_write_b16_d16_hi v65, v12 offset:8704
	v_cvt_pk_bf16_f32 v12, v13, v14
	ds_write_b16 v65, v12 offset:8976
	ds_write_b16_d16_hi v65, v12 offset:9248
	v_cvt_pk_bf16_f32 v12, 0, v15
	ds_write_b16_d16_hi v65, v12 offset:9520
	v_cvt_pk_bf16_f32 v8, 0, v8
	ds_write_b16_d16_hi v65, v8 offset:8736
	v_cvt_pk_bf16_f32 v8, v9, v10
	ds_write_b16 v65, v8 offset:9008
	ds_write_b16_d16_hi v65, v8 offset:9280
	v_cvt_pk_bf16_f32 v8, 0, v11
	ds_write_b16_d16_hi v65, v8 offset:9552
	v_cvt_pk_bf16_f32 v4, 0, v4
	ds_write_b16_d16_hi v65, v4 offset:8768
	v_cvt_pk_bf16_f32 v4, v5, v6
	ds_write_b16 v65, v4 offset:9040
	ds_write_b16_d16_hi v65, v4 offset:9312
	v_cvt_pk_bf16_f32 v4, 0, v7
	ds_write_b16_d16_hi v65, v4 offset:9584
	v_cvt_pk_bf16_f32 v0, 0, v0
	ds_write_b16_d16_hi v65, v0 offset:8800
	v_cvt_pk_bf16_f32 v0, v1, v2
	ds_write_b16 v65, v0 offset:9072
	ds_write_b16_d16_hi v65, v0 offset:9344
	v_cvt_pk_bf16_f32 v0, v3, v60
	ds_write_b16 v65, v0 offset:9616
	ds_write_b16_d16_hi v65, v0 offset:13056
	v_cvt_pk_bf16_f32 v0, v61, v62
	ds_write_b16 v65, v0 offset:13328
	ds_write_b16_d16_hi v65, v0 offset:13600
	v_cvt_pk_bf16_f32 v0, v63, v56
	ds_write_b16 v65, v0 offset:13872
	ds_write_b16_d16_hi v65, v0 offset:13088
	v_cvt_pk_bf16_f32 v0, v57, v58
	ds_write_b16 v65, v0 offset:13360
	ds_write_b16_d16_hi v65, v0 offset:13632
	v_cvt_pk_bf16_f32 v0, v59, v52
	ds_write_b16 v65, v0 offset:13904
	ds_write_b16_d16_hi v65, v0 offset:13120
	v_cvt_pk_bf16_f32 v0, v53, v54
	ds_write_b16 v65, v0 offset:13392
	ds_write_b16_d16_hi v65, v0 offset:13664
	v_cvt_pk_bf16_f32 v0, v55, v48
	ds_write_b16 v65, v0 offset:13936
	ds_write_b16_d16_hi v65, v0 offset:13152
	v_cvt_pk_bf16_f32 v0, v49, v50
	ds_write_b16 v65, v0 offset:13424
	ds_write_b16_d16_hi v65, v0 offset:13696
	s_lshl_b32 s22, s22, 7
	s_mul_hi_i32 s14, s16, 0x130000
	s_mul_i32 s16, s16, 0x130000
	v_cvt_pk_bf16_f32 v0, 0, v51
	s_add_u32 s24, s40, s16
	ds_write_b16_d16_hi v65, v0 offset:13968
	v_ashrrev_i32_e32 v0, 31, v64
	s_addc_u32 s14, s41, s14
	s_ashr_i32 s23, s22, 31
	v_lshrrev_b32_e32 v0, 28, v0
	s_lshl_b64 s[16:17], s[22:23], 1
	v_add_u32_e32 v0, v64, v0
	s_add_u32 s16, s24, s16
	v_ashrrev_i32_e32 v6, 4, v0
	v_and_b32_e32 v0, -16, v0
	s_addc_u32 s17, s14, s17
	v_sub_u32_e32 v0, v64, v0
	v_lshlrev_b32_e32 v4, 3, v0
	v_mov_b64_e32 v[8:9], s[16:17]
	v_mul_lo_u32 v1, v6, s53
	v_ashrrev_i32_e32 v5, 31, v4
	v_mad_i64_i32 v[6:7], s[16:17], v6, s54, v[8:9]
	v_lshl_add_u64 v[10:11], v[4:5], 1, v[6:7]
	v_add_u32_e32 v4, 0x100, v64
	v_ashrrev_i32_e32 v5, 31, v4
	v_lshrrev_b32_e32 v5, 28, v5
	v_lshl_add_u32 v0, v0, 4, v1
	v_add_u32_e32 v5, v4, v5
	s_waitcnt lgkmcnt(0)
	s_barrier
	ds_read_b128 v[0:3], v0
	v_ashrrev_i32_e32 v12, 4, v5
	v_and_b32_e32 v5, -16, v5
	v_sub_u32_e32 v13, v4, v5
	v_mul_lo_u32 v4, v12, s53
	v_lshl_add_u32 v4, v13, 4, v4
	ds_read_b128 v[4:7], v4
	s_waitcnt lgkmcnt(1)
	global_store_dwordx4 v[10:11], v[0:3], off
	s_add_i32 s55, s55, s61
	s_cmp_lt_i32 s55, s47
	v_lshlrev_b32_e32 v0, 3, v13
	v_ashrrev_i32_e32 v1, 31, v0
	v_mad_i64_i32 v[2:3], s[16:17], v12, s54, v[8:9]
	v_lshl_add_u64 v[0:1], v[0:1], 1, v[2:3]
	s_waitcnt lgkmcnt(0)
	global_store_dwordx4 v[0:1], v[4:7], off
	v_add_u32_e32 v0, 0x200, v64
	v_ashrrev_i32_e32 v1, 31, v0
	v_lshrrev_b32_e32 v1, 28, v1
	v_add_u32_e32 v1, v0, v1
	v_ashrrev_i32_e32 v6, 4, v1
	v_and_b32_e32 v1, -16, v1
	v_sub_u32_e32 v0, v0, v1
	v_lshlrev_b32_e32 v4, 3, v0
	v_mul_lo_u32 v1, v6, s53
	v_ashrrev_i32_e32 v5, 31, v4
	v_mad_i64_i32 v[6:7], s[16:17], v6, s54, v[8:9]
	v_lshl_add_u64 v[10:11], v[4:5], 1, v[6:7]
	v_add_u32_e32 v4, 0x300, v64
	v_ashrrev_i32_e32 v5, 31, v4
	v_lshrrev_b32_e32 v5, 28, v5
	v_lshl_add_u32 v0, v0, 4, v1
	v_add_u32_e32 v5, v4, v5
	ds_read_b128 v[0:3], v0
	v_ashrrev_i32_e32 v12, 4, v5
	v_and_b32_e32 v5, -16, v5
	v_sub_u32_e32 v13, v4, v5
	v_mul_lo_u32 v4, v12, s53
	v_lshl_add_u32 v4, v13, 4, v4
	ds_read_b128 v[4:7], v4
	s_waitcnt lgkmcnt(1)
	global_store_dwordx4 v[10:11], v[0:3], off
	s_nop 1
	v_lshlrev_b32_e32 v0, 3, v13
	v_ashrrev_i32_e32 v1, 31, v0
	v_mad_i64_i32 v[2:3], s[16:17], v12, s54, v[8:9]
	v_lshl_add_u64 v[0:1], v[0:1], 1, v[2:3]
	s_waitcnt lgkmcnt(0)
	global_store_dwordx4 v[0:1], v[4:7], off
	v_add_u32_e32 v0, 0x400, v64
	v_ashrrev_i32_e32 v1, 31, v0
	v_lshrrev_b32_e32 v1, 28, v1
	v_add_u32_e32 v1, v0, v1
	v_ashrrev_i32_e32 v6, 4, v1
	v_and_b32_e32 v1, -16, v1
	v_sub_u32_e32 v0, v0, v1
	v_lshlrev_b32_e32 v4, 3, v0
	v_mul_lo_u32 v1, v6, s53
	v_ashrrev_i32_e32 v5, 31, v4
	v_mad_i64_i32 v[6:7], s[16:17], v6, s54, v[8:9]
	v_lshl_add_u64 v[10:11], v[4:5], 1, v[6:7]
	v_add_u32_e32 v4, 0x500, v64
	v_ashrrev_i32_e32 v5, 31, v4
	v_lshrrev_b32_e32 v5, 28, v5
	v_lshl_add_u32 v0, v0, 4, v1
	v_add_u32_e32 v5, v4, v5
	ds_read_b128 v[0:3], v0
	v_ashrrev_i32_e32 v12, 4, v5
	v_and_b32_e32 v5, -16, v5
	v_sub_u32_e32 v13, v4, v5
	v_mul_lo_u32 v4, v12, s53
	v_lshl_add_u32 v4, v13, 4, v4
	ds_read_b128 v[4:7], v4
	s_waitcnt lgkmcnt(1)
	global_store_dwordx4 v[10:11], v[0:3], off
	s_nop 1
	v_lshlrev_b32_e32 v0, 3, v13
	v_ashrrev_i32_e32 v1, 31, v0
	v_mad_i64_i32 v[2:3], s[16:17], v12, s54, v[8:9]
	v_lshl_add_u64 v[0:1], v[0:1], 1, v[2:3]
	s_waitcnt lgkmcnt(0)
	global_store_dwordx4 v[0:1], v[4:7], off
	v_add_u32_e32 v0, 0x600, v64
	v_ashrrev_i32_e32 v1, 31, v0
	v_lshrrev_b32_e32 v1, 28, v1
	v_add_u32_e32 v1, v0, v1
	v_ashrrev_i32_e32 v6, 4, v1
	v_and_b32_e32 v1, -16, v1
	v_sub_u32_e32 v0, v0, v1
	v_lshlrev_b32_e32 v4, 3, v0
	v_mul_lo_u32 v1, v6, s53
	v_ashrrev_i32_e32 v5, 31, v4
	v_mad_i64_i32 v[6:7], s[16:17], v6, s54, v[8:9]
	v_lshl_add_u64 v[10:11], v[4:5], 1, v[6:7]
	v_add_u32_e32 v4, 0x700, v64
	v_ashrrev_i32_e32 v5, 31, v4
	v_lshrrev_b32_e32 v5, 28, v5
	v_lshl_add_u32 v0, v0, 4, v1
	v_add_u32_e32 v5, v4, v5
	ds_read_b128 v[0:3], v0
	v_ashrrev_i32_e32 v12, 4, v5
	v_and_b32_e32 v5, -16, v5
	v_sub_u32_e32 v13, v4, v5
	v_mul_lo_u32 v4, v12, s53
	v_lshl_add_u32 v4, v13, 4, v4
	ds_read_b128 v[4:7], v4
	s_waitcnt lgkmcnt(1)
	global_store_dwordx4 v[10:11], v[0:3], off
	s_nop 1
	v_lshlrev_b32_e32 v0, 3, v13
	v_ashrrev_i32_e32 v1, 31, v0
	v_mad_i64_i32 v[2:3], s[16:17], v12, s54, v[8:9]
	v_lshl_add_u64 v[0:1], v[0:1], 1, v[2:3]
	s_waitcnt lgkmcnt(0)
	global_store_dwordx4 v[0:1], v[4:7], off
	s_cbranch_scc0 .LBB0_431

.LBB0_578:
	v_mov_b32_e32 v1, v232
	s_waitcnt vmcnt(7)
	v_lshrrev_b32_e32 v3, 2, v1
	v_lshrrev_b32_e32 v2, 1, v1
	v_and_b32_e32 v3, 12, v3
	v_and_or_b32 v2, v2, s64, v3
	v_and_b32_e32 v3, 0x4f, v1
	v_mul_lo_u32 v2, v2, s65
	v_lshl_add_u32 v2, v3, 1, v2
	v_cvt_pk_bf16_f32 v3, v65, v66
	ds_write_b16 v2, v3 offset:272
	ds_write_b16_d16_hi v2, v3 offset:544
	v_cvt_pk_bf16_f32 v3, v67, v60
	ds_write_b16 v2, v3 offset:816
	ds_write_b16_d16_hi v2, v3 offset:32
	v_cvt_pk_bf16_f32 v3, v61, v62
	ds_write_b16 v2, v3 offset:304
	ds_write_b16_d16_hi v2, v3 offset:576
	v_cvt_pk_bf16_f32 v3, v63, v56
	ds_write_b16 v2, v3 offset:848
	ds_write_b16_d16_hi v2, v3 offset:64
	v_cvt_pk_bf16_f32 v3, v57, v58
	ds_write_b16 v2, v3 offset:336
	ds_write_b16_d16_hi v2, v3 offset:608
	v_cvt_pk_bf16_f32 v3, v59, v52
	ds_write_b16 v2, v3 offset:880
	ds_write_b16_d16_hi v2, v3 offset:96
	v_cvt_pk_bf16_f32 v3, v53, v54
	ds_write_b16 v2, v3 offset:368
	ds_write_b16_d16_hi v2, v3 offset:640
	v_cvt_pk_bf16_f32 v3, v55, v48
	ds_write_b16 v2, v3 offset:912
	ds_write_b16_d16_hi v2, v3 offset:4352
	v_cvt_pk_bf16_f32 v3, v49, v50
	ds_write_b16 v2, v3 offset:4624
	ds_write_b16_d16_hi v2, v3 offset:4896
	v_cvt_pk_bf16_f32 v3, v51, v44
	ds_write_b16 v2, v3 offset:5168
	ds_write_b16_d16_hi v2, v3 offset:4384
	v_cvt_pk_bf16_f32 v3, v45, v46
	ds_write_b16 v2, v3 offset:4656
	ds_write_b16_d16_hi v2, v3 offset:4928
	v_cvt_pk_bf16_f32 v3, v47, v40
	ds_write_b16 v2, v3 offset:5200
	ds_write_b16_d16_hi v2, v3 offset:4416
	v_cvt_pk_bf16_f32 v3, v41, v42
	ds_write_b16 v2, v3 offset:4688
	ds_write_b16_d16_hi v2, v3 offset:4960
	v_cvt_pk_bf16_f32 v3, v43, v36
	ds_write_b16 v2, v3 offset:5232
	ds_write_b16_d16_hi v2, v3 offset:4448
	v_cvt_pk_bf16_f32 v3, v37, v38
	ds_write_b16 v2, v3 offset:4720
	ds_write_b16_d16_hi v2, v3 offset:4992
	v_cvt_pk_bf16_f32 v3, v39, v32
	ds_write_b16 v2, v3 offset:5264
	ds_write_b16_d16_hi v2, v3 offset:8704
	v_cvt_pk_bf16_f32 v3, v33, v34
	ds_write_b16 v2, v3 offset:8976
	ds_write_b16_d16_hi v2, v3 offset:9248
	v_cvt_pk_bf16_f32 v3, v35, v28
	ds_write_b16 v2, v3 offset:9520
	ds_write_b16_d16_hi v2, v3 offset:8736
	v_cvt_pk_bf16_f32 v3, v29, v30
	ds_write_b16 v2, v3 offset:9008
	ds_write_b16_d16_hi v2, v3 offset:9280
	v_cvt_pk_bf16_f32 v3, v31, v24
	ds_write_b16 v2, v3 offset:9552
	ds_write_b16_d16_hi v2, v3 offset:8768
	v_cvt_pk_bf16_f32 v3, v25, v26
	ds_write_b16 v2, v3 offset:9040
	ds_write_b16_d16_hi v2, v3 offset:9312
	v_cvt_pk_bf16_f32 v3, v27, v20
	ds_write_b16 v2, v3 offset:9584
	ds_write_b16_d16_hi v2, v3 offset:8800
	v_cvt_pk_bf16_f32 v3, v21, v22
	ds_write_b16 v2, v3 offset:9072
	ds_write_b16_d16_hi v2, v3 offset:9344
	v_cvt_pk_bf16_f32 v3, v23, v16
	ds_write_b16 v2, v3 offset:9616
	ds_write_b16_d16_hi v2, v3 offset:13056
	v_cvt_pk_bf16_f32 v3, v17, v18
	ds_write_b16 v2, v3 offset:13328
	ds_write_b16_d16_hi v2, v3 offset:13600
	v_cvt_pk_bf16_f32 v3, v19, v12
	ds_write_b16 v2, v3 offset:13872
	ds_write_b16_d16_hi v2, v3 offset:13088
	v_cvt_pk_bf16_f32 v3, v13, v14
	ds_write_b16 v2, v3 offset:13360
	ds_write_b16_d16_hi v2, v3 offset:13632
	v_cvt_pk_bf16_f32 v3, v15, v8
	ds_write_b16 v2, v3 offset:13904
	ds_write_b16_d16_hi v2, v3 offset:13120
	v_cvt_pk_bf16_f32 v3, v9, v10
	ds_write_b16 v2, v3 offset:13392
	ds_write_b16_d16_hi v2, v3 offset:13664
	v_cvt_pk_bf16_f32 v3, v11, v4
	ds_write_b16 v2, v3 offset:13936
	ds_write_b16_d16_hi v2, v3 offset:13152
	v_cvt_pk_bf16_f32 v3, v5, v6
	ds_write_b16 v2, v3 offset:13424
	ds_write_b16_d16_hi v2, v3 offset:13696
	v_cvt_pk_bf16_f32 v64, 0, v64
	v_cvt_pk_bf16_f32 v3, 0, v7
	ds_write_b16_d16_hi v2, v64
	ds_write_b16_d16_hi v2, v3 offset:13968
	v_ashrrev_i32_e32 v2, 31, v1
	s_lshl_b64 s[12:13], s[24:25], 1
	v_lshrrev_b32_e32 v2, 28, v2
	s_add_u32 s14, s51, s12
	v_add_u32_e32 v2, v1, v2
	s_addc_u32 s15, s52, s13
	s_lshl_b64 s[12:13], s[36:37], 1
	v_ashrrev_i32_e32 v6, 4, v2
	v_and_b32_e32 v2, -16, v2
	s_add_u32 s12, s14, s12
	v_sub_u32_e32 v2, v1, v2
	v_ashrrev_i32_e32 v7, 31, v6
	s_addc_u32 s13, s15, s13
	v_mul_lo_u32 v3, v6, s65
	v_lshlrev_b32_e32 v8, 3, v2
	v_lshlrev_b64 v[6:7], 11, v[6:7]
	v_ashrrev_i32_e32 v9, 31, v8
	v_lshl_add_u64 v[6:7], s[12:13], 0, v[6:7]
	v_lshl_add_u64 v[10:11], v[8:9], 1, v[6:7]
	v_add_u32_e32 v6, 0x100, v1
	v_ashrrev_i32_e32 v7, 31, v6
	v_lshl_add_u32 v2, v2, 4, v3
	v_lshrrev_b32_e32 v7, 28, v7
	s_waitcnt lgkmcnt(0)
	s_barrier
	ds_read_b128 v[2:5], v2
	v_add_u32_e32 v7, v6, v7
	v_ashrrev_i32_e32 v12, 4, v7
	v_and_b32_e32 v7, -16, v7
	v_sub_u32_e32 v13, v6, v7
	v_mul_lo_u32 v6, v12, s65
	v_lshl_add_u32 v6, v13, 4, v6
	ds_read_b128 v[6:9], v6
	s_waitcnt lgkmcnt(1)
	global_store_dwordx4 v[10:11], v[2:5], off
	s_add_i32 s66, s66, s61
	s_cmp_lt_i32 s66, s62
	v_lshlrev_b32_e32 v2, 3, v13
	v_ashrrev_i32_e32 v13, 31, v12
	v_lshlrev_b64 v[4:5], 11, v[12:13]
	v_ashrrev_i32_e32 v3, 31, v2
	v_lshl_add_u64 v[4:5], s[12:13], 0, v[4:5]
	v_lshl_add_u64 v[2:3], v[2:3], 1, v[4:5]
	s_waitcnt lgkmcnt(0)
	global_store_dwordx4 v[2:3], v[6:9], off
	v_add_u32_e32 v2, 0x200, v1
	v_ashrrev_i32_e32 v3, 31, v2
	v_lshrrev_b32_e32 v3, 28, v3
	v_add_u32_e32 v3, v2, v3
	v_ashrrev_i32_e32 v6, 4, v3
	v_and_b32_e32 v3, -16, v3
	v_sub_u32_e32 v2, v2, v3
	v_ashrrev_i32_e32 v7, 31, v6
	v_mul_lo_u32 v3, v6, s65
	v_lshlrev_b32_e32 v8, 3, v2
	v_lshlrev_b64 v[6:7], 11, v[6:7]
	v_ashrrev_i32_e32 v9, 31, v8
	v_lshl_add_u64 v[6:7], s[12:13], 0, v[6:7]
	v_lshl_add_u64 v[10:11], v[8:9], 1, v[6:7]
	v_add_u32_e32 v6, 0x300, v1
	v_ashrrev_i32_e32 v7, 31, v6
	v_lshl_add_u32 v2, v2, 4, v3
	v_lshrrev_b32_e32 v7, 28, v7
	ds_read_b128 v[2:5], v2
	v_add_u32_e32 v7, v6, v7
	v_ashrrev_i32_e32 v12, 4, v7
	v_and_b32_e32 v7, -16, v7
	v_sub_u32_e32 v13, v6, v7
	v_mul_lo_u32 v6, v12, s65
	v_lshl_add_u32 v6, v13, 4, v6
	ds_read_b128 v[6:9], v6
	s_waitcnt lgkmcnt(1)
	global_store_dwordx4 v[10:11], v[2:5], off
	s_nop 1
	v_lshlrev_b32_e32 v2, 3, v13
	v_ashrrev_i32_e32 v13, 31, v12
	v_lshlrev_b64 v[4:5], 11, v[12:13]
	v_ashrrev_i32_e32 v3, 31, v2
	v_lshl_add_u64 v[4:5], s[12:13], 0, v[4:5]
	v_lshl_add_u64 v[2:3], v[2:3], 1, v[4:5]
	s_waitcnt lgkmcnt(0)
	global_store_dwordx4 v[2:3], v[6:9], off
	v_add_u32_e32 v2, 0x400, v1
	v_ashrrev_i32_e32 v3, 31, v2
	v_lshrrev_b32_e32 v3, 28, v3
	v_add_u32_e32 v3, v2, v3
	v_ashrrev_i32_e32 v6, 4, v3
	v_and_b32_e32 v3, -16, v3
	v_sub_u32_e32 v2, v2, v3
	v_ashrrev_i32_e32 v7, 31, v6
	v_mul_lo_u32 v3, v6, s65
	v_lshlrev_b32_e32 v8, 3, v2
	v_lshlrev_b64 v[6:7], 11, v[6:7]
	v_ashrrev_i32_e32 v9, 31, v8
	v_lshl_add_u64 v[6:7], s[12:13], 0, v[6:7]
	v_lshl_add_u64 v[10:11], v[8:9], 1, v[6:7]
	v_add_u32_e32 v6, 0x500, v1
	v_ashrrev_i32_e32 v7, 31, v6
	v_lshl_add_u32 v2, v2, 4, v3
	v_lshrrev_b32_e32 v7, 28, v7
	ds_read_b128 v[2:5], v2
	v_add_u32_e32 v7, v6, v7
	v_ashrrev_i32_e32 v12, 4, v7
	v_and_b32_e32 v7, -16, v7
	v_sub_u32_e32 v13, v6, v7
	v_mul_lo_u32 v6, v12, s65
	v_lshl_add_u32 v6, v13, 4, v6
	ds_read_b128 v[6:9], v6
	s_waitcnt lgkmcnt(1)
	global_store_dwordx4 v[10:11], v[2:5], off
	s_nop 1
	v_lshlrev_b32_e32 v2, 3, v13
	v_ashrrev_i32_e32 v13, 31, v12
	v_lshlrev_b64 v[4:5], 11, v[12:13]
	v_ashrrev_i32_e32 v3, 31, v2
	v_lshl_add_u64 v[4:5], s[12:13], 0, v[4:5]
	v_lshl_add_u64 v[2:3], v[2:3], 1, v[4:5]
	s_waitcnt lgkmcnt(0)
	global_store_dwordx4 v[2:3], v[6:9], off
	v_add_u32_e32 v2, 0x600, v1
	v_ashrrev_i32_e32 v3, 31, v2
	v_lshrrev_b32_e32 v3, 28, v3
	v_add_u32_e32 v3, v2, v3
	v_ashrrev_i32_e32 v6, 4, v3
	v_and_b32_e32 v3, -16, v3
	v_sub_u32_e32 v2, v2, v3
	v_ashrrev_i32_e32 v7, 31, v6
	v_mul_lo_u32 v3, v6, s65
	v_lshlrev_b32_e32 v8, 3, v2
	v_lshlrev_b64 v[6:7], 11, v[6:7]
	v_ashrrev_i32_e32 v9, 31, v8
	v_lshl_add_u64 v[6:7], s[12:13], 0, v[6:7]
	v_add_u32_e32 v1, 0x700, v1
	v_lshl_add_u64 v[10:11], v[8:9], 1, v[6:7]
	v_ashrrev_i32_e32 v6, 31, v1
	v_lshrrev_b32_e32 v6, 28, v6
	v_lshl_add_u32 v2, v2, 4, v3
	v_add_u32_e32 v6, v1, v6
	ds_read_b128 v[2:5], v2
	v_ashrrev_i32_e32 v12, 4, v6
	v_and_b32_e32 v6, -16, v6
	v_sub_u32_e32 v1, v1, v6
	v_mul_lo_u32 v6, v12, s65
	v_lshl_add_u32 v6, v1, 4, v6
	ds_read_b128 v[6:9], v6
	v_ashrrev_i32_e32 v13, 31, v12
	s_waitcnt lgkmcnt(1)
	global_store_dwordx4 v[10:11], v[2:5], off
	s_nop 1
	v_lshlrev_b32_e32 v2, 3, v1
	v_lshlrev_b64 v[4:5], 11, v[12:13]
	v_ashrrev_i32_e32 v3, 31, v2
	v_lshl_add_u64 v[4:5], s[12:13], 0, v[4:5]
	v_lshl_add_u64 v[2:3], v[2:3], 1, v[4:5]
	s_waitcnt lgkmcnt(0)
	global_store_dwordx4 v[2:3], v[6:9], off
	s_cbranch_scc0 .LBB0_599

.LBB0_639:
	s_add_i32 s44, s13, 2
	s_add_i32 s13, s13, 4
	s_min_u32 s13, s13, 15
	s_lshl_b32 s13, s13, 7
	s_add_u32 s92, s16, s13
	s_addc_u32 s93, s17, 0
	s_add_u32 s94, s20, s13
	s_addc_u32 s95, s21, 0
	ds_read_b128 v[144:147], v124
	ds_read_b128 v[128:131], v125 offset:16512
	ds_read_b128 v[132:135], v125 offset:17536
	ds_read_b128 v[136:139], v125 offset:18560
	ds_read_b128 v[140:143], v125 offset:19584
	v_mfma_f32_16x16x32_bf16 v[64:67], v[48:51], v[64:67], v[92:95]
	v_mfma_f32_16x16x32_bf16 v[88:91], v[48:51], v[104:107], v[88:91]
	s_waitcnt vmcnt(7)
	ds_write_b128 v126, v[32:35] offset:33024
	global_load_dwordx4 v[32:35], v116, s[92:93]
	s_add_u32 s48, s16, s13
	s_addc_u32 s49, s17, 0
	v_mfma_f32_16x16x32_bf16 v[80:83], v[48:51], v[112:115], v[80:83]
	v_mfma_f32_16x16x32_bf16 v[48:51], v[48:51], v[108:111], v[56:59]
	s_waitcnt lgkmcnt(4)
	v_mfma_f32_16x16x32_bf16 v[56:59], v[144:147], v[128:131], v[100:103]
	ds_read_b128 v[92:95], v124 offset:1024
	s_waitcnt lgkmcnt(4)
	v_mfma_f32_16x16x32_bf16 v[96:99], v[144:147], v[132:135], v[96:99]
	s_waitcnt vmcnt(7)
	ds_write_b128 v126, v[20:23] offset:35072
	global_load_dwordx4 v[20:23], v118, s[92:93]
	ds_read_b128 v[100:103], v124 offset:2048
	s_waitcnt lgkmcnt(5)
	v_mfma_f32_16x16x32_bf16 v[84:87], v[144:147], v[136:139], v[84:87]
	ds_read_b128 v[104:107], v124 offset:3072
	s_waitcnt lgkmcnt(5)
	v_mfma_f32_16x16x32_bf16 v[76:79], v[144:147], v[140:143], v[76:79]
	ds_read_b128 v[108:111], v124 offset:8256
	s_waitcnt lgkmcnt(4)
	v_mfma_f32_16x16x32_bf16 v[72:75], v[92:95], v[128:131], v[72:75]
	ds_read_b128 v[112:115], v124 offset:9280
	v_mfma_f32_16x16x32_bf16 v[68:71], v[92:95], v[132:135], v[68:71]
	ds_read_b128 v[144:147], v124 offset:10304
	v_mfma_f32_16x16x32_bf16 v[60:63], v[92:95], v[136:139], v[60:63]
	s_waitcnt vmcnt(7)
	ds_write_b128 v126, v[16:19] offset:37120
	global_load_dwordx4 v[16:19], v120, s[92:93]
	ds_read_b128 v[148:151], v124 offset:11328
	v_mfma_f32_16x16x32_bf16 v[52:55], v[92:95], v[140:143], v[52:55]
	ds_read_b128 v[92:95], v125 offset:24768
	s_waitcnt lgkmcnt(7)
	v_mfma_f32_16x16x32_bf16 v[44:47], v[100:103], v[128:131], v[44:47]
	ds_read_b128 v[152:155], v125 offset:25792
	v_mfma_f32_16x16x32_bf16 v[40:43], v[100:103], v[132:135], v[40:43]
	ds_read_b128 v[156:159], v125 offset:26816
	v_mfma_f32_16x16x32_bf16 v[36:39], v[100:103], v[136:139], v[36:39]
	s_waitcnt vmcnt(7)
	ds_write_b128 v126, v[24:27] offset:39168
	global_load_dwordx4 v[24:27], v122, s[92:93]
	ds_read_b128 v[160:163], v125 offset:27840
	v_mfma_f32_16x16x32_bf16 v[28:31], v[100:103], v[140:143], v[28:31]
	s_waitcnt lgkmcnt(10)
	v_mfma_f32_16x16x32_bf16 v[64:67], v[104:107], v[128:131], v[64:67]
	v_mfma_f32_16x16x32_bf16 v[88:91], v[104:107], v[132:135], v[88:91]
	v_mfma_f32_16x16x32_bf16 v[80:83], v[104:107], v[136:139], v[80:83]
	v_mfma_f32_16x16x32_bf16 v[48:51], v[104:107], v[140:143], v[48:51]
	s_waitcnt vmcnt(7)
	ds_write_b128 v126, v[12:15] offset:49536
	global_load_dwordx4 v[12:15], v116, s[94:95]
	s_waitcnt lgkmcnt(5)
	v_mfma_f32_16x16x32_bf16 v[56:59], v[108:111], v[92:95], v[56:59]
	s_add_u32 s48, s20, s13
	s_addc_u32 s49, s21, 0
	s_waitcnt lgkmcnt(4)
	v_mfma_f32_16x16x32_bf16 v[96:99], v[108:111], v[152:155], v[96:99]
	s_min_u32 s13, s44, 12
	s_lshl_b32 s13, s13, 7
	s_waitcnt lgkmcnt(3)
	v_mfma_f32_16x16x32_bf16 v[84:87], v[108:111], v[156:159], v[84:87]
	s_waitcnt lgkmcnt(1)
	v_mfma_f32_16x16x32_bf16 v[76:79], v[108:111], v[160:163], v[76:79]
	s_waitcnt vmcnt(7)
	ds_write_b128 v126, v[8:11] offset:51584
	global_load_dwordx4 v[8:11], v118, s[94:95]
	v_mfma_f32_16x16x32_bf16 v[72:75], v[112:115], v[92:95], v[72:75]
	v_mfma_f32_16x16x32_bf16 v[68:71], v[112:115], v[152:155], v[68:71]
	v_mfma_f32_16x16x32_bf16 v[60:63], v[112:115], v[156:159], v[60:63]
	v_mfma_f32_16x16x32_bf16 v[52:55], v[112:115], v[160:163], v[52:55]
	v_mfma_f32_16x16x32_bf16 v[44:47], v[144:147], v[92:95], v[44:47]
	s_waitcnt vmcnt(7)
	ds_write_b128 v126, v[4:7] offset:53632
	global_load_dwordx4 v[4:7], v120, s[94:95]
	v_mfma_f32_16x16x32_bf16 v[40:43], v[144:147], v[152:155], v[40:43]
	s_add_u32 s48, s16, s13
	s_addc_u32 s49, s17, 0
	s_add_u32 s50, s20, s13
	v_mfma_f32_16x16x32_bf16 v[36:39], v[144:147], v[156:159], v[36:39]
	s_addc_u32 s51, s21, 0
	v_mfma_f32_16x16x32_bf16 v[28:31], v[144:147], v[160:163], v[28:31]
	v_mfma_f32_16x16x32_bf16 v[92:95], v[148:151], v[92:95], v[64:67]
	s_waitcnt vmcnt(7)
	ds_write_b128 v126, v[0:3] offset:55680
	global_load_dwordx4 v[0:3], v122, s[94:95]
	v_mfma_f32_16x16x32_bf16 v[88:91], v[148:151], v[152:155], v[88:91]
	v_mfma_f32_16x16x32_bf16 v[80:83], v[148:151], v[156:159], v[80:83]
	v_mfma_f32_16x16x32_bf16 v[100:103], v[148:151], v[160:163], v[48:51]
	s_waitcnt lgkmcnt(0)
	s_barrier
	s_nop 0
	ds_read_b128 v[48:51], v124 offset:33024
	ds_read_b128 v[108:111], v125 offset:49536
	ds_read_b128 v[128:131], v125 offset:50560
	ds_read_b128 v[132:135], v125 offset:51584
	ds_read_b128 v[136:139], v125 offset:52608
	s_waitcnt lgkmcnt(3)
	v_mfma_f32_16x16x32_bf16 v[140:143], v[48:51], v[108:111], v[56:59]
	s_waitcnt lgkmcnt(2)
	v_mfma_f32_16x16x32_bf16 v[96:99], v[48:51], v[128:131], v[96:99]
	s_waitcnt vmcnt(7)
	ds_write_b128 v126, v[32:35]
	global_load_dwordx4 v[32:35], v116, s[48:49] offset:384
	s_waitcnt lgkmcnt(2)
	v_mfma_f32_16x16x32_bf16 v[84:87], v[48:51], v[132:135], v[84:87]
	s_waitcnt lgkmcnt(0)
	v_mfma_f32_16x16x32_bf16 v[76:79], v[48:51], v[136:139], v[76:79]
	ds_read_b128 v[48:51], v124 offset:34048
	s_waitcnt lgkmcnt(0)
	v_mfma_f32_16x16x32_bf16 v[72:75], v[48:51], v[108:111], v[72:75]
	s_waitcnt vmcnt(7)
	ds_write_b128 v126, v[20:23] offset:2048
	global_load_dwordx4 v[20:23], v118, s[48:49] offset:384
	ds_read_b128 v[56:59], v124 offset:35072
	v_mfma_f32_16x16x32_bf16 v[68:71], v[48:51], v[128:131], v[68:71]
	ds_read_b128 v[144:147], v124 offset:36096
	v_mfma_f32_16x16x32_bf16 v[60:63], v[48:51], v[132:135], v[60:63]
	ds_read_b128 v[148:151], v124 offset:41280
	v_mfma_f32_16x16x32_bf16 v[52:55], v[48:51], v[136:139], v[52:55]
	ds_read_b128 v[152:155], v124 offset:42304
	s_waitcnt lgkmcnt(3)
	v_mfma_f32_16x16x32_bf16 v[44:47], v[56:59], v[108:111], v[44:47]
	s_waitcnt vmcnt(7)
	ds_write_b128 v126, v[16:19] offset:4096
	global_load_dwordx4 v[16:19], v120, s[48:49] offset:384
	ds_read_b128 v[156:159], v124 offset:43328
	v_mfma_f32_16x16x32_bf16 v[40:43], v[56:59], v[128:131], v[40:43]
	ds_read_b128 v[48:51], v124 offset:44352
	v_mfma_f32_16x16x32_bf16 v[36:39], v[56:59], v[132:135], v[36:39]
	ds_read_b128 v[64:67], v125 offset:57792
	v_mfma_f32_16x16x32_bf16 v[28:31], v[56:59], v[136:139], v[28:31]
	s_waitcnt vmcnt(7)
	ds_write_b128 v126, v[24:27] offset:6144
	global_load_dwordx4 v[24:27], v122, s[48:49] offset:384
	ds_read_b128 v[104:107], v125 offset:58816
	s_waitcnt lgkmcnt(8)
	v_mfma_f32_16x16x32_bf16 v[92:95], v[144:147], v[108:111], v[92:95]
	ds_read_b128 v[112:115], v125 offset:59840
	v_mfma_f32_16x16x32_bf16 v[88:91], v[144:147], v[128:131], v[88:91]
	ds_read_b128 v[108:111], v125 offset:60864
	v_mfma_f32_16x16x32_bf16 v[80:83], v[144:147], v[132:135], v[80:83]
	v_mfma_f32_16x16x32_bf16 v[56:59], v[144:147], v[136:139], v[100:103]
	s_waitcnt vmcnt(7)
	ds_write_b128 v126, v[12:15] offset:16512
	global_load_dwordx4 v[12:15], v116, s[50:51] offset:384
	s_waitcnt lgkmcnt(5)
	v_mfma_f32_16x16x32_bf16 v[100:103], v[148:151], v[64:67], v[140:143]
	s_waitcnt lgkmcnt(3)
	v_mfma_f32_16x16x32_bf16 v[96:99], v[148:151], v[104:107], v[96:99]
	s_waitcnt lgkmcnt(2)
	v_mfma_f32_16x16x32_bf16 v[84:87], v[148:151], v[112:115], v[84:87]
	s_waitcnt vmcnt(7)
	ds_write_b128 v126, v[8:11] offset:18560
	global_load_dwordx4 v[8:11], v118, s[50:51] offset:384
	s_waitcnt lgkmcnt(2)
	v_mfma_f32_16x16x32_bf16 v[76:79], v[148:151], v[108:111], v[76:79]
	v_mfma_f32_16x16x32_bf16 v[72:75], v[152:155], v[64:67], v[72:75]
	v_mfma_f32_16x16x32_bf16 v[68:71], v[152:155], v[104:107], v[68:71]
	v_mfma_f32_16x16x32_bf16 v[60:63], v[152:155], v[112:115], v[60:63]
	s_waitcnt vmcnt(7)
	ds_write_b128 v126, v[4:7] offset:20608
	global_load_dwordx4 v[4:7], v120, s[50:51] offset:384
	v_mfma_f32_16x16x32_bf16 v[52:55], v[152:155], v[108:111], v[52:55]
	v_mfma_f32_16x16x32_bf16 v[44:47], v[156:159], v[64:67], v[44:47]
	v_mfma_f32_16x16x32_bf16 v[40:43], v[156:159], v[104:107], v[40:43]
	s_waitcnt vmcnt(7)
	ds_write_b128 v126, v[0:3] offset:22656
	global_load_dwordx4 v[0:3], v122, s[50:51] offset:384
	v_mfma_f32_16x16x32_bf16 v[36:39], v[156:159], v[112:115], v[36:39]
	v_mfma_f32_16x16x32_bf16 v[28:31], v[156:159], v[108:111], v[28:31]
	s_cmp_lt_u32 s44, 12
	s_mov_b32 s13, s44
	s_waitcnt lgkmcnt(0)
	s_barrier
	s_cbranch_scc1 .LBB0_639
	ds_read_b128 v[144:147], v124
	ds_read_b128 v[128:131], v125 offset:16512
	ds_read_b128 v[132:135], v125 offset:17536
	ds_read_b128 v[136:139], v125 offset:18560
	ds_read_b128 v[140:143], v125 offset:19584
	v_mfma_f32_16x16x32_bf16 v[64:67], v[48:51], v[64:67], v[92:95]
	s_add_i32 s44, s13, 2
	s_add_i32 s13, s13, 4
	s_min_u32 s13, s13, 15
	v_mfma_f32_16x16x32_bf16 v[88:91], v[48:51], v[104:107], v[88:91]
	s_lshl_b32 s13, s13, 7
	s_add_u32 s48, s16, s13
	s_addc_u32 s49, s17, 0
	v_mfma_f32_16x16x32_bf16 v[80:83], v[48:51], v[112:115], v[80:83]
	v_mfma_f32_16x16x32_bf16 v[48:51], v[48:51], v[108:111], v[56:59]
	s_waitcnt lgkmcnt(3)
	v_mfma_f32_16x16x32_bf16 v[56:59], v[144:147], v[128:131], v[100:103]
	ds_read_b128 v[92:95], v124 offset:1024
	s_waitcnt lgkmcnt(3)
	v_mfma_f32_16x16x32_bf16 v[96:99], v[144:147], v[132:135], v[96:99]
	ds_read_b128 v[100:103], v124 offset:2048
	s_waitcnt lgkmcnt(3)
	v_mfma_f32_16x16x32_bf16 v[84:87], v[144:147], v[136:139], v[84:87]
	ds_read_b128 v[104:107], v124 offset:3072
	s_waitcnt lgkmcnt(3)
	v_mfma_f32_16x16x32_bf16 v[76:79], v[144:147], v[140:143], v[76:79]
	ds_read_b128 v[108:111], v124 offset:8256
	s_waitcnt lgkmcnt(3)
	v_mfma_f32_16x16x32_bf16 v[72:75], v[92:95], v[128:131], v[72:75]
	ds_read_b128 v[112:115], v124 offset:9280
	v_mfma_f32_16x16x32_bf16 v[68:71], v[92:95], v[132:135], v[68:71]
	ds_read_b128 v[144:147], v124 offset:10304
	v_mfma_f32_16x16x32_bf16 v[60:63], v[92:95], v[136:139], v[60:63]
	ds_read_b128 v[148:151], v124 offset:11328
	v_mfma_f32_16x16x32_bf16 v[52:55], v[92:95], v[140:143], v[52:55]
	ds_read_b128 v[92:95], v125 offset:24768
	s_waitcnt lgkmcnt(6)
	v_mfma_f32_16x16x32_bf16 v[44:47], v[100:103], v[128:131], v[44:47]
	ds_read_b128 v[152:155], v125 offset:25792
	v_mfma_f32_16x16x32_bf16 v[40:43], v[100:103], v[132:135], v[40:43]
	ds_read_b128 v[156:159], v125 offset:26816
	v_mfma_f32_16x16x32_bf16 v[36:39], v[100:103], v[136:139], v[36:39]
	ds_read_b128 v[160:163], v125 offset:27840
	v_mfma_f32_16x16x32_bf16 v[28:31], v[100:103], v[140:143], v[28:31]
	s_waitcnt lgkmcnt(8)
	v_mfma_f32_16x16x32_bf16 v[64:67], v[104:107], v[128:131], v[64:67]
	s_waitcnt vmcnt(7)
	ds_write_b128 v126, v[32:35] offset:33024
	v_mfma_f32_16x16x32_bf16 v[88:91], v[104:107], v[132:135], v[88:91]
	v_mfma_f32_16x16x32_bf16 v[80:83], v[104:107], v[136:139], v[80:83]
	s_waitcnt vmcnt(6)
	ds_write_b128 v126, v[20:23] offset:35072
	v_mfma_f32_16x16x32_bf16 v[48:51], v[104:107], v[140:143], v[48:51]
	s_waitcnt lgkmcnt(5)
	v_mfma_f32_16x16x32_bf16 v[56:59], v[108:111], v[92:95], v[56:59]
	s_waitcnt vmcnt(5)
	ds_write_b128 v126, v[16:19] offset:37120
	s_add_u32 s48, s20, s13
	s_addc_u32 s49, s21, 0
	s_waitcnt lgkmcnt(5)
	v_mfma_f32_16x16x32_bf16 v[96:99], v[108:111], v[152:155], v[96:99]
	s_min_u32 s13, s44, 12
	s_lshl_b32 s13, s13, 7
	s_waitcnt lgkmcnt(4)
	v_mfma_f32_16x16x32_bf16 v[84:87], v[108:111], v[156:159], v[84:87]
	s_waitcnt vmcnt(4)
	ds_write_b128 v126, v[24:27] offset:39168
	s_waitcnt lgkmcnt(4)
	v_mfma_f32_16x16x32_bf16 v[76:79], v[108:111], v[160:163], v[76:79]
	v_mfma_f32_16x16x32_bf16 v[72:75], v[112:115], v[92:95], v[72:75]
	s_waitcnt vmcnt(3)
	ds_write_b128 v126, v[12:15] offset:49536
	v_mfma_f32_16x16x32_bf16 v[68:71], v[112:115], v[152:155], v[68:71]
	v_mfma_f32_16x16x32_bf16 v[60:63], v[112:115], v[156:159], v[60:63]
	s_waitcnt vmcnt(2)
	ds_write_b128 v126, v[8:11] offset:51584
	v_mfma_f32_16x16x32_bf16 v[52:55], v[112:115], v[160:163], v[52:55]
	v_mfma_f32_16x16x32_bf16 v[44:47], v[144:147], v[92:95], v[44:47]
	s_waitcnt vmcnt(1)
	ds_write_b128 v126, v[4:7] offset:53632
	v_mfma_f32_16x16x32_bf16 v[40:43], v[144:147], v[152:155], v[40:43]
	s_add_u32 s48, s16, s13
	s_addc_u32 s49, s17, 0
	s_add_u32 s50, s20, s13
	v_mfma_f32_16x16x32_bf16 v[36:39], v[144:147], v[156:159], v[36:39]
	s_waitcnt vmcnt(0)
	ds_write_b128 v126, v[0:3] offset:55680
	s_addc_u32 s51, s21, 0
	v_mfma_f32_16x16x32_bf16 v[28:31], v[144:147], v[160:163], v[28:31]
	v_mfma_f32_16x16x32_bf16 v[92:95], v[148:151], v[92:95], v[64:67]
	v_mfma_f32_16x16x32_bf16 v[88:91], v[148:151], v[152:155], v[88:91]
	v_mfma_f32_16x16x32_bf16 v[80:83], v[148:151], v[156:159], v[80:83]
	v_mfma_f32_16x16x32_bf16 v[100:103], v[148:151], v[160:163], v[48:51]
	s_waitcnt lgkmcnt(0)
	s_barrier
	s_nop 0
	ds_read_b128 v[48:51], v124 offset:33024
	ds_read_b128 v[108:111], v125 offset:49536
	ds_read_b128 v[128:131], v125 offset:50560
	ds_read_b128 v[132:135], v125 offset:51584
	ds_read_b128 v[136:139], v125 offset:52608
	s_waitcnt lgkmcnt(3)
	v_mfma_f32_16x16x32_bf16 v[140:143], v[48:51], v[108:111], v[56:59]
	s_waitcnt lgkmcnt(2)
	v_mfma_f32_16x16x32_bf16 v[96:99], v[48:51], v[128:131], v[96:99]
	s_waitcnt lgkmcnt(1)
	v_mfma_f32_16x16x32_bf16 v[84:87], v[48:51], v[132:135], v[84:87]
	s_waitcnt lgkmcnt(0)
	v_mfma_f32_16x16x32_bf16 v[76:79], v[48:51], v[136:139], v[76:79]
	ds_read_b128 v[48:51], v124 offset:34048
	s_waitcnt lgkmcnt(0)
	v_mfma_f32_16x16x32_bf16 v[72:75], v[48:51], v[108:111], v[72:75]
	ds_read_b128 v[56:59], v124 offset:35072
	v_mfma_f32_16x16x32_bf16 v[68:71], v[48:51], v[128:131], v[68:71]
	ds_read_b128 v[144:147], v124 offset:36096
	v_mfma_f32_16x16x32_bf16 v[60:63], v[48:51], v[132:135], v[60:63]
	ds_read_b128 v[148:151], v124 offset:41280
	v_mfma_f32_16x16x32_bf16 v[52:55], v[48:51], v[136:139], v[52:55]
	ds_read_b128 v[152:155], v124 offset:42304
	s_waitcnt lgkmcnt(3)
	v_mfma_f32_16x16x32_bf16 v[44:47], v[56:59], v[108:111], v[44:47]
	ds_read_b128 v[156:159], v124 offset:43328
	v_mfma_f32_16x16x32_bf16 v[40:43], v[56:59], v[128:131], v[40:43]
	ds_read_b128 v[48:51], v124 offset:44352
	v_mfma_f32_16x16x32_bf16 v[36:39], v[56:59], v[132:135], v[36:39]
	ds_read_b128 v[64:67], v125 offset:57792
	v_mfma_f32_16x16x32_bf16 v[28:31], v[56:59], v[136:139], v[28:31]
	ds_read_b128 v[104:107], v125 offset:58816
	s_waitcnt lgkmcnt(6)
	v_mfma_f32_16x16x32_bf16 v[92:95], v[144:147], v[108:111], v[92:95]
	ds_read_b128 v[112:115], v125 offset:59840
	v_mfma_f32_16x16x32_bf16 v[88:91], v[144:147], v[128:131], v[88:91]
	ds_read_b128 v[108:111], v125 offset:60864
	v_mfma_f32_16x16x32_bf16 v[80:83], v[144:147], v[132:135], v[80:83]
	v_mfma_f32_16x16x32_bf16 v[56:59], v[144:147], v[136:139], v[100:103]
	ds_write_b128 v126, v[32:35]
	s_waitcnt lgkmcnt(4)
	v_mfma_f32_16x16x32_bf16 v[100:103], v[148:151], v[64:67], v[140:143]
	s_waitcnt lgkmcnt(3)
	v_mfma_f32_16x16x32_bf16 v[96:99], v[148:151], v[104:107], v[96:99]
	ds_write_b128 v126, v[20:23] offset:2048
	s_waitcnt lgkmcnt(3)
	v_mfma_f32_16x16x32_bf16 v[84:87], v[148:151], v[112:115], v[84:87]
	s_waitcnt lgkmcnt(2)
	v_mfma_f32_16x16x32_bf16 v[76:79], v[148:151], v[108:111], v[76:79]
	ds_write_b128 v126, v[16:19] offset:4096
	v_mfma_f32_16x16x32_bf16 v[72:75], v[152:155], v[64:67], v[72:75]
	v_mfma_f32_16x16x32_bf16 v[68:71], v[152:155], v[104:107], v[68:71]
	ds_write_b128 v126, v[24:27] offset:6144
	v_mfma_f32_16x16x32_bf16 v[60:63], v[152:155], v[112:115], v[60:63]
	v_mfma_f32_16x16x32_bf16 v[52:55], v[152:155], v[108:111], v[52:55]
	ds_write_b128 v126, v[12:15] offset:16512
	v_mfma_f32_16x16x32_bf16 v[44:47], v[156:159], v[64:67], v[44:47]
	v_mfma_f32_16x16x32_bf16 v[40:43], v[156:159], v[104:107], v[40:43]
	ds_write_b128 v126, v[8:11] offset:18560
	v_mfma_f32_16x16x32_bf16 v[36:39], v[156:159], v[112:115], v[36:39]
	v_mfma_f32_16x16x32_bf16 v[28:31], v[156:159], v[108:111], v[28:31]
	ds_write_b128 v126, v[4:7] offset:20608
	ds_write_b128 v126, v[0:3] offset:22656
	s_cmp_lt_u32 s44, 14
	s_mov_b32 s13, s44
	s_waitcnt lgkmcnt(0)
	s_barrier
	s_waitcnt vmcnt(5)
	v_mov_b32_e32 v16, v232
	s_waitcnt vmcnt(0)
	v_mfma_f32_16x16x32_bf16 v[0:3], v[48:51], v[64:67], v[92:95]
	v_lshrrev_b32_e32 v18, 2, v16
	v_lshrrev_b32_e32 v17, 1, v16
	v_and_b32_e32 v18, 12, v18
	v_and_or_b32 v17, v17, s40, v18
	v_and_b32_e32 v18, 0x4f, v16
	v_mul_lo_u32 v17, v17, s42
	v_lshl_add_u32 v17, v18, 1, v17
	v_cvt_pk_bf16_f32 v18, v101, v102
	ds_write_b16 v17, v18 offset:272
	ds_write_b16_d16_hi v17, v18 offset:544
	v_cvt_pk_bf16_f32 v18, v103, v96
	ds_write_b16 v17, v18 offset:816
	ds_write_b16_d16_hi v17, v18 offset:32
	v_cvt_pk_bf16_f32 v18, v97, v98
	ds_write_b16 v17, v18 offset:304
	ds_write_b16_d16_hi v17, v18 offset:576
	v_cvt_pk_bf16_f32 v18, v99, v84
	ds_write_b16 v17, v18 offset:848
	ds_write_b16_d16_hi v17, v18 offset:64
	v_cvt_pk_bf16_f32 v18, v85, v86
	ds_write_b16 v17, v18 offset:336
	ds_write_b16_d16_hi v17, v18 offset:608
	v_cvt_pk_bf16_f32 v18, v87, v76
	ds_write_b16 v17, v18 offset:880
	ds_write_b16_d16_hi v17, v18 offset:96
	v_cvt_pk_bf16_f32 v18, v77, v78
	ds_write_b16 v17, v18 offset:368
	ds_write_b16_d16_hi v17, v18 offset:640
	v_cvt_pk_bf16_f32 v18, v79, v72
	ds_write_b16 v17, v18 offset:912
	ds_write_b16_d16_hi v17, v18 offset:4352
	v_cvt_pk_bf16_f32 v18, v73, v74
	ds_write_b16 v17, v18 offset:4624
	ds_write_b16_d16_hi v17, v18 offset:4896
	v_cvt_pk_bf16_f32 v18, v75, v68
	ds_write_b16 v17, v18 offset:5168
	ds_write_b16_d16_hi v17, v18 offset:4384
	v_cvt_pk_bf16_f32 v18, v69, v70
	ds_write_b16 v17, v18 offset:4656
	ds_write_b16_d16_hi v17, v18 offset:4928
	v_cvt_pk_bf16_f32 v18, v71, v60
	ds_write_b16 v17, v18 offset:5200
	ds_write_b16_d16_hi v17, v18 offset:4416
	v_cvt_pk_bf16_f32 v18, v61, v62
	ds_write_b16 v17, v18 offset:4688
	ds_write_b16_d16_hi v17, v18 offset:4960
	v_cvt_pk_bf16_f32 v18, v63, v52
	ds_write_b16 v17, v18 offset:5232
	ds_write_b16_d16_hi v17, v18 offset:4448
	v_cvt_pk_bf16_f32 v18, v53, v54
	ds_write_b16 v17, v18 offset:4720
	ds_write_b16_d16_hi v17, v18 offset:4992
	v_cvt_pk_bf16_f32 v18, v55, v44
	ds_write_b16 v17, v18 offset:5264
	ds_write_b16_d16_hi v17, v18 offset:8704
	v_cvt_pk_bf16_f32 v18, v45, v46
	ds_write_b16 v17, v18 offset:8976
	ds_write_b16_d16_hi v17, v18 offset:9248
	v_cvt_pk_bf16_f32 v18, v47, v40
	ds_write_b16 v17, v18 offset:9520
	ds_write_b16_d16_hi v17, v18 offset:8736
	v_cvt_pk_bf16_f32 v18, v41, v42
	ds_write_b16 v17, v18 offset:9008
	ds_write_b16_d16_hi v17, v18 offset:9280
	v_cvt_pk_bf16_f32 v18, v43, v36
	ds_write_b16 v17, v18 offset:9552
	ds_write_b16_d16_hi v17, v18 offset:8768
	v_cvt_pk_bf16_f32 v18, v37, v38
	ds_write_b16 v17, v18 offset:9040
	ds_write_b16_d16_hi v17, v18 offset:9312
	v_cvt_pk_bf16_f32 v18, v39, v28
	ds_write_b16 v17, v18 offset:9584
	ds_write_b16_d16_hi v17, v18 offset:8800
	v_cvt_pk_bf16_f32 v18, v29, v30
	ds_write_b16 v17, v18 offset:9072
	ds_write_b16_d16_hi v17, v18 offset:9344
	v_cvt_pk_bf16_f32 v18, 0, v31
	ds_write_b16_d16_hi v17, v18 offset:9616
	v_cvt_pk_bf16_f32 v0, 0, v0
	ds_write_b16_d16_hi v17, v0 offset:13056
	v_cvt_pk_bf16_f32 v0, 0, v1
	v_mfma_f32_16x16x32_bf16 v[4:7], v[48:51], v[104:107], v[88:91]
	ds_write_b16_d16_hi v17, v0 offset:13328
	v_cvt_pk_bf16_f32 v0, v2, v3
	ds_write_b16 v17, v0 offset:13600
	ds_write_b16_d16_hi v17, v0 offset:13872
	s_nop 0
	s_nop 1
	s_nop 0
	v_cvt_pk_bf16_f32 v0, 0, v4
	ds_write_b16_d16_hi v17, v0 offset:13088
	v_cvt_pk_bf16_f32 v0, 0, v5
	v_mfma_f32_16x16x32_bf16 v[8:11], v[48:51], v[112:115], v[80:83]
	ds_write_b16_d16_hi v17, v0 offset:13360
	v_cvt_pk_bf16_f32 v0, v6, v7
	ds_write_b16 v17, v0 offset:13632
	ds_write_b16_d16_hi v17, v0 offset:13904
	s_nop 0
	s_nop 1
	s_nop 0
	v_cvt_pk_bf16_f32 v0, 0, v8
	ds_write_b16_d16_hi v17, v0 offset:13120
	v_cvt_pk_bf16_f32 v0, 0, v9
	v_mfma_f32_16x16x32_bf16 v[12:15], v[48:51], v[108:111], v[56:59]
	ds_write_b16_d16_hi v17, v0 offset:13392
	v_cvt_pk_bf16_f32 v0, v10, v11
	ds_write_b16 v17, v0 offset:13664
	ds_write_b16_d16_hi v17, v0 offset:13936
	s_nop 0
	s_nop 1
	s_nop 0
	v_cvt_pk_bf16_f32 v0, v12, v13
	ds_write_b16 v17, v0 offset:13152
	ds_write_b16_d16_hi v17, v0 offset:13424
	v_cvt_pk_bf16_f32 v0, 0, v14
	ds_write_b16_d16_hi v17, v0 offset:13696
	s_lshl_b64 s[14:15], s[14:15], 1
	v_cvt_pk_bf16_f32 v0, 0, v15
	s_add_u32 s14, s26, s14
	ds_write_b16_d16_hi v17, v0 offset:13968
	v_ashrrev_i32_e32 v0, 31, v16
	s_addc_u32 s15, s27, s15
	s_lshl_b32 s12, s12, 7
	v_lshrrev_b32_e32 v0, 28, v0
	s_ashr_i32 s13, s12, 31
	v_add_u32_e32 v0, v16, v0
	s_lshl_b64 s[12:13], s[12:13], 1
	v_ashrrev_i32_e32 v4, 4, v0
	v_and_b32_e32 v0, -16, v0
	s_add_u32 s12, s14, s12
	v_sub_u32_e32 v0, v16, v0
	v_ashrrev_i32_e32 v5, 31, v4
	s_addc_u32 s13, s15, s13
	v_mul_lo_u32 v1, v4, s42
	v_lshlrev_b32_e32 v6, 3, v0
	v_lshlrev_b64 v[4:5], 11, v[4:5]
	v_ashrrev_i32_e32 v7, 31, v6
	v_lshl_add_u64 v[4:5], s[12:13], 0, v[4:5]
	v_lshl_add_u64 v[8:9], v[6:7], 1, v[4:5]
	v_add_u32_e32 v4, 0x100, v16
	v_ashrrev_i32_e32 v5, 31, v4
	v_cvt_pk_bf16_f32 v19, 0, v100
	v_lshl_add_u32 v0, v0, 4, v1
	v_lshrrev_b32_e32 v5, 28, v5
	ds_write_b16_d16_hi v17, v19
	s_waitcnt lgkmcnt(0)
	s_barrier
	ds_read_b128 v[0:3], v0
	v_add_u32_e32 v5, v4, v5
	v_ashrrev_i32_e32 v10, 4, v5
	v_and_b32_e32 v5, -16, v5
	v_sub_u32_e32 v11, v4, v5
	v_mul_lo_u32 v4, v10, s42
	v_lshl_add_u32 v4, v11, 4, v4
	ds_read_b128 v[4:7], v4
	s_waitcnt lgkmcnt(1)
	global_store_dwordx4 v[8:9], v[0:3], off
	s_add_i32 s43, s43, s61
	s_cmp_lt_i32 s43, s62
	v_lshlrev_b32_e32 v0, 3, v11
	v_ashrrev_i32_e32 v11, 31, v10
	v_lshlrev_b64 v[2:3], 11, v[10:11]
	v_ashrrev_i32_e32 v1, 31, v0
	v_lshl_add_u64 v[2:3], s[12:13], 0, v[2:3]
	v_lshl_add_u64 v[0:1], v[0:1], 1, v[2:3]
	s_waitcnt lgkmcnt(0)
	global_store_dwordx4 v[0:1], v[4:7], off
	v_add_u32_e32 v0, 0x200, v16
	v_ashrrev_i32_e32 v1, 31, v0
	v_lshrrev_b32_e32 v1, 28, v1
	v_add_u32_e32 v1, v0, v1
	v_ashrrev_i32_e32 v4, 4, v1
	v_and_b32_e32 v1, -16, v1
	v_sub_u32_e32 v0, v0, v1
	v_ashrrev_i32_e32 v5, 31, v4
	v_mul_lo_u32 v1, v4, s42
	v_lshlrev_b32_e32 v6, 3, v0
	v_lshlrev_b64 v[4:5], 11, v[4:5]
	v_ashrrev_i32_e32 v7, 31, v6
	v_lshl_add_u64 v[4:5], s[12:13], 0, v[4:5]
	v_lshl_add_u64 v[8:9], v[6:7], 1, v[4:5]
	v_add_u32_e32 v4, 0x300, v16
	v_ashrrev_i32_e32 v5, 31, v4
	v_lshl_add_u32 v0, v0, 4, v1
	v_lshrrev_b32_e32 v5, 28, v5
	ds_read_b128 v[0:3], v0
	v_add_u32_e32 v5, v4, v5
	v_ashrrev_i32_e32 v10, 4, v5
	v_and_b32_e32 v5, -16, v5
	v_sub_u32_e32 v11, v4, v5
	v_mul_lo_u32 v4, v10, s42
	v_lshl_add_u32 v4, v11, 4, v4
	ds_read_b128 v[4:7], v4
	s_waitcnt lgkmcnt(1)
	global_store_dwordx4 v[8:9], v[0:3], off
	s_nop 1
	v_lshlrev_b32_e32 v0, 3, v11
	v_ashrrev_i32_e32 v11, 31, v10
	v_lshlrev_b64 v[2:3], 11, v[10:11]
	v_ashrrev_i32_e32 v1, 31, v0
	v_lshl_add_u64 v[2:3], s[12:13], 0, v[2:3]
	v_lshl_add_u64 v[0:1], v[0:1], 1, v[2:3]
	s_waitcnt lgkmcnt(0)
	global_store_dwordx4 v[0:1], v[4:7], off
	v_add_u32_e32 v0, 0x400, v16
	v_ashrrev_i32_e32 v1, 31, v0
	v_lshrrev_b32_e32 v1, 28, v1
	v_add_u32_e32 v1, v0, v1
	v_ashrrev_i32_e32 v4, 4, v1
	v_and_b32_e32 v1, -16, v1
	v_sub_u32_e32 v0, v0, v1
	v_ashrrev_i32_e32 v5, 31, v4
	v_mul_lo_u32 v1, v4, s42
	v_lshlrev_b32_e32 v6, 3, v0
	v_lshlrev_b64 v[4:5], 11, v[4:5]
	v_ashrrev_i32_e32 v7, 31, v6
	v_lshl_add_u64 v[4:5], s[12:13], 0, v[4:5]
	v_lshl_add_u64 v[8:9], v[6:7], 1, v[4:5]
	v_add_u32_e32 v4, 0x500, v16
	v_ashrrev_i32_e32 v5, 31, v4
	v_lshl_add_u32 v0, v0, 4, v1
	v_lshrrev_b32_e32 v5, 28, v5
	ds_read_b128 v[0:3], v0
	v_add_u32_e32 v5, v4, v5
	v_ashrrev_i32_e32 v10, 4, v5
	v_and_b32_e32 v5, -16, v5
	v_sub_u32_e32 v11, v4, v5
	v_mul_lo_u32 v4, v10, s42
	v_lshl_add_u32 v4, v11, 4, v4
	ds_read_b128 v[4:7], v4
	s_waitcnt lgkmcnt(1)
	global_store_dwordx4 v[8:9], v[0:3], off
	s_nop 1
	v_lshlrev_b32_e32 v0, 3, v11
	v_ashrrev_i32_e32 v11, 31, v10
	v_lshlrev_b64 v[2:3], 11, v[10:11]
	v_ashrrev_i32_e32 v1, 31, v0
	v_lshl_add_u64 v[2:3], s[12:13], 0, v[2:3]
	v_lshl_add_u64 v[0:1], v[0:1], 1, v[2:3]
	s_waitcnt lgkmcnt(0)
	global_store_dwordx4 v[0:1], v[4:7], off
	v_add_u32_e32 v0, 0x600, v16
	v_ashrrev_i32_e32 v1, 31, v0
	v_lshrrev_b32_e32 v1, 28, v1
	v_add_u32_e32 v1, v0, v1
	v_ashrrev_i32_e32 v4, 4, v1
	v_and_b32_e32 v1, -16, v1
	v_sub_u32_e32 v0, v0, v1
	v_ashrrev_i32_e32 v5, 31, v4
	v_mul_lo_u32 v1, v4, s42
	v_lshlrev_b32_e32 v6, 3, v0
	v_lshlrev_b64 v[4:5], 11, v[4:5]
	v_ashrrev_i32_e32 v7, 31, v6
	v_lshl_add_u64 v[4:5], s[12:13], 0, v[4:5]
	v_lshl_add_u64 v[8:9], v[6:7], 1, v[4:5]
	v_add_u32_e32 v4, 0x700, v16
	v_ashrrev_i32_e32 v5, 31, v4
	v_lshl_add_u32 v0, v0, 4, v1
	v_lshrrev_b32_e32 v5, 28, v5
	ds_read_b128 v[0:3], v0
	v_add_u32_e32 v5, v4, v5
	v_ashrrev_i32_e32 v10, 4, v5
	v_and_b32_e32 v5, -16, v5
	v_sub_u32_e32 v11, v4, v5
	v_mul_lo_u32 v4, v10, s42
	v_lshl_add_u32 v4, v11, 4, v4
	ds_read_b128 v[4:7], v4
	s_waitcnt lgkmcnt(1)
	global_store_dwordx4 v[8:9], v[0:3], off
	s_nop 1
	v_lshlrev_b32_e32 v0, 3, v11
	v_ashrrev_i32_e32 v11, 31, v10
	v_lshlrev_b64 v[2:3], 11, v[10:11]
	v_ashrrev_i32_e32 v1, 31, v0
	v_lshl_add_u64 v[2:3], s[12:13], 0, v[2:3]
	v_lshl_add_u64 v[0:1], v[0:1], 1, v[2:3]
	s_waitcnt lgkmcnt(0)
	global_store_dwordx4 v[0:1], v[4:7], off
	s_cbranch_scc1 .LBB0_638

; template <int WM, int WN>
; __device__ __forceinline__ void store_tile_bf16(const f32x4 (&acc)[WM][WN], u16* dst, int ld, char* smem) {
;   constexpr int BM = 32 * WM, BN = 32 * WN, STR = BN + 8;
;   const int tid = opaque_tid(), lane = tid & 63, wid = tid >> 6;
;   const int wr = wid >> 1, wc = wid & 1, fr = lane & 15, fq = lane >> 4;
;   u16* T = reinterpret_cast<u16*>(smem);
; #pragma unroll
;   for (int m = 0; m < WM; ++m)
; #pragma unroll
;     for (int n = 0; n < WN; ++n)
; #pragma unroll
;       for (int j = 0; j < 4; ++j)
;         T[(wr * 16 * WM + m * 16 + fq * 4 + j) * STR + wc * 16 * WN + n * 16 + fr] = f2bf(acc[m][n][j]);
;   __syncthreads();
.LBB0_744:
	v_mov_b32_e32 v64, v232
	v_lshrrev_b32_e32 v66, 2, v64
	s_waitcnt lgkmcnt(0)
	v_lshrrev_b32_e32 v65, 1, v64
	v_and_b32_e32 v66, 12, v66
	v_and_or_b32 v65, v65, s51, v66
	v_and_b32_e32 v66, 0x4f, v64
	v_mul_lo_u32 v65, v65, s53
	v_cvt_pk_bf16_f32 v44, 0, v44
	v_lshl_add_u32 v65, v66, 1, v65
	ds_write_b16_d16_hi v65, v44
	v_cvt_pk_bf16_f32 v44, v45, v46
	ds_write_b16 v65, v44 offset:272
	ds_write_b16_d16_hi v65, v44 offset:544
	v_cvt_pk_bf16_f32 v44, 0, v47
	ds_write_b16_d16_hi v65, v44 offset:816
	v_cvt_pk_bf16_f32 v40, 0, v40
	ds_write_b16_d16_hi v65, v40 offset:32
	v_cvt_pk_bf16_f32 v40, v41, v42
	ds_write_b16 v65, v40 offset:304
	ds_write_b16_d16_hi v65, v40 offset:576
	v_cvt_pk_bf16_f32 v40, 0, v43
	ds_write_b16_d16_hi v65, v40 offset:848
	v_cvt_pk_bf16_f32 v36, 0, v36
	ds_write_b16_d16_hi v65, v36 offset:64
	v_cvt_pk_bf16_f32 v36, v37, v38
	ds_write_b16 v65, v36 offset:336
	ds_write_b16_d16_hi v65, v36 offset:608
	v_cvt_pk_bf16_f32 v36, 0, v39
	ds_write_b16_d16_hi v65, v36 offset:880
	v_cvt_pk_bf16_f32 v32, 0, v32
	ds_write_b16_d16_hi v65, v32 offset:96
	v_cvt_pk_bf16_f32 v32, v33, v34
	ds_write_b16 v65, v32 offset:368
	ds_write_b16_d16_hi v65, v32 offset:640
	v_cvt_pk_bf16_f32 v32, 0, v35
	ds_write_b16_d16_hi v65, v32 offset:912
	v_cvt_pk_bf16_f32 v28, 0, v28
	ds_write_b16_d16_hi v65, v28 offset:4352
	v_cvt_pk_bf16_f32 v28, v29, v30
	ds_write_b16 v65, v28 offset:4624
	ds_write_b16_d16_hi v65, v28 offset:4896
	v_cvt_pk_bf16_f32 v28, 0, v31
	ds_write_b16_d16_hi v65, v28 offset:5168
	v_cvt_pk_bf16_f32 v24, 0, v24
	ds_write_b16_d16_hi v65, v24 offset:4384
	v_cvt_pk_bf16_f32 v24, v25, v26
	ds_write_b16 v65, v24 offset:4656
	ds_write_b16_d16_hi v65, v24 offset:4928
	v_cvt_pk_bf16_f32 v24, 0, v27
	ds_write_b16_d16_hi v65, v24 offset:5200
	v_cvt_pk_bf16_f32 v20, 0, v20
	ds_write_b16_d16_hi v65, v20 offset:4416
	v_cvt_pk_bf16_f32 v20, v21, v22
	ds_write_b16 v65, v20 offset:4688
	ds_write_b16_d16_hi v65, v20 offset:4960
	v_cvt_pk_bf16_f32 v20, 0, v23
	ds_write_b16_d16_hi v65, v20 offset:5232
	v_cvt_pk_bf16_f32 v16, 0, v16
	ds_write_b16_d16_hi v65, v16 offset:4448
	v_cvt_pk_bf16_f32 v16, v17, v18
	ds_write_b16 v65, v16 offset:4720
	ds_write_b16_d16_hi v65, v16 offset:4992
	v_cvt_pk_bf16_f32 v16, 0, v19
	ds_write_b16_d16_hi v65, v16 offset:5264
	v_cvt_pk_bf16_f32 v12, 0, v12
	ds_write_b16_d16_hi v65, v12 offset:8704
	v_cvt_pk_bf16_f32 v12, v13, v14
	ds_write_b16 v65, v12 offset:8976
	ds_write_b16_d16_hi v65, v12 offset:9248
	v_cvt_pk_bf16_f32 v12, 0, v15
	ds_write_b16_d16_hi v65, v12 offset:9520
	v_cvt_pk_bf16_f32 v8, 0, v8
	ds_write_b16_d16_hi v65, v8 offset:8736
	v_cvt_pk_bf16_f32 v8, v9, v10
	ds_write_b16 v65, v8 offset:9008
	ds_write_b16_d16_hi v65, v8 offset:9280
	v_cvt_pk_bf16_f32 v8, 0, v11
	ds_write_b16_d16_hi v65, v8 offset:9552
	v_cvt_pk_bf16_f32 v4, 0, v4
	ds_write_b16_d16_hi v65, v4 offset:8768
	v_cvt_pk_bf16_f32 v4, v5, v6
	ds_write_b16 v65, v4 offset:9040
	ds_write_b16_d16_hi v65, v4 offset:9312
	v_cvt_pk_bf16_f32 v4, 0, v7
	ds_write_b16_d16_hi v65, v4 offset:9584
	v_cvt_pk_bf16_f32 v0, 0, v0
	ds_write_b16_d16_hi v65, v0 offset:8800
	v_cvt_pk_bf16_f32 v0, v1, v2
	ds_write_b16 v65, v0 offset:9072
	ds_write_b16_d16_hi v65, v0 offset:9344
	v_cvt_pk_bf16_f32 v0, v3, v60
	ds_write_b16 v65, v0 offset:9616
	ds_write_b16_d16_hi v65, v0 offset:13056
	v_cvt_pk_bf16_f32 v0, v61, v62
	ds_write_b16 v65, v0 offset:13328
	ds_write_b16_d16_hi v65, v0 offset:13600
	v_cvt_pk_bf16_f32 v0, v63, v56
	ds_write_b16 v65, v0 offset:13872
	ds_write_b16_d16_hi v65, v0 offset:13088
	v_cvt_pk_bf16_f32 v0, v57, v58
	ds_write_b16 v65, v0 offset:13360
	ds_write_b16_d16_hi v65, v0 offset:13632
	v_cvt_pk_bf16_f32 v0, v59, v52
	ds_write_b16 v65, v0 offset:13904
	ds_write_b16_d16_hi v65, v0 offset:13120
	v_cvt_pk_bf16_f32 v0, v53, v54
	ds_write_b16 v65, v0 offset:13392
	ds_write_b16_d16_hi v65, v0 offset:13664
	v_cvt_pk_bf16_f32 v0, v55, v48
	ds_write_b16 v65, v0 offset:13936
	ds_write_b16_d16_hi v65, v0 offset:13152
	v_cvt_pk_bf16_f32 v0, v49, v50
	ds_write_b16 v65, v0 offset:13424
	ds_write_b16_d16_hi v65, v0 offset:13696
	s_lshl_b32 s22, s22, 7
	s_mul_hi_i32 s16, s20, 0x130000
	s_mul_i32 s20, s20, 0x130000
	v_cvt_pk_bf16_f32 v0, 0, v51
	s_add_u32 s24, s40, s20
	ds_write_b16_d16_hi v65, v0 offset:13968
	v_ashrrev_i32_e32 v0, 31, v64
	s_addc_u32 s16, s41, s16
	s_ashr_i32 s23, s22, 31
	v_lshrrev_b32_e32 v0, 28, v0
	s_lshl_b64 s[20:21], s[22:23], 1
	v_add_u32_e32 v0, v64, v0
	s_add_u32 s20, s24, s20
	v_ashrrev_i32_e32 v6, 4, v0
	v_and_b32_e32 v0, -16, v0
	s_addc_u32 s21, s16, s21
	v_sub_u32_e32 v0, v64, v0
	v_lshlrev_b32_e32 v4, 3, v0
	v_mov_b64_e32 v[8:9], s[20:21]
	v_mul_lo_u32 v1, v6, s53
	v_ashrrev_i32_e32 v5, 31, v4
	v_mad_i64_i32 v[6:7], s[20:21], v6, s54, v[8:9]
	v_lshl_add_u64 v[10:11], v[4:5], 1, v[6:7]
	v_add_u32_e32 v4, 0x100, v64
	v_ashrrev_i32_e32 v5, 31, v4
	v_lshrrev_b32_e32 v5, 28, v5
	v_lshl_add_u32 v0, v0, 4, v1
	v_add_u32_e32 v5, v4, v5
	s_waitcnt lgkmcnt(0)
	s_barrier
; template <int WM, int WN>
; __device__ __forceinline__ void store_tile_bf16(const f32x4 (&acc)[WM][WN], u16* dst, int ld, char* smem) {
;     ...
;   constexpr int CPR = BN / 8;
; #pragma unroll
;   for (int i = 0; i < BM * CPR / 256; ++i) {
;     int q = tid + 256 * i, row = q / CPR, c = q % CPR;
;     uint4 v = *reinterpret_cast<const uint4*>(T + row * STR + c * 8);
;     *reinterpret_cast<uint4*>(dst + (size_t)row * ld + c * 8) = v;
;   }
	ds_read_b128 v[0:3], v0
	v_ashrrev_i32_e32 v12, 4, v5
	v_and_b32_e32 v5, -16, v5
	v_sub_u32_e32 v13, v4, v5
	v_mul_lo_u32 v4, v12, s53
	v_lshl_add_u32 v4, v13, 4, v4
	ds_read_b128 v[4:7], v4
	s_waitcnt lgkmcnt(1)
	global_store_dwordx4 v[10:11], v[0:3], off
	s_add_i32 s55, s55, s61
	s_cmp_lt_i32 s55, s47
	v_lshlrev_b32_e32 v0, 3, v13
	v_ashrrev_i32_e32 v1, 31, v0
	v_mad_i64_i32 v[2:3], s[20:21], v12, s54, v[8:9]
	v_lshl_add_u64 v[0:1], v[0:1], 1, v[2:3]
	s_waitcnt lgkmcnt(0)
	global_store_dwordx4 v[0:1], v[4:7], off
	v_add_u32_e32 v0, 0x200, v64
	v_ashrrev_i32_e32 v1, 31, v0
	v_lshrrev_b32_e32 v1, 28, v1
	v_add_u32_e32 v1, v0, v1
	v_ashrrev_i32_e32 v6, 4, v1
	v_and_b32_e32 v1, -16, v1
	v_sub_u32_e32 v0, v0, v1
	v_lshlrev_b32_e32 v4, 3, v0
	v_mul_lo_u32 v1, v6, s53
	v_ashrrev_i32_e32 v5, 31, v4
	v_mad_i64_i32 v[6:7], s[20:21], v6, s54, v[8:9]
	v_lshl_add_u64 v[10:11], v[4:5], 1, v[6:7]
	v_add_u32_e32 v4, 0x300, v64
	v_ashrrev_i32_e32 v5, 31, v4
	v_lshrrev_b32_e32 v5, 28, v5
	v_lshl_add_u32 v0, v0, 4, v1
	v_add_u32_e32 v5, v4, v5
	ds_read_b128 v[0:3], v0
	v_ashrrev_i32_e32 v12, 4, v5
	v_and_b32_e32 v5, -16, v5
	v_sub_u32_e32 v13, v4, v5
	v_mul_lo_u32 v4, v12, s53
	v_lshl_add_u32 v4, v13, 4, v4
	ds_read_b128 v[4:7], v4
	s_waitcnt lgkmcnt(1)
	global_store_dwordx4 v[10:11], v[0:3], off
	s_nop 1
	v_lshlrev_b32_e32 v0, 3, v13
	v_ashrrev_i32_e32 v1, 31, v0
	v_mad_i64_i32 v[2:3], s[20:21], v12, s54, v[8:9]
	v_lshl_add_u64 v[0:1], v[0:1], 1, v[2:3]
	s_waitcnt lgkmcnt(0)
	global_store_dwordx4 v[0:1], v[4:7], off
	v_add_u32_e32 v0, 0x400, v64
	v_ashrrev_i32_e32 v1, 31, v0
	v_lshrrev_b32_e32 v1, 28, v1
	v_add_u32_e32 v1, v0, v1
	v_ashrrev_i32_e32 v6, 4, v1
	v_and_b32_e32 v1, -16, v1
	v_sub_u32_e32 v0, v0, v1
	v_lshlrev_b32_e32 v4, 3, v0
	v_mul_lo_u32 v1, v6, s53
	v_ashrrev_i32_e32 v5, 31, v4
	v_mad_i64_i32 v[6:7], s[20:21], v6, s54, v[8:9]
	v_lshl_add_u64 v[10:11], v[4:5], 1, v[6:7]
	v_add_u32_e32 v4, 0x500, v64
	v_ashrrev_i32_e32 v5, 31, v4
	v_lshrrev_b32_e32 v5, 28, v5
	v_lshl_add_u32 v0, v0, 4, v1
	v_add_u32_e32 v5, v4, v5
	ds_read_b128 v[0:3], v0
	v_ashrrev_i32_e32 v12, 4, v5
	v_and_b32_e32 v5, -16, v5
	v_sub_u32_e32 v13, v4, v5
	v_mul_lo_u32 v4, v12, s53
	v_lshl_add_u32 v4, v13, 4, v4
	ds_read_b128 v[4:7], v4
	s_waitcnt lgkmcnt(1)
	global_store_dwordx4 v[10:11], v[0:3], off
	s_nop 1
	v_lshlrev_b32_e32 v0, 3, v13
	v_ashrrev_i32_e32 v1, 31, v0
	v_mad_i64_i32 v[2:3], s[20:21], v12, s54, v[8:9]
	v_lshl_add_u64 v[0:1], v[0:1], 1, v[2:3]
	s_waitcnt lgkmcnt(0)
	global_store_dwordx4 v[0:1], v[4:7], off
	v_add_u32_e32 v0, 0x600, v64
	v_ashrrev_i32_e32 v1, 31, v0
	v_lshrrev_b32_e32 v1, 28, v1
	v_add_u32_e32 v1, v0, v1
	v_ashrrev_i32_e32 v6, 4, v1
	v_and_b32_e32 v1, -16, v1
	v_sub_u32_e32 v0, v0, v1
	v_lshlrev_b32_e32 v4, 3, v0
	v_mul_lo_u32 v1, v6, s53
	v_ashrrev_i32_e32 v5, 31, v4
	v_mad_i64_i32 v[6:7], s[20:21], v6, s54, v[8:9]
	v_lshl_add_u64 v[10:11], v[4:5], 1, v[6:7]
	v_add_u32_e32 v4, 0x700, v64
	v_ashrrev_i32_e32 v5, 31, v4
	v_lshrrev_b32_e32 v5, 28, v5
	v_lshl_add_u32 v0, v0, 4, v1
	v_add_u32_e32 v5, v4, v5
	ds_read_b128 v[0:3], v0
	v_ashrrev_i32_e32 v12, 4, v5
	v_and_b32_e32 v5, -16, v5
	v_sub_u32_e32 v13, v4, v5
	v_mul_lo_u32 v4, v12, s53
	v_lshl_add_u32 v4, v13, 4, v4
	ds_read_b128 v[4:7], v4
	s_waitcnt lgkmcnt(1)
	global_store_dwordx4 v[10:11], v[0:3], off
	s_nop 1
	v_lshlrev_b32_e32 v0, 3, v13
	v_ashrrev_i32_e32 v1, 31, v0
	v_mad_i64_i32 v[2:3], s[20:21], v12, s54, v[8:9]
	v_lshl_add_u64 v[0:1], v[0:1], 1, v[2:3]
	s_waitcnt lgkmcnt(0)
	global_store_dwordx4 v[0:1], v[4:7], off
	s_cbranch_scc0 .LBB0_752

; template <int WM, int WN>
; __device__ __forceinline__ void store_tile_bf16(const f32x4 (&acc)[WM][WN], u16* dst, int ld, char* smem) {
;   constexpr int BM = 32 * WM, BN = 32 * WN, STR = BN + 8;
;   const int tid = opaque_tid(), lane = tid & 63, wid = tid >> 6;
;   const int wr = wid >> 1, wc = wid & 1, fr = lane & 15, fq = lane >> 4;
;   u16* T = reinterpret_cast<u16*>(smem);
; #pragma unroll
;   for (int m = 0; m < WM; ++m)
; #pragma unroll
;     for (int n = 0; n < WN; ++n)
; #pragma unroll
;       for (int j = 0; j < 4; ++j)
;         T[(wr * 16 * WM + m * 16 + fq * 4 + j) * STR + wc * 16 * WN + n * 16 + fr] = f2bf(acc[m][n][j]);
;   __syncthreads();
.LBB0_1065:
	v_mov_b32_e32 v64, v232
	v_lshrrev_b32_e32 v66, 2, v64
	s_waitcnt lgkmcnt(0)
	v_lshrrev_b32_e32 v65, 1, v64
	v_and_b32_e32 v66, 12, v66
	v_and_or_b32 v65, v65, s46, v66
	v_and_b32_e32 v66, 0x4f, v64
	v_mul_lo_u32 v65, v65, s49
	v_cvt_pk_bf16_f32 v44, 0, v44
	v_lshl_add_u32 v65, v66, 1, v65
	ds_write_b16_d16_hi v65, v44
	v_cvt_pk_bf16_f32 v44, v45, v46
	ds_write_b16 v65, v44 offset:272
	ds_write_b16_d16_hi v65, v44 offset:544
	v_cvt_pk_bf16_f32 v44, 0, v47
	ds_write_b16_d16_hi v65, v44 offset:816
	v_cvt_pk_bf16_f32 v40, 0, v40
	ds_write_b16_d16_hi v65, v40 offset:32
	v_cvt_pk_bf16_f32 v40, v41, v42
	ds_write_b16 v65, v40 offset:304
	ds_write_b16_d16_hi v65, v40 offset:576
	v_cvt_pk_bf16_f32 v40, 0, v43
	ds_write_b16_d16_hi v65, v40 offset:848
	v_cvt_pk_bf16_f32 v36, 0, v36
	ds_write_b16_d16_hi v65, v36 offset:64
	v_cvt_pk_bf16_f32 v36, v37, v38
	ds_write_b16 v65, v36 offset:336
	ds_write_b16_d16_hi v65, v36 offset:608
	v_cvt_pk_bf16_f32 v36, 0, v39
	ds_write_b16_d16_hi v65, v36 offset:880
	v_cvt_pk_bf16_f32 v32, 0, v32
	ds_write_b16_d16_hi v65, v32 offset:96
	v_cvt_pk_bf16_f32 v32, v33, v34
	ds_write_b16 v65, v32 offset:368
	ds_write_b16_d16_hi v65, v32 offset:640
	v_cvt_pk_bf16_f32 v32, 0, v35
	ds_write_b16_d16_hi v65, v32 offset:912
	v_cvt_pk_bf16_f32 v28, 0, v28
	ds_write_b16_d16_hi v65, v28 offset:4352
	v_cvt_pk_bf16_f32 v28, v29, v30
	ds_write_b16 v65, v28 offset:4624
	ds_write_b16_d16_hi v65, v28 offset:4896
	v_cvt_pk_bf16_f32 v28, 0, v31
	ds_write_b16_d16_hi v65, v28 offset:5168
	v_cvt_pk_bf16_f32 v24, 0, v24
	ds_write_b16_d16_hi v65, v24 offset:4384
	v_cvt_pk_bf16_f32 v24, v25, v26
	ds_write_b16 v65, v24 offset:4656
	ds_write_b16_d16_hi v65, v24 offset:4928
	v_cvt_pk_bf16_f32 v24, 0, v27
	ds_write_b16_d16_hi v65, v24 offset:5200
	v_cvt_pk_bf16_f32 v20, 0, v20
	ds_write_b16_d16_hi v65, v20 offset:4416
	v_cvt_pk_bf16_f32 v20, v21, v22
	ds_write_b16 v65, v20 offset:4688
	ds_write_b16_d16_hi v65, v20 offset:4960
	v_cvt_pk_bf16_f32 v20, 0, v23
	ds_write_b16_d16_hi v65, v20 offset:5232
	v_cvt_pk_bf16_f32 v16, 0, v16
	ds_write_b16_d16_hi v65, v16 offset:4448
	v_cvt_pk_bf16_f32 v16, v17, v18
	ds_write_b16 v65, v16 offset:4720
	ds_write_b16_d16_hi v65, v16 offset:4992
	v_cvt_pk_bf16_f32 v16, 0, v19
	ds_write_b16_d16_hi v65, v16 offset:5264
	v_cvt_pk_bf16_f32 v12, 0, v12
	ds_write_b16_d16_hi v65, v12 offset:8704
	v_cvt_pk_bf16_f32 v12, v13, v14
	ds_write_b16 v65, v12 offset:8976
	ds_write_b16_d16_hi v65, v12 offset:9248
	v_cvt_pk_bf16_f32 v12, 0, v15
	ds_write_b16_d16_hi v65, v12 offset:9520
	v_cvt_pk_bf16_f32 v8, 0, v8
	ds_write_b16_d16_hi v65, v8 offset:8736
	v_cvt_pk_bf16_f32 v8, v9, v10
	ds_write_b16 v65, v8 offset:9008
	ds_write_b16_d16_hi v65, v8 offset:9280
	v_cvt_pk_bf16_f32 v8, 0, v11
	ds_write_b16_d16_hi v65, v8 offset:9552
	v_cvt_pk_bf16_f32 v4, 0, v4
	ds_write_b16_d16_hi v65, v4 offset:8768
	v_cvt_pk_bf16_f32 v4, v5, v6
	ds_write_b16 v65, v4 offset:9040
	ds_write_b16_d16_hi v65, v4 offset:9312
	v_cvt_pk_bf16_f32 v4, 0, v7
	ds_write_b16_d16_hi v65, v4 offset:9584
	v_cvt_pk_bf16_f32 v0, 0, v0
	ds_write_b16_d16_hi v65, v0 offset:8800
	v_cvt_pk_bf16_f32 v0, v1, v2
	ds_write_b16 v65, v0 offset:9072
	ds_write_b16_d16_hi v65, v0 offset:9344
	v_cvt_pk_bf16_f32 v0, v3, v60
	ds_write_b16 v65, v0 offset:9616
	ds_write_b16_d16_hi v65, v0 offset:13056
	v_cvt_pk_bf16_f32 v0, v61, v62
	ds_write_b16 v65, v0 offset:13328
	ds_write_b16_d16_hi v65, v0 offset:13600
	v_cvt_pk_bf16_f32 v0, v63, v56
	ds_write_b16 v65, v0 offset:13872
	ds_write_b16_d16_hi v65, v0 offset:13088
	v_cvt_pk_bf16_f32 v0, v57, v58
	ds_write_b16 v65, v0 offset:13360
	ds_write_b16_d16_hi v65, v0 offset:13632
	v_cvt_pk_bf16_f32 v0, v59, v52
	ds_write_b16 v65, v0 offset:13904
	ds_write_b16_d16_hi v65, v0 offset:13120
	v_cvt_pk_bf16_f32 v0, v53, v54
	ds_write_b16 v65, v0 offset:13392
	ds_write_b16_d16_hi v65, v0 offset:13664
	v_cvt_pk_bf16_f32 v0, v55, v48
	ds_write_b16 v65, v0 offset:13936
	ds_write_b16_d16_hi v65, v0 offset:13152
	v_cvt_pk_bf16_f32 v0, v49, v50
	ds_write_b16 v65, v0 offset:13424
	ds_write_b16_d16_hi v65, v0 offset:13696
	s_lshl_b32 s16, s16, 7
	s_mul_hi_i32 s12, s14, 0x130000
	s_mul_i32 s14, s14, 0x130000
	v_cvt_pk_bf16_f32 v0, 0, v51
	s_add_u32 s20, s36, s14
	ds_write_b16_d16_hi v65, v0 offset:13968
	v_ashrrev_i32_e32 v0, 31, v64
	s_addc_u32 s12, s37, s12
	s_ashr_i32 s17, s16, 31
	v_lshrrev_b32_e32 v0, 28, v0
	s_lshl_b64 s[14:15], s[16:17], 1
	v_add_u32_e32 v0, v64, v0
	s_add_u32 s14, s20, s14
	v_ashrrev_i32_e32 v6, 4, v0
	v_and_b32_e32 v0, -16, v0
	s_addc_u32 s15, s12, s15
	v_sub_u32_e32 v0, v64, v0
	v_lshlrev_b32_e32 v4, 3, v0
	v_mov_b64_e32 v[8:9], s[14:15]
	v_mul_lo_u32 v1, v6, s49
	v_ashrrev_i32_e32 v5, 31, v4
	v_mad_i64_i32 v[6:7], s[14:15], v6, s50, v[8:9]
	v_lshl_add_u64 v[10:11], v[4:5], 1, v[6:7]
	v_add_u32_e32 v4, 0x100, v64
	v_ashrrev_i32_e32 v5, 31, v4
	v_lshrrev_b32_e32 v5, 28, v5
	v_lshl_add_u32 v0, v0, 4, v1
	v_add_u32_e32 v5, v4, v5
	s_waitcnt lgkmcnt(0)
	s_barrier
; template <int WM, int WN>
; __device__ __forceinline__ void store_tile_bf16(const f32x4 (&acc)[WM][WN], u16* dst, int ld, char* smem) {
;     ...
;   constexpr int CPR = BN / 8;
; #pragma unroll
;   for (int i = 0; i < BM * CPR / 256; ++i) {
;     int q = tid + 256 * i, row = q / CPR, c = q % CPR;
;     uint4 v = *reinterpret_cast<const uint4*>(T + row * STR + c * 8);
;     *reinterpret_cast<uint4*>(dst + (size_t)row * ld + c * 8) = v;
;   }
	ds_read_b128 v[0:3], v0
	v_ashrrev_i32_e32 v12, 4, v5
	v_and_b32_e32 v5, -16, v5
	v_sub_u32_e32 v13, v4, v5
	v_mul_lo_u32 v4, v12, s49
	v_lshl_add_u32 v4, v13, 4, v4
	ds_read_b128 v[4:7], v4
	s_waitcnt lgkmcnt(1)
	global_store_dwordx4 v[10:11], v[0:3], off
	s_add_i32 s51, s51, s61
	s_cmp_lt_i32 s51, s47
	v_lshlrev_b32_e32 v0, 3, v13
	v_ashrrev_i32_e32 v1, 31, v0
	v_mad_i64_i32 v[2:3], s[14:15], v12, s50, v[8:9]
	v_lshl_add_u64 v[0:1], v[0:1], 1, v[2:3]
	s_waitcnt lgkmcnt(0)
	global_store_dwordx4 v[0:1], v[4:7], off
	v_add_u32_e32 v0, 0x200, v64
	v_ashrrev_i32_e32 v1, 31, v0
	v_lshrrev_b32_e32 v1, 28, v1
	v_add_u32_e32 v1, v0, v1
	v_ashrrev_i32_e32 v6, 4, v1
	v_and_b32_e32 v1, -16, v1
	v_sub_u32_e32 v0, v0, v1
	v_lshlrev_b32_e32 v4, 3, v0
	v_mul_lo_u32 v1, v6, s49
	v_ashrrev_i32_e32 v5, 31, v4
	v_mad_i64_i32 v[6:7], s[14:15], v6, s50, v[8:9]
	v_lshl_add_u64 v[10:11], v[4:5], 1, v[6:7]
	v_add_u32_e32 v4, 0x300, v64
	v_ashrrev_i32_e32 v5, 31, v4
	v_lshrrev_b32_e32 v5, 28, v5
	v_lshl_add_u32 v0, v0, 4, v1
	v_add_u32_e32 v5, v4, v5
	ds_read_b128 v[0:3], v0
	v_ashrrev_i32_e32 v12, 4, v5
	v_and_b32_e32 v5, -16, v5
	v_sub_u32_e32 v13, v4, v5
	v_mul_lo_u32 v4, v12, s49
	v_lshl_add_u32 v4, v13, 4, v4
	ds_read_b128 v[4:7], v4
	s_waitcnt lgkmcnt(1)
	global_store_dwordx4 v[10:11], v[0:3], off
	s_nop 1
	v_lshlrev_b32_e32 v0, 3, v13
	v_ashrrev_i32_e32 v1, 31, v0
	v_mad_i64_i32 v[2:3], s[14:15], v12, s50, v[8:9]
	v_lshl_add_u64 v[0:1], v[0:1], 1, v[2:3]
	s_waitcnt lgkmcnt(0)
	global_store_dwordx4 v[0:1], v[4:7], off
	v_add_u32_e32 v0, 0x400, v64
	v_ashrrev_i32_e32 v1, 31, v0
	v_lshrrev_b32_e32 v1, 28, v1
	v_add_u32_e32 v1, v0, v1
	v_ashrrev_i32_e32 v6, 4, v1
	v_and_b32_e32 v1, -16, v1
	v_sub_u32_e32 v0, v0, v1
	v_lshlrev_b32_e32 v4, 3, v0
	v_mul_lo_u32 v1, v6, s49
	v_ashrrev_i32_e32 v5, 31, v4
	v_mad_i64_i32 v[6:7], s[14:15], v6, s50, v[8:9]
	v_lshl_add_u64 v[10:11], v[4:5], 1, v[6:7]
	v_add_u32_e32 v4, 0x500, v64
	v_ashrrev_i32_e32 v5, 31, v4
	v_lshrrev_b32_e32 v5, 28, v5
	v_lshl_add_u32 v0, v0, 4, v1
	v_add_u32_e32 v5, v4, v5
	ds_read_b128 v[0:3], v0
	v_ashrrev_i32_e32 v12, 4, v5
	v_and_b32_e32 v5, -16, v5
	v_sub_u32_e32 v13, v4, v5
	v_mul_lo_u32 v4, v12, s49
	v_lshl_add_u32 v4, v13, 4, v4
	ds_read_b128 v[4:7], v4
	s_waitcnt lgkmcnt(1)
	global_store_dwordx4 v[10:11], v[0:3], off
	s_nop 1
	v_lshlrev_b32_e32 v0, 3, v13
	v_ashrrev_i32_e32 v1, 31, v0
	v_mad_i64_i32 v[2:3], s[14:15], v12, s50, v[8:9]
	v_lshl_add_u64 v[0:1], v[0:1], 1, v[2:3]
	s_waitcnt lgkmcnt(0)
	global_store_dwordx4 v[0:1], v[4:7], off
	v_add_u32_e32 v0, 0x600, v64
	v_ashrrev_i32_e32 v1, 31, v0
	v_lshrrev_b32_e32 v1, 28, v1
	v_add_u32_e32 v1, v0, v1
	v_ashrrev_i32_e32 v6, 4, v1
	v_and_b32_e32 v1, -16, v1
	v_sub_u32_e32 v0, v0, v1
	v_lshlrev_b32_e32 v4, 3, v0
	v_mul_lo_u32 v1, v6, s49
	v_ashrrev_i32_e32 v5, 31, v4
	v_mad_i64_i32 v[6:7], s[14:15], v6, s50, v[8:9]
	v_lshl_add_u64 v[10:11], v[4:5], 1, v[6:7]
	v_add_u32_e32 v4, 0x700, v64
	v_ashrrev_i32_e32 v5, 31, v4
	v_lshrrev_b32_e32 v5, 28, v5
	v_lshl_add_u32 v0, v0, 4, v1
	v_add_u32_e32 v5, v4, v5
	ds_read_b128 v[0:3], v0
	v_ashrrev_i32_e32 v12, 4, v5
	v_and_b32_e32 v5, -16, v5
	v_sub_u32_e32 v13, v4, v5
	v_mul_lo_u32 v4, v12, s49
	v_lshl_add_u32 v4, v13, 4, v4
	ds_read_b128 v[4:7], v4
	s_waitcnt lgkmcnt(1)
	global_store_dwordx4 v[10:11], v[0:3], off
	s_nop 1
	v_lshlrev_b32_e32 v0, 3, v13
	v_ashrrev_i32_e32 v1, 31, v0
	v_mad_i64_i32 v[2:3], s[14:15], v12, s50, v[8:9]
	v_lshl_add_u64 v[0:1], v[0:1], 1, v[2:3]
	s_waitcnt lgkmcnt(0)
	global_store_dwordx4 v[0:1], v[4:7], off
	s_cbranch_scc0 .LBB0_1073

; template <int WM, int WN>
; __device__ __forceinline__ void store_tile_bf16(const f32x4 (&acc)[WM][WN], u16* dst, int ld, char* smem) {
;   constexpr int BM = 32 * WM, BN = 32 * WN, STR = BN + 8;
;   const int tid = opaque_tid(), lane = tid & 63, wid = tid >> 6;
;   const int wr = wid >> 1, wc = wid & 1, fr = lane & 15, fq = lane >> 4;
;   u16* T = reinterpret_cast<u16*>(smem);
; #pragma unroll
;   for (int m = 0; m < WM; ++m)
; #pragma unroll
;     for (int n = 0; n < WN; ++n)
; #pragma unroll
;       for (int j = 0; j < 4; ++j)
;         T[(wr * 16 * WM + m * 16 + fq * 4 + j) * STR + wc * 16 * WN + n * 16 + fr] = f2bf(acc[m][n][j]);
;   __syncthreads();
.LBB0_1220:
	v_mov_b32_e32 v1, v232
	s_waitcnt vmcnt(7)
	v_lshrrev_b32_e32 v3, 2, v1
	v_lshrrev_b32_e32 v2, 1, v1
	v_and_b32_e32 v3, 12, v3
	v_and_or_b32 v2, v2, s50, v3
	v_and_b32_e32 v3, 0x4f, v1
	v_mul_lo_u32 v2, v2, s51
	v_lshl_add_u32 v2, v3, 1, v2
	v_cvt_pk_bf16_f32 v3, v65, v66
	ds_write_b16 v2, v3 offset:272
	ds_write_b16_d16_hi v2, v3 offset:544
	v_cvt_pk_bf16_f32 v3, v67, v60
	ds_write_b16 v2, v3 offset:816
	ds_write_b16_d16_hi v2, v3 offset:32
	v_cvt_pk_bf16_f32 v3, v61, v62
	ds_write_b16 v2, v3 offset:304
	ds_write_b16_d16_hi v2, v3 offset:576
	v_cvt_pk_bf16_f32 v3, v63, v56
	ds_write_b16 v2, v3 offset:848
	ds_write_b16_d16_hi v2, v3 offset:64
	v_cvt_pk_bf16_f32 v3, v57, v58
	ds_write_b16 v2, v3 offset:336
	ds_write_b16_d16_hi v2, v3 offset:608
	v_cvt_pk_bf16_f32 v3, v59, v52
	ds_write_b16 v2, v3 offset:880
	ds_write_b16_d16_hi v2, v3 offset:96
	v_cvt_pk_bf16_f32 v3, v53, v54
	ds_write_b16 v2, v3 offset:368
	ds_write_b16_d16_hi v2, v3 offset:640
	v_cvt_pk_bf16_f32 v3, v55, v48
	ds_write_b16 v2, v3 offset:912
	ds_write_b16_d16_hi v2, v3 offset:4352
	v_cvt_pk_bf16_f32 v3, v49, v50
	ds_write_b16 v2, v3 offset:4624
	ds_write_b16_d16_hi v2, v3 offset:4896
	v_cvt_pk_bf16_f32 v3, v51, v44
	ds_write_b16 v2, v3 offset:5168
	ds_write_b16_d16_hi v2, v3 offset:4384
	v_cvt_pk_bf16_f32 v3, v45, v46
	ds_write_b16 v2, v3 offset:4656
	ds_write_b16_d16_hi v2, v3 offset:4928
	v_cvt_pk_bf16_f32 v3, v47, v40
	ds_write_b16 v2, v3 offset:5200
	ds_write_b16_d16_hi v2, v3 offset:4416
	v_cvt_pk_bf16_f32 v3, v41, v42
	ds_write_b16 v2, v3 offset:4688
	ds_write_b16_d16_hi v2, v3 offset:4960
	v_cvt_pk_bf16_f32 v3, v43, v36
	ds_write_b16 v2, v3 offset:5232
	ds_write_b16_d16_hi v2, v3 offset:4448
	v_cvt_pk_bf16_f32 v3, v37, v38
	ds_write_b16 v2, v3 offset:4720
	ds_write_b16_d16_hi v2, v3 offset:4992
	v_cvt_pk_bf16_f32 v3, v39, v32
	ds_write_b16 v2, v3 offset:5264
	ds_write_b16_d16_hi v2, v3 offset:8704
	v_cvt_pk_bf16_f32 v3, v33, v34
	ds_write_b16 v2, v3 offset:8976
	ds_write_b16_d16_hi v2, v3 offset:9248
	v_cvt_pk_bf16_f32 v3, v35, v28
	ds_write_b16 v2, v3 offset:9520
	ds_write_b16_d16_hi v2, v3 offset:8736
	v_cvt_pk_bf16_f32 v3, v29, v30
	ds_write_b16 v2, v3 offset:9008
	ds_write_b16_d16_hi v2, v3 offset:9280
	v_cvt_pk_bf16_f32 v3, v31, v24
	ds_write_b16 v2, v3 offset:9552
	ds_write_b16_d16_hi v2, v3 offset:8768
	v_cvt_pk_bf16_f32 v3, v25, v26
	ds_write_b16 v2, v3 offset:9040
	ds_write_b16_d16_hi v2, v3 offset:9312
	v_cvt_pk_bf16_f32 v3, v27, v20
	ds_write_b16 v2, v3 offset:9584
	ds_write_b16_d16_hi v2, v3 offset:8800
	v_cvt_pk_bf16_f32 v3, v21, v22
	ds_write_b16 v2, v3 offset:9072
	ds_write_b16_d16_hi v2, v3 offset:9344
	v_cvt_pk_bf16_f32 v3, v23, v16
	ds_write_b16 v2, v3 offset:9616
	ds_write_b16_d16_hi v2, v3 offset:13056
	v_cvt_pk_bf16_f32 v3, v17, v18
	ds_write_b16 v2, v3 offset:13328
	ds_write_b16_d16_hi v2, v3 offset:13600
	v_cvt_pk_bf16_f32 v3, v19, v12
	ds_write_b16 v2, v3 offset:13872
	ds_write_b16_d16_hi v2, v3 offset:13088
	v_cvt_pk_bf16_f32 v3, v13, v14
	ds_write_b16 v2, v3 offset:13360
	ds_write_b16_d16_hi v2, v3 offset:13632
	v_cvt_pk_bf16_f32 v3, v15, v8
	ds_write_b16 v2, v3 offset:13904
	ds_write_b16_d16_hi v2, v3 offset:13120
	v_cvt_pk_bf16_f32 v3, v9, v10
	ds_write_b16 v2, v3 offset:13392
	ds_write_b16_d16_hi v2, v3 offset:13664
	v_cvt_pk_bf16_f32 v3, v11, v4
	ds_write_b16 v2, v3 offset:13936
	ds_write_b16_d16_hi v2, v3 offset:13152
	v_cvt_pk_bf16_f32 v3, v5, v6
	ds_write_b16 v2, v3 offset:13424
	ds_write_b16_d16_hi v2, v3 offset:13696
	v_cvt_pk_bf16_f32 v64, 0, v64
	v_cvt_pk_bf16_f32 v3, 0, v7
	ds_write_b16_d16_hi v2, v64
	ds_write_b16_d16_hi v2, v3 offset:13968
	v_ashrrev_i32_e32 v2, 31, v1
	s_lshl_b64 s[6:7], s[16:17], 1
	v_lshrrev_b32_e32 v2, 28, v2
	s_add_u32 s8, s44, s6
	v_add_u32_e32 v2, v1, v2
	s_addc_u32 s9, s45, s7
	s_lshl_b64 s[6:7], s[22:23], 1
	v_ashrrev_i32_e32 v6, 4, v2
	v_and_b32_e32 v2, -16, v2
	s_add_u32 s6, s8, s6
	v_sub_u32_e32 v2, v1, v2
	v_ashrrev_i32_e32 v7, 31, v6
	s_addc_u32 s7, s9, s7
	v_mul_lo_u32 v3, v6, s51
	v_lshlrev_b32_e32 v8, 3, v2
	v_lshlrev_b64 v[6:7], 11, v[6:7]
	v_ashrrev_i32_e32 v9, 31, v8
	v_lshl_add_u64 v[6:7], s[6:7], 0, v[6:7]
	v_lshl_add_u64 v[10:11], v[8:9], 1, v[6:7]
	v_add_u32_e32 v6, 0x100, v1
	v_ashrrev_i32_e32 v7, 31, v6
	v_lshl_add_u32 v2, v2, 4, v3
	v_lshrrev_b32_e32 v7, 28, v7
	s_waitcnt lgkmcnt(0)
	s_barrier
; template <int WM, int WN>
; __device__ __forceinline__ void store_tile_bf16(const f32x4 (&acc)[WM][WN], u16* dst, int ld, char* smem) {
;     ...
;   constexpr int CPR = BN / 8;
; #pragma unroll
;   for (int i = 0; i < BM * CPR / 256; ++i) {
;     int q = tid + 256 * i, row = q / CPR, c = q % CPR;
;     uint4 v = *reinterpret_cast<const uint4*>(T + row * STR + c * 8);
;     *reinterpret_cast<uint4*>(dst + (size_t)row * ld + c * 8) = v;
;   }
	ds_read_b128 v[2:5], v2
	v_add_u32_e32 v7, v6, v7
	v_ashrrev_i32_e32 v12, 4, v7
	v_and_b32_e32 v7, -16, v7
	v_sub_u32_e32 v13, v6, v7
	v_mul_lo_u32 v6, v12, s51
	v_lshl_add_u32 v6, v13, 4, v6
	ds_read_b128 v[6:9], v6
	s_waitcnt lgkmcnt(1)
	global_store_dwordx4 v[10:11], v[2:5], off
	s_add_i32 s52, s52, s61
	s_cmp_lt_i32 s52, s62
	v_lshlrev_b32_e32 v2, 3, v13
	v_ashrrev_i32_e32 v13, 31, v12
	v_lshlrev_b64 v[4:5], 11, v[12:13]
	v_ashrrev_i32_e32 v3, 31, v2
	v_lshl_add_u64 v[4:5], s[6:7], 0, v[4:5]
	v_lshl_add_u64 v[2:3], v[2:3], 1, v[4:5]
	s_waitcnt lgkmcnt(0)
	global_store_dwordx4 v[2:3], v[6:9], off
	v_add_u32_e32 v2, 0x200, v1
	v_ashrrev_i32_e32 v3, 31, v2
	v_lshrrev_b32_e32 v3, 28, v3
	v_add_u32_e32 v3, v2, v3
	v_ashrrev_i32_e32 v6, 4, v3
	v_and_b32_e32 v3, -16, v3
	v_sub_u32_e32 v2, v2, v3
	v_ashrrev_i32_e32 v7, 31, v6
	v_mul_lo_u32 v3, v6, s51
	v_lshlrev_b32_e32 v8, 3, v2
	v_lshlrev_b64 v[6:7], 11, v[6:7]
	v_ashrrev_i32_e32 v9, 31, v8
	v_lshl_add_u64 v[6:7], s[6:7], 0, v[6:7]
	v_lshl_add_u64 v[10:11], v[8:9], 1, v[6:7]
	v_add_u32_e32 v6, 0x300, v1
	v_ashrrev_i32_e32 v7, 31, v6
	v_lshl_add_u32 v2, v2, 4, v3
	v_lshrrev_b32_e32 v7, 28, v7
	ds_read_b128 v[2:5], v2
	v_add_u32_e32 v7, v6, v7
	v_ashrrev_i32_e32 v12, 4, v7
	v_and_b32_e32 v7, -16, v7
	v_sub_u32_e32 v13, v6, v7
	v_mul_lo_u32 v6, v12, s51
	v_lshl_add_u32 v6, v13, 4, v6
	ds_read_b128 v[6:9], v6
	s_waitcnt lgkmcnt(1)
	global_store_dwordx4 v[10:11], v[2:5], off
	s_nop 1
	v_lshlrev_b32_e32 v2, 3, v13
	v_ashrrev_i32_e32 v13, 31, v12
	v_lshlrev_b64 v[4:5], 11, v[12:13]
	v_ashrrev_i32_e32 v3, 31, v2
	v_lshl_add_u64 v[4:5], s[6:7], 0, v[4:5]
	v_lshl_add_u64 v[2:3], v[2:3], 1, v[4:5]
	s_waitcnt lgkmcnt(0)
	global_store_dwordx4 v[2:3], v[6:9], off
	v_add_u32_e32 v2, 0x400, v1
	v_ashrrev_i32_e32 v3, 31, v2
	v_lshrrev_b32_e32 v3, 28, v3
	v_add_u32_e32 v3, v2, v3
	v_ashrrev_i32_e32 v6, 4, v3
	v_and_b32_e32 v3, -16, v3
	v_sub_u32_e32 v2, v2, v3
	v_ashrrev_i32_e32 v7, 31, v6
	v_mul_lo_u32 v3, v6, s51
	v_lshlrev_b32_e32 v8, 3, v2
	v_lshlrev_b64 v[6:7], 11, v[6:7]
	v_ashrrev_i32_e32 v9, 31, v8
	v_lshl_add_u64 v[6:7], s[6:7], 0, v[6:7]
	v_lshl_add_u64 v[10:11], v[8:9], 1, v[6:7]
	v_add_u32_e32 v6, 0x500, v1
	v_ashrrev_i32_e32 v7, 31, v6
	v_lshl_add_u32 v2, v2, 4, v3
	v_lshrrev_b32_e32 v7, 28, v7
	ds_read_b128 v[2:5], v2
	v_add_u32_e32 v7, v6, v7
	v_ashrrev_i32_e32 v12, 4, v7
	v_and_b32_e32 v7, -16, v7
	v_sub_u32_e32 v13, v6, v7
	v_mul_lo_u32 v6, v12, s51
	v_lshl_add_u32 v6, v13, 4, v6
	ds_read_b128 v[6:9], v6
	s_waitcnt lgkmcnt(1)
	global_store_dwordx4 v[10:11], v[2:5], off
	s_nop 1
	v_lshlrev_b32_e32 v2, 3, v13
	v_ashrrev_i32_e32 v13, 31, v12
	v_lshlrev_b64 v[4:5], 11, v[12:13]
	v_ashrrev_i32_e32 v3, 31, v2
	v_lshl_add_u64 v[4:5], s[6:7], 0, v[4:5]
	v_lshl_add_u64 v[2:3], v[2:3], 1, v[4:5]
	s_waitcnt lgkmcnt(0)
	global_store_dwordx4 v[2:3], v[6:9], off
	v_add_u32_e32 v2, 0x600, v1
	v_ashrrev_i32_e32 v3, 31, v2
	v_lshrrev_b32_e32 v3, 28, v3
	v_add_u32_e32 v3, v2, v3
	v_ashrrev_i32_e32 v6, 4, v3
	v_and_b32_e32 v3, -16, v3
	v_sub_u32_e32 v2, v2, v3
	v_ashrrev_i32_e32 v7, 31, v6
	v_mul_lo_u32 v3, v6, s51
	v_lshlrev_b32_e32 v8, 3, v2
	v_lshlrev_b64 v[6:7], 11, v[6:7]
	v_ashrrev_i32_e32 v9, 31, v8
	v_lshl_add_u64 v[6:7], s[6:7], 0, v[6:7]
	v_add_u32_e32 v1, 0x700, v1
	v_lshl_add_u64 v[10:11], v[8:9], 1, v[6:7]
	v_ashrrev_i32_e32 v6, 31, v1
	v_lshrrev_b32_e32 v6, 28, v6
	v_lshl_add_u32 v2, v2, 4, v3
	v_add_u32_e32 v6, v1, v6
	ds_read_b128 v[2:5], v2
	v_ashrrev_i32_e32 v12, 4, v6
	v_and_b32_e32 v6, -16, v6
	v_sub_u32_e32 v1, v1, v6
	v_mul_lo_u32 v6, v12, s51
	v_lshl_add_u32 v6, v1, 4, v6
	ds_read_b128 v[6:9], v6
	v_ashrrev_i32_e32 v13, 31, v12
	s_waitcnt lgkmcnt(1)
	global_store_dwordx4 v[10:11], v[2:5], off
	s_nop 1
	v_lshlrev_b32_e32 v2, 3, v1
	v_lshlrev_b64 v[4:5], 11, v[12:13]
	v_ashrrev_i32_e32 v3, 31, v2
	v_lshl_add_u64 v[4:5], s[6:7], 0, v[4:5]
	v_lshl_add_u64 v[2:3], v[2:3], 1, v[4:5]
	s_waitcnt lgkmcnt(0)
	global_store_dwordx4 v[2:3], v[6:9], off
	s_cbranch_scc0 .LBB0_1241

; template <int WM, int WN> ...
;   static_assert(WM == 4 && WN == 4, "128x128 block tile");
;   constexpr int APAN = 128 * 64 + PPAD, BPAN = 128 * 64 + PPAD;
;   bf16x8 fa0[4], fb0[4], fa1[4], fb1[4];
; #pragma unroll
;   for (int n = 0; n < 4; ++n) fb0[n] = LDSF(cur + boff + n * 1024);
; #pragma unroll
;   for (int m = 0; m < 4; ++m) fa0[m] = LDSF(cur + aoff + m * 1024);
;   acc[3][0] = MFMA16(pa, pb0, acc[3][0]);
;   acc[3][1] = MFMA16(pa, pb1, acc[3][1]);
;   acc[3][2] = MFMA16(pa, pb2, acc[3][2]);
;   acc[3][3] = MFMA16(pa, pb3, acc[3][3]);
; #pragma unroll
;   for (int n = 0; n < 4; ++n) acc[0][n] = MFMA16(fa0[0], fb0[n], acc[0][n]);
; #pragma unroll
;   for (int m = 0; m < 4; ++m) fa1[m] = LDSF(cur + aoff + APAN + m * 1024);
; #pragma unroll
;   for (int n = 0; n < 4; ++n) acc[1][n] = MFMA16(fa0[1], fb0[n], acc[1][n]);
; #pragma unroll
;   for (int n = 0; n < 4; ++n) fb1[n] = LDSF(cur + boff + BPAN + n * 1024);
; #pragma unroll
;   for (int n = 0; n < 4; ++n) acc[2][n] = MFMA16(fa0[2], fb0[n], acc[2][n]);
;   *reinterpret_cast<uint4*>(nxt + wao) = a0;
;   *reinterpret_cast<uint4*>(nxt + wao + 32 * 64) = a1;
; #pragma unroll
;   for (int n = 0; n < 4; ++n) acc[3][n] = MFMA16(fa0[3], fb0[n], acc[3][n]);
;   *reinterpret_cast<uint4*>(nxt + wao + 64 * 64) = a2;
;   *reinterpret_cast<uint4*>(nxt + wao + 96 * 64) = a3;
; #pragma unroll
;   for (int n = 0; n < 4; ++n) acc[0][n] = MFMA16(fa1[0], fb1[n], acc[0][n]);
;   *reinterpret_cast<uint4*>(nxt + wbo) = b0;
; template <int WM, int WN, typename SrcF, typename PostF>
; __device__ __forceinline__ void gemm_stream(const int nsteps, SrcF src, PostF post, f32x4 (&acc)[WM][WN], char* smem) {
;     ...
;   for (int kt = 0; kt < nsteps; kt += 2) {
;     {
;       TileSrc s = src(min(kt + 2, nsteps - 1));
;       GLOAD_TILE(xa, s.a, s.lda, ACH);
;       GLOAD_TILE(xb, s.b, s.ldb, BCH);
;     }
;     step_compute<WM, WN>(smem, smem + STAGE, acc, aoff, boff, wao, wbo, ya0, ya1, ya2, ya3, yb0, yb1, yb2, yb3, pa, pb0, pb1, pb2, pb3);
;     SB_;
;     post(kt);
;     __syncthreads();
;     {
;       TileSrc s = src(min(kt + 3, nsteps - 1));
;       GLOAD_TILE(ya, s.a, s.lda, ACH);
;       GLOAD_TILE(yb, s.b, s.ldb, BCH);
;     }
;     step_compute<WM, WN>(smem + STAGE, smem, acc, aoff, boff, wao, wbo, xa0, xa1, xa2, xa3, xb0, xb1, xb2, xb3, pa, pb0, pb1, pb2, pb3);
;     SB_;
;     post(kt + 1);
;     __syncthreads();
;   }
.LBB0_1281:
	s_add_i32 s27, s5, 2
	s_add_i32 s5, s5, 4
	s_min_u32 s5, s5, 15
	s_lshl_b32 s5, s5, 7
	s_add_u32 s92, s8, s5
	s_addc_u32 s93, s9, 0
	s_add_u32 s94, s10, s5
	s_addc_u32 s95, s11, 0
	ds_read_b128 v[144:147], v124
	ds_read_b128 v[128:131], v125 offset:16512
	ds_read_b128 v[132:135], v125 offset:17536
	ds_read_b128 v[136:139], v125 offset:18560
	ds_read_b128 v[140:143], v125 offset:19584
	v_mfma_f32_16x16x32_bf16 v[64:67], v[48:51], v[64:67], v[92:95]
	v_mfma_f32_16x16x32_bf16 v[88:91], v[48:51], v[104:107], v[88:91]
	s_waitcnt vmcnt(7)
	ds_write_b128 v126, v[32:35] offset:33024
	global_load_dwordx4 v[32:35], v116, s[92:93]
	s_add_u32 s34, s8, s5
	s_addc_u32 s35, s9, 0
	v_mfma_f32_16x16x32_bf16 v[80:83], v[48:51], v[112:115], v[80:83]
	v_mfma_f32_16x16x32_bf16 v[48:51], v[48:51], v[108:111], v[56:59]
	s_waitcnt lgkmcnt(4)
	v_mfma_f32_16x16x32_bf16 v[56:59], v[144:147], v[128:131], v[100:103]
	ds_read_b128 v[92:95], v124 offset:1024
	s_waitcnt lgkmcnt(4)
	v_mfma_f32_16x16x32_bf16 v[96:99], v[144:147], v[132:135], v[96:99]
	s_waitcnt vmcnt(7)
	ds_write_b128 v126, v[20:23] offset:35072
	global_load_dwordx4 v[20:23], v118, s[92:93]
	ds_read_b128 v[100:103], v124 offset:2048
	s_waitcnt lgkmcnt(5)
	v_mfma_f32_16x16x32_bf16 v[84:87], v[144:147], v[136:139], v[84:87]
	ds_read_b128 v[104:107], v124 offset:3072
	s_waitcnt lgkmcnt(5)
	v_mfma_f32_16x16x32_bf16 v[76:79], v[144:147], v[140:143], v[76:79]
	ds_read_b128 v[108:111], v124 offset:8256
	s_waitcnt lgkmcnt(4)
	v_mfma_f32_16x16x32_bf16 v[72:75], v[92:95], v[128:131], v[72:75]
	ds_read_b128 v[112:115], v124 offset:9280
	v_mfma_f32_16x16x32_bf16 v[68:71], v[92:95], v[132:135], v[68:71]
	ds_read_b128 v[144:147], v124 offset:10304
	v_mfma_f32_16x16x32_bf16 v[60:63], v[92:95], v[136:139], v[60:63]
	s_waitcnt vmcnt(7)
	ds_write_b128 v126, v[16:19] offset:37120
	global_load_dwordx4 v[16:19], v120, s[92:93]
	ds_read_b128 v[148:151], v124 offset:11328
	v_mfma_f32_16x16x32_bf16 v[52:55], v[92:95], v[140:143], v[52:55]
	ds_read_b128 v[92:95], v125 offset:24768
	s_waitcnt lgkmcnt(7)
	v_mfma_f32_16x16x32_bf16 v[44:47], v[100:103], v[128:131], v[44:47]
	ds_read_b128 v[152:155], v125 offset:25792
	v_mfma_f32_16x16x32_bf16 v[40:43], v[100:103], v[132:135], v[40:43]
	ds_read_b128 v[156:159], v125 offset:26816
	v_mfma_f32_16x16x32_bf16 v[36:39], v[100:103], v[136:139], v[36:39]
	s_waitcnt vmcnt(7)
	ds_write_b128 v126, v[24:27] offset:39168
	global_load_dwordx4 v[24:27], v122, s[92:93]
	ds_read_b128 v[160:163], v125 offset:27840
	v_mfma_f32_16x16x32_bf16 v[28:31], v[100:103], v[140:143], v[28:31]
	s_waitcnt lgkmcnt(10)
	v_mfma_f32_16x16x32_bf16 v[64:67], v[104:107], v[128:131], v[64:67]
	v_mfma_f32_16x16x32_bf16 v[88:91], v[104:107], v[132:135], v[88:91]
	v_mfma_f32_16x16x32_bf16 v[80:83], v[104:107], v[136:139], v[80:83]
	v_mfma_f32_16x16x32_bf16 v[48:51], v[104:107], v[140:143], v[48:51]
	s_waitcnt vmcnt(7)
	ds_write_b128 v126, v[12:15] offset:49536
	global_load_dwordx4 v[12:15], v116, s[94:95]
	s_waitcnt lgkmcnt(5)
	v_mfma_f32_16x16x32_bf16 v[56:59], v[108:111], v[92:95], v[56:59]
	s_add_u32 s34, s10, s5
	s_addc_u32 s35, s11, 0
	s_waitcnt lgkmcnt(4)
	v_mfma_f32_16x16x32_bf16 v[96:99], v[108:111], v[152:155], v[96:99]
	s_min_u32 s5, s27, 12
	s_lshl_b32 s5, s5, 7
	s_waitcnt lgkmcnt(3)
	v_mfma_f32_16x16x32_bf16 v[84:87], v[108:111], v[156:159], v[84:87]
	s_waitcnt lgkmcnt(1)
	v_mfma_f32_16x16x32_bf16 v[76:79], v[108:111], v[160:163], v[76:79]
	s_waitcnt vmcnt(7)
	ds_write_b128 v126, v[8:11] offset:51584
	global_load_dwordx4 v[8:11], v118, s[94:95]
	v_mfma_f32_16x16x32_bf16 v[72:75], v[112:115], v[92:95], v[72:75]
	v_mfma_f32_16x16x32_bf16 v[68:71], v[112:115], v[152:155], v[68:71]
	v_mfma_f32_16x16x32_bf16 v[60:63], v[112:115], v[156:159], v[60:63]
	v_mfma_f32_16x16x32_bf16 v[52:55], v[112:115], v[160:163], v[52:55]
	v_mfma_f32_16x16x32_bf16 v[44:47], v[144:147], v[92:95], v[44:47]
	s_waitcnt vmcnt(7)
	ds_write_b128 v126, v[4:7] offset:53632
	global_load_dwordx4 v[4:7], v120, s[94:95]
	v_mfma_f32_16x16x32_bf16 v[40:43], v[144:147], v[152:155], v[40:43]
	s_add_u32 s34, s8, s5
	s_addc_u32 s35, s9, 0
	s_add_u32 s36, s10, s5
	v_mfma_f32_16x16x32_bf16 v[36:39], v[144:147], v[156:159], v[36:39]
	s_addc_u32 s37, s11, 0
	v_mfma_f32_16x16x32_bf16 v[28:31], v[144:147], v[160:163], v[28:31]
	v_mfma_f32_16x16x32_bf16 v[92:95], v[148:151], v[92:95], v[64:67]
	s_waitcnt vmcnt(7)
	ds_write_b128 v126, v[0:3] offset:55680
	global_load_dwordx4 v[0:3], v122, s[94:95]
	v_mfma_f32_16x16x32_bf16 v[88:91], v[148:151], v[152:155], v[88:91]
	v_mfma_f32_16x16x32_bf16 v[80:83], v[148:151], v[156:159], v[80:83]
	v_mfma_f32_16x16x32_bf16 v[100:103], v[148:151], v[160:163], v[48:51]
	s_waitcnt lgkmcnt(0)
	s_barrier
; template <int WM, int WN> ...
;   static_assert(WM == 4 && WN == 4, "128x128 block tile");
;   constexpr int APAN = 128 * 64 + PPAD, BPAN = 128 * 64 + PPAD;
;   bf16x8 fa0[4], fb0[4], fa1[4], fb1[4];
; #pragma unroll
;   for (int n = 0; n < 4; ++n) fb0[n] = LDSF(cur + boff + n * 1024);
; #pragma unroll
;   for (int m = 0; m < 4; ++m) fa0[m] = LDSF(cur + aoff + m * 1024);
;   acc[3][0] = MFMA16(pa, pb0, acc[3][0]);
;   acc[3][1] = MFMA16(pa, pb1, acc[3][1]);
;   acc[3][2] = MFMA16(pa, pb2, acc[3][2]);
;   acc[3][3] = MFMA16(pa, pb3, acc[3][3]);
; #pragma unroll
;   for (int n = 0; n < 4; ++n) acc[0][n] = MFMA16(fa0[0], fb0[n], acc[0][n]);
; #pragma unroll
;   for (int m = 0; m < 4; ++m) fa1[m] = LDSF(cur + aoff + APAN + m * 1024);
; #pragma unroll
;   for (int n = 0; n < 4; ++n) acc[1][n] = MFMA16(fa0[1], fb0[n], acc[1][n]);
; #pragma unroll
;   for (int n = 0; n < 4; ++n) fb1[n] = LDSF(cur + boff + BPAN + n * 1024);
; #pragma unroll
;   for (int n = 0; n < 4; ++n) acc[2][n] = MFMA16(fa0[2], fb0[n], acc[2][n]);
;   *reinterpret_cast<uint4*>(nxt + wao) = a0;
;   *reinterpret_cast<uint4*>(nxt + wao + 32 * 64) = a1;
; #pragma unroll
;   for (int n = 0; n < 4; ++n) acc[3][n] = MFMA16(fa0[3], fb0[n], acc[3][n]);
;   *reinterpret_cast<uint4*>(nxt + wao + 64 * 64) = a2;
;   *reinterpret_cast<uint4*>(nxt + wao + 96 * 64) = a3;
; #pragma unroll
;   for (int n = 0; n < 4; ++n) acc[0][n] = MFMA16(fa1[0], fb1[n], acc[0][n]);
;   *reinterpret_cast<uint4*>(nxt + wbo) = b0;
; template <int WM, int WN, typename SrcF, typename PostF>
; __device__ __forceinline__ void gemm_stream(const int nsteps, SrcF src, PostF post, f32x4 (&acc)[WM][WN], char* smem) {
;     ...
;   for (int kt = 0; kt < nsteps; kt += 2) {
;     {
;       TileSrc s = src(min(kt + 2, nsteps - 1));
;       GLOAD_TILE(xa, s.a, s.lda, ACH);
;       GLOAD_TILE(xb, s.b, s.ldb, BCH);
;     }
;     step_compute<WM, WN>(smem, smem + STAGE, acc, aoff, boff, wao, wbo, ya0, ya1, ya2, ya3, yb0, yb1, yb2, yb3, pa, pb0, pb1, pb2, pb3);
;     SB_;
;     post(kt);
;     __syncthreads();
;     {
;       TileSrc s = src(min(kt + 3, nsteps - 1));
;       GLOAD_TILE(ya, s.a, s.lda, ACH);
;       GLOAD_TILE(yb, s.b, s.ldb, BCH);
;     }
;     step_compute<WM, WN>(smem + STAGE, smem, acc, aoff, boff, wao, wbo, xa0, xa1, xa2, xa3, xb0, xb1, xb2, xb3, pa, pb0, pb1, pb2, pb3);
;     SB_;
;     post(kt + 1);
;     __syncthreads();
;   }
	s_nop 0
	ds_read_b128 v[48:51], v124 offset:33024
	ds_read_b128 v[108:111], v125 offset:49536
	ds_read_b128 v[128:131], v125 offset:50560
	ds_read_b128 v[132:135], v125 offset:51584
	ds_read_b128 v[136:139], v125 offset:52608
	s_waitcnt lgkmcnt(3)
	v_mfma_f32_16x16x32_bf16 v[140:143], v[48:51], v[108:111], v[56:59]
	s_waitcnt lgkmcnt(2)
	v_mfma_f32_16x16x32_bf16 v[96:99], v[48:51], v[128:131], v[96:99]
	s_waitcnt vmcnt(7)
	ds_write_b128 v126, v[32:35]
	global_load_dwordx4 v[32:35], v116, s[34:35] offset:384
	s_waitcnt lgkmcnt(2)
	v_mfma_f32_16x16x32_bf16 v[84:87], v[48:51], v[132:135], v[84:87]
	s_waitcnt lgkmcnt(0)
	v_mfma_f32_16x16x32_bf16 v[76:79], v[48:51], v[136:139], v[76:79]
	ds_read_b128 v[48:51], v124 offset:34048
	s_waitcnt lgkmcnt(0)
	v_mfma_f32_16x16x32_bf16 v[72:75], v[48:51], v[108:111], v[72:75]
	s_waitcnt vmcnt(7)
	ds_write_b128 v126, v[20:23] offset:2048
	global_load_dwordx4 v[20:23], v118, s[34:35] offset:384
	ds_read_b128 v[56:59], v124 offset:35072
	v_mfma_f32_16x16x32_bf16 v[68:71], v[48:51], v[128:131], v[68:71]
	ds_read_b128 v[144:147], v124 offset:36096
	v_mfma_f32_16x16x32_bf16 v[60:63], v[48:51], v[132:135], v[60:63]
	ds_read_b128 v[148:151], v124 offset:41280
	v_mfma_f32_16x16x32_bf16 v[52:55], v[48:51], v[136:139], v[52:55]
	ds_read_b128 v[152:155], v124 offset:42304
	s_waitcnt lgkmcnt(3)
	v_mfma_f32_16x16x32_bf16 v[44:47], v[56:59], v[108:111], v[44:47]
	s_waitcnt vmcnt(7)
	ds_write_b128 v126, v[16:19] offset:4096
	global_load_dwordx4 v[16:19], v120, s[34:35] offset:384
	ds_read_b128 v[156:159], v124 offset:43328
	v_mfma_f32_16x16x32_bf16 v[40:43], v[56:59], v[128:131], v[40:43]
	ds_read_b128 v[48:51], v124 offset:44352
	v_mfma_f32_16x16x32_bf16 v[36:39], v[56:59], v[132:135], v[36:39]
	ds_read_b128 v[64:67], v125 offset:57792
	v_mfma_f32_16x16x32_bf16 v[28:31], v[56:59], v[136:139], v[28:31]
	s_waitcnt vmcnt(7)
	ds_write_b128 v126, v[24:27] offset:6144
	global_load_dwordx4 v[24:27], v122, s[34:35] offset:384
	ds_read_b128 v[104:107], v125 offset:58816
	s_waitcnt lgkmcnt(8)
	v_mfma_f32_16x16x32_bf16 v[92:95], v[144:147], v[108:111], v[92:95]
	ds_read_b128 v[112:115], v125 offset:59840
	v_mfma_f32_16x16x32_bf16 v[88:91], v[144:147], v[128:131], v[88:91]
	ds_read_b128 v[108:111], v125 offset:60864
	v_mfma_f32_16x16x32_bf16 v[80:83], v[144:147], v[132:135], v[80:83]
	v_mfma_f32_16x16x32_bf16 v[56:59], v[144:147], v[136:139], v[100:103]
	s_waitcnt vmcnt(7)
	ds_write_b128 v126, v[12:15] offset:16512
	global_load_dwordx4 v[12:15], v116, s[36:37] offset:384
	s_waitcnt lgkmcnt(5)
	v_mfma_f32_16x16x32_bf16 v[100:103], v[148:151], v[64:67], v[140:143]
	s_waitcnt lgkmcnt(3)
	v_mfma_f32_16x16x32_bf16 v[96:99], v[148:151], v[104:107], v[96:99]
	s_waitcnt lgkmcnt(2)
	v_mfma_f32_16x16x32_bf16 v[84:87], v[148:151], v[112:115], v[84:87]
	s_waitcnt vmcnt(7)
	ds_write_b128 v126, v[8:11] offset:18560
	global_load_dwordx4 v[8:11], v118, s[36:37] offset:384
	s_waitcnt lgkmcnt(2)
	v_mfma_f32_16x16x32_bf16 v[76:79], v[148:151], v[108:111], v[76:79]
	v_mfma_f32_16x16x32_bf16 v[72:75], v[152:155], v[64:67], v[72:75]
	v_mfma_f32_16x16x32_bf16 v[68:71], v[152:155], v[104:107], v[68:71]
	v_mfma_f32_16x16x32_bf16 v[60:63], v[152:155], v[112:115], v[60:63]
	s_waitcnt vmcnt(7)
	ds_write_b128 v126, v[4:7] offset:20608
	global_load_dwordx4 v[4:7], v120, s[36:37] offset:384
	v_mfma_f32_16x16x32_bf16 v[52:55], v[152:155], v[108:111], v[52:55]
	v_mfma_f32_16x16x32_bf16 v[44:47], v[156:159], v[64:67], v[44:47]
	v_mfma_f32_16x16x32_bf16 v[40:43], v[156:159], v[104:107], v[40:43]
	s_waitcnt vmcnt(7)
	ds_write_b128 v126, v[0:3] offset:22656
	global_load_dwordx4 v[0:3], v122, s[36:37] offset:384
	v_mfma_f32_16x16x32_bf16 v[36:39], v[156:159], v[112:115], v[36:39]
	v_mfma_f32_16x16x32_bf16 v[28:31], v[156:159], v[108:111], v[28:31]
	s_cmp_lt_u32 s27, 12
	s_mov_b32 s5, s27
	s_waitcnt lgkmcnt(0)
	s_barrier
	s_cbranch_scc1 .LBB0_1281
	ds_read_b128 v[144:147], v124
	ds_read_b128 v[128:131], v125 offset:16512
	ds_read_b128 v[132:135], v125 offset:17536
	ds_read_b128 v[136:139], v125 offset:18560
	ds_read_b128 v[140:143], v125 offset:19584
	v_mfma_f32_16x16x32_bf16 v[64:67], v[48:51], v[64:67], v[92:95]
	s_add_i32 s27, s5, 2
	s_add_i32 s5, s5, 4
	s_min_u32 s5, s5, 15
	v_mfma_f32_16x16x32_bf16 v[88:91], v[48:51], v[104:107], v[88:91]
	s_lshl_b32 s5, s5, 7
	s_add_u32 s34, s8, s5
	s_addc_u32 s35, s9, 0
	v_mfma_f32_16x16x32_bf16 v[80:83], v[48:51], v[112:115], v[80:83]
	v_mfma_f32_16x16x32_bf16 v[48:51], v[48:51], v[108:111], v[56:59]
	s_waitcnt lgkmcnt(3)
	v_mfma_f32_16x16x32_bf16 v[56:59], v[144:147], v[128:131], v[100:103]
	ds_read_b128 v[92:95], v124 offset:1024
	s_waitcnt lgkmcnt(3)
	v_mfma_f32_16x16x32_bf16 v[96:99], v[144:147], v[132:135], v[96:99]
	ds_read_b128 v[100:103], v124 offset:2048
	s_waitcnt lgkmcnt(3)
	v_mfma_f32_16x16x32_bf16 v[84:87], v[144:147], v[136:139], v[84:87]
	ds_read_b128 v[104:107], v124 offset:3072
	s_waitcnt lgkmcnt(3)
	v_mfma_f32_16x16x32_bf16 v[76:79], v[144:147], v[140:143], v[76:79]
	ds_read_b128 v[108:111], v124 offset:8256
	s_waitcnt lgkmcnt(3)
	v_mfma_f32_16x16x32_bf16 v[72:75], v[92:95], v[128:131], v[72:75]
	ds_read_b128 v[112:115], v124 offset:9280
	v_mfma_f32_16x16x32_bf16 v[68:71], v[92:95], v[132:135], v[68:71]
	ds_read_b128 v[144:147], v124 offset:10304
	v_mfma_f32_16x16x32_bf16 v[60:63], v[92:95], v[136:139], v[60:63]
	ds_read_b128 v[148:151], v124 offset:11328
	v_mfma_f32_16x16x32_bf16 v[52:55], v[92:95], v[140:143], v[52:55]
	ds_read_b128 v[92:95], v125 offset:24768
	s_waitcnt lgkmcnt(6)
; #define MFMA16(a, b, c) __builtin_amdgcn_mfma_f32_16x16x32_bf16(a, b, c, 0, 0, 0)
; #define SGB_(mask_, n_) __builtin_amdgcn_sched_group_barrier(mask_, n_, 0)
; template <int WM, int WN> ...
;   static_assert(WM == 4 && WN == 4, "128x128 block tile");
;   constexpr int APAN = 128 * 64 + PPAD, BPAN = 128 * 64 + PPAD;
;   bf16x8 fa0[4], fb0[4], fa1[4], fb1[4];
; #pragma unroll
;   for (int n = 0; n < 4; ++n) fb0[n] = LDSF(cur + boff + n * 1024);
; #pragma unroll
;   for (int m = 0; m < 4; ++m) fa0[m] = LDSF(cur + aoff + m * 1024);
;   acc[3][0] = MFMA16(pa, pb0, acc[3][0]);
;   acc[3][1] = MFMA16(pa, pb1, acc[3][1]);
;   acc[3][2] = MFMA16(pa, pb2, acc[3][2]);
;   acc[3][3] = MFMA16(pa, pb3, acc[3][3]);
; #pragma unroll
;   for (int n = 0; n < 4; ++n) acc[0][n] = MFMA16(fa0[0], fb0[n], acc[0][n]);
; #pragma unroll
;   for (int m = 0; m < 4; ++m) fa1[m] = LDSF(cur + aoff + APAN + m * 1024);
; #pragma unroll
;   for (int n = 0; n < 4; ++n) acc[1][n] = MFMA16(fa0[1], fb0[n], acc[1][n]);
; #pragma unroll
;   for (int n = 0; n < 4; ++n) fb1[n] = LDSF(cur + boff + BPAN + n * 1024);
; #pragma unroll
;   for (int n = 0; n < 4; ++n) acc[2][n] = MFMA16(fa0[2], fb0[n], acc[2][n]);
;   *reinterpret_cast<uint4*>(nxt + wao) = a0;
;   *reinterpret_cast<uint4*>(nxt + wao + 32 * 64) = a1;
; #pragma unroll
;   for (int n = 0; n < 4; ++n) acc[3][n] = MFMA16(fa0[3], fb0[n], acc[3][n]);
;   *reinterpret_cast<uint4*>(nxt + wao + 64 * 64) = a2;
;   *reinterpret_cast<uint4*>(nxt + wao + 96 * 64) = a3;
; #pragma unroll
;   for (int n = 0; n < 4; ++n) acc[0][n] = MFMA16(fa1[0], fb1[n], acc[0][n]);
;   *reinterpret_cast<uint4*>(nxt + wbo) = b0;
;   *reinterpret_cast<uint4*>(nxt + wbo + 32 * 64) = b1;
; #pragma unroll
;   for (int n = 0; n < 4; ++n) acc[1][n] = MFMA16(fa1[1], fb1[n], acc[1][n]);
;   *reinterpret_cast<uint4*>(nxt + wbo + 64 * 64) = b2;
;   *reinterpret_cast<uint4*>(nxt + wbo + 96 * 64) = b3;
; #pragma unroll
;   for (int n = 0; n < 4; ++n) acc[2][n] = MFMA16(fa1[2], fb1[n], acc[2][n]);
;   pa = fa1[3];
;   pb0 = fb1[0]; pb1 = fb1[1]; pb2 = fb1[2]; pb3 = fb1[3];
;   SGB_(0x100, 5);
;   SGB_(0x008, 4);
; #pragma unroll
;   for (int i_ = 0; i_ < 11; ++i_) { SGB_(0x008, 1); SGB_(0x100, 1); }
; #pragma unroll
;   for (int i_ = 0; i_ < 8; ++i_) { SGB_(0x008, 2); SGB_(0x200, 1); SGB_(0x020, 1); }
;   SGB_(0x008, 1);
; }
	v_mfma_f32_16x16x32_bf16 v[44:47], v[100:103], v[128:131], v[44:47]
	ds_read_b128 v[152:155], v125 offset:25792
	v_mfma_f32_16x16x32_bf16 v[40:43], v[100:103], v[132:135], v[40:43]
	ds_read_b128 v[156:159], v125 offset:26816
	v_mfma_f32_16x16x32_bf16 v[36:39], v[100:103], v[136:139], v[36:39]
	ds_read_b128 v[160:163], v125 offset:27840
	v_mfma_f32_16x16x32_bf16 v[28:31], v[100:103], v[140:143], v[28:31]
	s_waitcnt lgkmcnt(8)
	v_mfma_f32_16x16x32_bf16 v[64:67], v[104:107], v[128:131], v[64:67]
	s_waitcnt vmcnt(7)
	ds_write_b128 v126, v[32:35] offset:33024
	v_mfma_f32_16x16x32_bf16 v[88:91], v[104:107], v[132:135], v[88:91]
	v_mfma_f32_16x16x32_bf16 v[80:83], v[104:107], v[136:139], v[80:83]
	s_waitcnt vmcnt(6)
	ds_write_b128 v126, v[20:23] offset:35072
	v_mfma_f32_16x16x32_bf16 v[48:51], v[104:107], v[140:143], v[48:51]
	s_waitcnt lgkmcnt(5)
	v_mfma_f32_16x16x32_bf16 v[56:59], v[108:111], v[92:95], v[56:59]
	s_waitcnt vmcnt(5)
	ds_write_b128 v126, v[16:19] offset:37120
	s_add_u32 s34, s10, s5
	s_addc_u32 s35, s11, 0
	s_waitcnt lgkmcnt(5)
	v_mfma_f32_16x16x32_bf16 v[96:99], v[108:111], v[152:155], v[96:99]
	s_min_u32 s5, s27, 12
	s_lshl_b32 s5, s5, 7
	s_waitcnt lgkmcnt(4)
	v_mfma_f32_16x16x32_bf16 v[84:87], v[108:111], v[156:159], v[84:87]
	s_waitcnt vmcnt(4)
	ds_write_b128 v126, v[24:27] offset:39168
	s_waitcnt lgkmcnt(4)
	v_mfma_f32_16x16x32_bf16 v[76:79], v[108:111], v[160:163], v[76:79]
	v_mfma_f32_16x16x32_bf16 v[72:75], v[112:115], v[92:95], v[72:75]
	s_waitcnt vmcnt(3)
	ds_write_b128 v126, v[12:15] offset:49536
	v_mfma_f32_16x16x32_bf16 v[68:71], v[112:115], v[152:155], v[68:71]
	v_mfma_f32_16x16x32_bf16 v[60:63], v[112:115], v[156:159], v[60:63]
	s_waitcnt vmcnt(2)
	ds_write_b128 v126, v[8:11] offset:51584
	v_mfma_f32_16x16x32_bf16 v[52:55], v[112:115], v[160:163], v[52:55]
	v_mfma_f32_16x16x32_bf16 v[44:47], v[144:147], v[92:95], v[44:47]
	s_waitcnt vmcnt(1)
	ds_write_b128 v126, v[4:7] offset:53632
	v_mfma_f32_16x16x32_bf16 v[40:43], v[144:147], v[152:155], v[40:43]
	s_add_u32 s34, s8, s5
	s_addc_u32 s35, s9, 0
	s_add_u32 s36, s10, s5
	v_mfma_f32_16x16x32_bf16 v[36:39], v[144:147], v[156:159], v[36:39]
	s_waitcnt vmcnt(0)
	ds_write_b128 v126, v[0:3] offset:55680
	s_addc_u32 s37, s11, 0
	v_mfma_f32_16x16x32_bf16 v[28:31], v[144:147], v[160:163], v[28:31]
	v_mfma_f32_16x16x32_bf16 v[92:95], v[148:151], v[92:95], v[64:67]
	v_mfma_f32_16x16x32_bf16 v[88:91], v[148:151], v[152:155], v[88:91]
	v_mfma_f32_16x16x32_bf16 v[80:83], v[148:151], v[156:159], v[80:83]
	v_mfma_f32_16x16x32_bf16 v[100:103], v[148:151], v[160:163], v[48:51]
	s_waitcnt lgkmcnt(0)
	s_barrier
	s_nop 0
	ds_read_b128 v[48:51], v124 offset:33024
	ds_read_b128 v[108:111], v125 offset:49536
	ds_read_b128 v[128:131], v125 offset:50560
	ds_read_b128 v[132:135], v125 offset:51584
	ds_read_b128 v[136:139], v125 offset:52608
	s_waitcnt lgkmcnt(3)
	v_mfma_f32_16x16x32_bf16 v[140:143], v[48:51], v[108:111], v[56:59]
	s_waitcnt lgkmcnt(2)
	v_mfma_f32_16x16x32_bf16 v[96:99], v[48:51], v[128:131], v[96:99]
	s_waitcnt lgkmcnt(1)
	v_mfma_f32_16x16x32_bf16 v[84:87], v[48:51], v[132:135], v[84:87]
	s_waitcnt lgkmcnt(0)
	v_mfma_f32_16x16x32_bf16 v[76:79], v[48:51], v[136:139], v[76:79]
	ds_read_b128 v[48:51], v124 offset:34048
	s_waitcnt lgkmcnt(0)
	v_mfma_f32_16x16x32_bf16 v[72:75], v[48:51], v[108:111], v[72:75]
	ds_read_b128 v[56:59], v124 offset:35072
	v_mfma_f32_16x16x32_bf16 v[68:71], v[48:51], v[128:131], v[68:71]
	ds_read_b128 v[144:147], v124 offset:36096
	v_mfma_f32_16x16x32_bf16 v[60:63], v[48:51], v[132:135], v[60:63]
	ds_read_b128 v[148:151], v124 offset:41280
	v_mfma_f32_16x16x32_bf16 v[52:55], v[48:51], v[136:139], v[52:55]
	ds_read_b128 v[152:155], v124 offset:42304
	s_waitcnt lgkmcnt(3)
	v_mfma_f32_16x16x32_bf16 v[44:47], v[56:59], v[108:111], v[44:47]
	ds_read_b128 v[156:159], v124 offset:43328
	v_mfma_f32_16x16x32_bf16 v[40:43], v[56:59], v[128:131], v[40:43]
	ds_read_b128 v[48:51], v124 offset:44352
	v_mfma_f32_16x16x32_bf16 v[36:39], v[56:59], v[132:135], v[36:39]
	ds_read_b128 v[64:67], v125 offset:57792
	v_mfma_f32_16x16x32_bf16 v[28:31], v[56:59], v[136:139], v[28:31]
	ds_read_b128 v[104:107], v125 offset:58816
	s_waitcnt lgkmcnt(6)
	v_mfma_f32_16x16x32_bf16 v[92:95], v[144:147], v[108:111], v[92:95]
	ds_read_b128 v[112:115], v125 offset:59840
	v_mfma_f32_16x16x32_bf16 v[88:91], v[144:147], v[128:131], v[88:91]
	ds_read_b128 v[108:111], v125 offset:60864
	v_mfma_f32_16x16x32_bf16 v[80:83], v[144:147], v[132:135], v[80:83]
	v_mfma_f32_16x16x32_bf16 v[56:59], v[144:147], v[136:139], v[100:103]
	ds_write_b128 v126, v[32:35]
	s_waitcnt lgkmcnt(4)
	v_mfma_f32_16x16x32_bf16 v[100:103], v[148:151], v[64:67], v[140:143]
	s_waitcnt lgkmcnt(3)
	v_mfma_f32_16x16x32_bf16 v[96:99], v[148:151], v[104:107], v[96:99]
	ds_write_b128 v126, v[20:23] offset:2048
	s_waitcnt lgkmcnt(3)
	v_mfma_f32_16x16x32_bf16 v[84:87], v[148:151], v[112:115], v[84:87]
	s_waitcnt lgkmcnt(2)
	v_mfma_f32_16x16x32_bf16 v[76:79], v[148:151], v[108:111], v[76:79]
	ds_write_b128 v126, v[16:19] offset:4096
	v_mfma_f32_16x16x32_bf16 v[72:75], v[152:155], v[64:67], v[72:75]
	v_mfma_f32_16x16x32_bf16 v[68:71], v[152:155], v[104:107], v[68:71]
	ds_write_b128 v126, v[24:27] offset:6144
	v_mfma_f32_16x16x32_bf16 v[60:63], v[152:155], v[112:115], v[60:63]
	v_mfma_f32_16x16x32_bf16 v[52:55], v[152:155], v[108:111], v[52:55]
	ds_write_b128 v126, v[12:15] offset:16512
	v_mfma_f32_16x16x32_bf16 v[44:47], v[156:159], v[64:67], v[44:47]
	v_mfma_f32_16x16x32_bf16 v[40:43], v[156:159], v[104:107], v[40:43]
	ds_write_b128 v126, v[8:11] offset:18560
	v_mfma_f32_16x16x32_bf16 v[36:39], v[156:159], v[112:115], v[36:39]
	v_mfma_f32_16x16x32_bf16 v[28:31], v[156:159], v[108:111], v[28:31]
	ds_write_b128 v126, v[4:7] offset:20608
	ds_write_b128 v126, v[0:3] offset:22656
	s_cmp_lt_u32 s27, 14
	s_mov_b32 s5, s27
	s_waitcnt lgkmcnt(0)
	s_barrier
; #define MFMA16(a, b, c) __builtin_amdgcn_mfma_f32_16x16x32_bf16(a, b, c, 0, 0, 0)
; template <int WM, int WN, typename SrcF, typename PostF>
; __device__ __forceinline__ void gemm_stream(const int nsteps, SrcF src, PostF post, f32x4 (&acc)[WM][WN], char* smem) {
;     ...
;   acc[3][0] = MFMA16(pa, pb0, acc[3][0]);
;   acc[3][1] = MFMA16(pa, pb1, acc[3][1]);
;   acc[3][2] = MFMA16(pa, pb2, acc[3][2]);
;   acc[3][3] = MFMA16(pa, pb3, acc[3][3]);
; template <int WM, int WN>
; __device__ __forceinline__ void store_tile_bf16(const f32x4 (&acc)[WM][WN], u16* dst, int ld, char* smem) {
;   constexpr int BM = 32 * WM, BN = 32 * WN, STR = BN + 8;
;   const int tid = opaque_tid(), lane = tid & 63, wid = tid >> 6;
;   const int wr = wid >> 1, wc = wid & 1, fr = lane & 15, fq = lane >> 4;
;   u16* T = reinterpret_cast<u16*>(smem);
; #pragma unroll
;   for (int m = 0; m < WM; ++m)
; #pragma unroll
;     for (int n = 0; n < WN; ++n)
; #pragma unroll
;       for (int j = 0; j < 4; ++j)
;         T[(wr * 16 * WM + m * 16 + fq * 4 + j) * STR + wc * 16 * WN + n * 16 + fr] = f2bf(acc[m][n][j]);
;   __syncthreads();
	s_waitcnt vmcnt(5)
	v_mov_b32_e32 v16, v232
	s_waitcnt vmcnt(0)
	v_mfma_f32_16x16x32_bf16 v[0:3], v[48:51], v[64:67], v[92:95]
	v_lshrrev_b32_e32 v18, 2, v16
	v_lshrrev_b32_e32 v17, 1, v16
	v_and_b32_e32 v18, 12, v18
	v_and_or_b32 v17, v17, s24, v18
	v_and_b32_e32 v18, 0x4f, v16
	v_mul_lo_u32 v17, v17, s26
	v_lshl_add_u32 v17, v18, 1, v17
	v_cvt_pk_bf16_f32 v18, v101, v102
	ds_write_b16 v17, v18 offset:272
	ds_write_b16_d16_hi v17, v18 offset:544
	v_cvt_pk_bf16_f32 v18, v103, v96
	ds_write_b16 v17, v18 offset:816
	ds_write_b16_d16_hi v17, v18 offset:32
	v_cvt_pk_bf16_f32 v18, v97, v98
	ds_write_b16 v17, v18 offset:304
	ds_write_b16_d16_hi v17, v18 offset:576
	v_cvt_pk_bf16_f32 v18, v99, v84
	ds_write_b16 v17, v18 offset:848
	ds_write_b16_d16_hi v17, v18 offset:64
	v_cvt_pk_bf16_f32 v18, v85, v86
	ds_write_b16 v17, v18 offset:336
	ds_write_b16_d16_hi v17, v18 offset:608
	v_cvt_pk_bf16_f32 v18, v87, v76
	ds_write_b16 v17, v18 offset:880
	ds_write_b16_d16_hi v17, v18 offset:96
	v_cvt_pk_bf16_f32 v18, v77, v78
	ds_write_b16 v17, v18 offset:368
	ds_write_b16_d16_hi v17, v18 offset:640
	v_cvt_pk_bf16_f32 v18, v79, v72
	ds_write_b16 v17, v18 offset:912
	ds_write_b16_d16_hi v17, v18 offset:4352
	v_cvt_pk_bf16_f32 v18, v73, v74
	ds_write_b16 v17, v18 offset:4624
	ds_write_b16_d16_hi v17, v18 offset:4896
	v_cvt_pk_bf16_f32 v18, v75, v68
	ds_write_b16 v17, v18 offset:5168
	ds_write_b16_d16_hi v17, v18 offset:4384
	v_cvt_pk_bf16_f32 v18, v69, v70
	ds_write_b16 v17, v18 offset:4656
	ds_write_b16_d16_hi v17, v18 offset:4928
	v_cvt_pk_bf16_f32 v18, v71, v60
	ds_write_b16 v17, v18 offset:5200
	ds_write_b16_d16_hi v17, v18 offset:4416
	v_cvt_pk_bf16_f32 v18, v61, v62
	ds_write_b16 v17, v18 offset:4688
	ds_write_b16_d16_hi v17, v18 offset:4960
	v_cvt_pk_bf16_f32 v18, v63, v52
	ds_write_b16 v17, v18 offset:5232
	ds_write_b16_d16_hi v17, v18 offset:4448
	v_cvt_pk_bf16_f32 v18, v53, v54
	ds_write_b16 v17, v18 offset:4720
	ds_write_b16_d16_hi v17, v18 offset:4992
	v_cvt_pk_bf16_f32 v18, v55, v44
	ds_write_b16 v17, v18 offset:5264
	ds_write_b16_d16_hi v17, v18 offset:8704
	v_cvt_pk_bf16_f32 v18, v45, v46
	ds_write_b16 v17, v18 offset:8976
	ds_write_b16_d16_hi v17, v18 offset:9248
	v_cvt_pk_bf16_f32 v18, v47, v40
	ds_write_b16 v17, v18 offset:9520
	ds_write_b16_d16_hi v17, v18 offset:8736
	v_cvt_pk_bf16_f32 v18, v41, v42
	ds_write_b16 v17, v18 offset:9008
	ds_write_b16_d16_hi v17, v18 offset:9280
	v_cvt_pk_bf16_f32 v18, v43, v36
	ds_write_b16 v17, v18 offset:9552
	ds_write_b16_d16_hi v17, v18 offset:8768
	v_cvt_pk_bf16_f32 v18, v37, v38
	ds_write_b16 v17, v18 offset:9040
	ds_write_b16_d16_hi v17, v18 offset:9312
	v_cvt_pk_bf16_f32 v18, v39, v28
	ds_write_b16 v17, v18 offset:9584
	ds_write_b16_d16_hi v17, v18 offset:8800
	v_cvt_pk_bf16_f32 v18, v29, v30
	ds_write_b16 v17, v18 offset:9072
	ds_write_b16_d16_hi v17, v18 offset:9344
	v_cvt_pk_bf16_f32 v18, 0, v31
	ds_write_b16_d16_hi v17, v18 offset:9616
	v_cvt_pk_bf16_f32 v0, 0, v0
	ds_write_b16_d16_hi v17, v0 offset:13056
	v_cvt_pk_bf16_f32 v0, 0, v1
	v_mfma_f32_16x16x32_bf16 v[4:7], v[48:51], v[104:107], v[88:91]
	ds_write_b16_d16_hi v17, v0 offset:13328
	v_cvt_pk_bf16_f32 v0, v2, v3
	ds_write_b16 v17, v0 offset:13600
	ds_write_b16_d16_hi v17, v0 offset:13872
	s_nop 0
	s_nop 1
	s_nop 0
	v_cvt_pk_bf16_f32 v0, 0, v4
	ds_write_b16_d16_hi v17, v0 offset:13088
	v_cvt_pk_bf16_f32 v0, 0, v5
	v_mfma_f32_16x16x32_bf16 v[8:11], v[48:51], v[112:115], v[80:83]
	ds_write_b16_d16_hi v17, v0 offset:13360
	v_cvt_pk_bf16_f32 v0, v6, v7
	ds_write_b16 v17, v0 offset:13632
	ds_write_b16_d16_hi v17, v0 offset:13904
	s_nop 0
	s_nop 1
	s_nop 0
	v_cvt_pk_bf16_f32 v0, 0, v8
	ds_write_b16_d16_hi v17, v0 offset:13120
	v_cvt_pk_bf16_f32 v0, 0, v9
	v_mfma_f32_16x16x32_bf16 v[12:15], v[48:51], v[108:111], v[56:59]
	ds_write_b16_d16_hi v17, v0 offset:13392
	v_cvt_pk_bf16_f32 v0, v10, v11
	ds_write_b16 v17, v0 offset:13664
	ds_write_b16_d16_hi v17, v0 offset:13936
	s_nop 0
	s_nop 1
	s_nop 0
	v_cvt_pk_bf16_f32 v0, v12, v13
	ds_write_b16 v17, v0 offset:13152
	ds_write_b16_d16_hi v17, v0 offset:13424
	v_cvt_pk_bf16_f32 v0, 0, v14
	ds_write_b16_d16_hi v17, v0 offset:13696
	s_lshl_b64 s[6:7], s[6:7], 1
	v_cvt_pk_bf16_f32 v0, 0, v15
	s_add_u32 s6, s16, s6
	ds_write_b16_d16_hi v17, v0 offset:13968
	v_ashrrev_i32_e32 v0, 31, v16
	s_addc_u32 s7, s17, s7
	s_lshl_b32 s4, s4, 7
	v_lshrrev_b32_e32 v0, 28, v0
	s_ashr_i32 s5, s4, 31
	v_add_u32_e32 v0, v16, v0
	s_lshl_b64 s[4:5], s[4:5], 1
	v_ashrrev_i32_e32 v4, 4, v0
	v_and_b32_e32 v0, -16, v0
	s_add_u32 s4, s6, s4
	v_sub_u32_e32 v0, v16, v0
	v_ashrrev_i32_e32 v5, 31, v4
	s_addc_u32 s5, s7, s5
	v_mul_lo_u32 v1, v4, s26
	v_lshlrev_b32_e32 v6, 3, v0
	v_lshlrev_b64 v[4:5], 11, v[4:5]
	v_ashrrev_i32_e32 v7, 31, v6
	v_lshl_add_u64 v[4:5], s[4:5], 0, v[4:5]
	v_lshl_add_u64 v[8:9], v[6:7], 1, v[4:5]
	v_add_u32_e32 v4, 0x100, v16
	v_ashrrev_i32_e32 v5, 31, v4
	v_cvt_pk_bf16_f32 v19, 0, v100
	v_lshl_add_u32 v0, v0, 4, v1
	v_lshrrev_b32_e32 v5, 28, v5
	ds_write_b16_d16_hi v17, v19
	s_waitcnt lgkmcnt(0)
	s_barrier
; template <int WM, int WN>
; __device__ __forceinline__ void store_tile_bf16(const f32x4 (&acc)[WM][WN], u16* dst, int ld, char* smem) {
;     ...
;   constexpr int CPR = BN / 8;
; #pragma unroll
;   for (int i = 0; i < BM * CPR / 256; ++i) {
;     int q = tid + 256 * i, row = q / CPR, c = q % CPR;
;     uint4 v = *reinterpret_cast<const uint4*>(T + row * STR + c * 8);
;     *reinterpret_cast<uint4*>(dst + (size_t)row * ld + c * 8) = v;
;   }
	ds_read_b128 v[0:3], v0
	v_add_u32_e32 v5, v4, v5
	v_ashrrev_i32_e32 v10, 4, v5
	v_and_b32_e32 v5, -16, v5
	v_sub_u32_e32 v11, v4, v5
	v_mul_lo_u32 v4, v10, s26
	v_lshl_add_u32 v4, v11, 4, v4
	ds_read_b128 v[4:7], v4
	s_waitcnt lgkmcnt(1)
	global_store_dwordx4 v[8:9], v[0:3], off
	s_add_i32 s60, s60, s61
	s_cmp_lt_i32 s60, s62
	v_lshlrev_b32_e32 v0, 3, v11
	v_ashrrev_i32_e32 v11, 31, v10
	v_lshlrev_b64 v[2:3], 11, v[10:11]
	v_ashrrev_i32_e32 v1, 31, v0
	v_lshl_add_u64 v[2:3], s[4:5], 0, v[2:3]
	v_lshl_add_u64 v[0:1], v[0:1], 1, v[2:3]
	s_waitcnt lgkmcnt(0)
	global_store_dwordx4 v[0:1], v[4:7], off
	v_add_u32_e32 v0, 0x200, v16
	v_ashrrev_i32_e32 v1, 31, v0
	v_lshrrev_b32_e32 v1, 28, v1
	v_add_u32_e32 v1, v0, v1
	v_ashrrev_i32_e32 v4, 4, v1
	v_and_b32_e32 v1, -16, v1
	v_sub_u32_e32 v0, v0, v1
	v_ashrrev_i32_e32 v5, 31, v4
	v_mul_lo_u32 v1, v4, s26
	v_lshlrev_b32_e32 v6, 3, v0
	v_lshlrev_b64 v[4:5], 11, v[4:5]
	v_ashrrev_i32_e32 v7, 31, v6
	v_lshl_add_u64 v[4:5], s[4:5], 0, v[4:5]
	v_lshl_add_u64 v[8:9], v[6:7], 1, v[4:5]
	v_add_u32_e32 v4, 0x300, v16
	v_ashrrev_i32_e32 v5, 31, v4
	v_lshl_add_u32 v0, v0, 4, v1
	v_lshrrev_b32_e32 v5, 28, v5
	ds_read_b128 v[0:3], v0
	v_add_u32_e32 v5, v4, v5
	v_ashrrev_i32_e32 v10, 4, v5
	v_and_b32_e32 v5, -16, v5
	v_sub_u32_e32 v11, v4, v5
	v_mul_lo_u32 v4, v10, s26
	v_lshl_add_u32 v4, v11, 4, v4
	ds_read_b128 v[4:7], v4
	s_waitcnt lgkmcnt(1)
	global_store_dwordx4 v[8:9], v[0:3], off
	s_nop 1
	v_lshlrev_b32_e32 v0, 3, v11
	v_ashrrev_i32_e32 v11, 31, v10
	v_lshlrev_b64 v[2:3], 11, v[10:11]
	v_ashrrev_i32_e32 v1, 31, v0
	v_lshl_add_u64 v[2:3], s[4:5], 0, v[2:3]
	v_lshl_add_u64 v[0:1], v[0:1], 1, v[2:3]
	s_waitcnt lgkmcnt(0)
	global_store_dwordx4 v[0:1], v[4:7], off
	v_add_u32_e32 v0, 0x400, v16
	v_ashrrev_i32_e32 v1, 31, v0
	v_lshrrev_b32_e32 v1, 28, v1
	v_add_u32_e32 v1, v0, v1
	v_ashrrev_i32_e32 v4, 4, v1
	v_and_b32_e32 v1, -16, v1
	v_sub_u32_e32 v0, v0, v1
	v_ashrrev_i32_e32 v5, 31, v4
	v_mul_lo_u32 v1, v4, s26
	v_lshlrev_b32_e32 v6, 3, v0
	v_lshlrev_b64 v[4:5], 11, v[4:5]
	v_ashrrev_i32_e32 v7, 31, v6
	v_lshl_add_u64 v[4:5], s[4:5], 0, v[4:5]
	v_lshl_add_u64 v[8:9], v[6:7], 1, v[4:5]
	v_add_u32_e32 v4, 0x500, v16
	v_ashrrev_i32_e32 v5, 31, v4
	v_lshl_add_u32 v0, v0, 4, v1
	v_lshrrev_b32_e32 v5, 28, v5
	ds_read_b128 v[0:3], v0
	v_add_u32_e32 v5, v4, v5
	v_ashrrev_i32_e32 v10, 4, v5
	v_and_b32_e32 v5, -16, v5
	v_sub_u32_e32 v11, v4, v5
	v_mul_lo_u32 v4, v10, s26
	v_lshl_add_u32 v4, v11, 4, v4
	ds_read_b128 v[4:7], v4
	s_waitcnt lgkmcnt(1)
	global_store_dwordx4 v[8:9], v[0:3], off
	s_nop 1
	v_lshlrev_b32_e32 v0, 3, v11
	v_ashrrev_i32_e32 v11, 31, v10
	v_lshlrev_b64 v[2:3], 11, v[10:11]
	v_ashrrev_i32_e32 v1, 31, v0
	v_lshl_add_u64 v[2:3], s[4:5], 0, v[2:3]
	v_lshl_add_u64 v[0:1], v[0:1], 1, v[2:3]
	s_waitcnt lgkmcnt(0)
	global_store_dwordx4 v[0:1], v[4:7], off
	v_add_u32_e32 v0, 0x600, v16
	v_ashrrev_i32_e32 v1, 31, v0
	v_lshrrev_b32_e32 v1, 28, v1
	v_add_u32_e32 v1, v0, v1
	v_ashrrev_i32_e32 v4, 4, v1
	v_and_b32_e32 v1, -16, v1
	v_sub_u32_e32 v0, v0, v1
	v_ashrrev_i32_e32 v5, 31, v4
	v_mul_lo_u32 v1, v4, s26
	v_lshlrev_b32_e32 v6, 3, v0
	v_lshlrev_b64 v[4:5], 11, v[4:5]
	v_ashrrev_i32_e32 v7, 31, v6
	v_lshl_add_u64 v[4:5], s[4:5], 0, v[4:5]
	v_lshl_add_u64 v[8:9], v[6:7], 1, v[4:5]
	v_add_u32_e32 v4, 0x700, v16
	v_ashrrev_i32_e32 v5, 31, v4
	v_lshl_add_u32 v0, v0, 4, v1
	v_lshrrev_b32_e32 v5, 28, v5
	ds_read_b128 v[0:3], v0
	v_add_u32_e32 v5, v4, v5
	v_ashrrev_i32_e32 v10, 4, v5
	v_and_b32_e32 v5, -16, v5
	v_sub_u32_e32 v11, v4, v5
	v_mul_lo_u32 v4, v10, s26
	v_lshl_add_u32 v4, v11, 4, v4
	ds_read_b128 v[4:7], v4
	s_waitcnt lgkmcnt(1)
	global_store_dwordx4 v[8:9], v[0:3], off
	s_nop 1
	v_lshlrev_b32_e32 v0, 3, v11
	v_ashrrev_i32_e32 v11, 31, v10
	v_lshlrev_b64 v[2:3], 11, v[10:11]
	v_ashrrev_i32_e32 v1, 31, v0
	v_lshl_add_u64 v[2:3], s[4:5], 0, v[2:3]
	v_lshl_add_u64 v[0:1], v[0:1], 1, v[2:3]
	s_waitcnt lgkmcnt(0)
	global_store_dwordx4 v[0:1], v[4:7], off
	s_cbranch_scc1 .LBB0_1280
